# all-reduce butterflies in post and the three row-wise loops: xor-1/2/4/8 steps as DPP adds (quad_perm, row_half_mirror, row_mirror) instead of ds_bpermute round trips; bit-identical
# speedup vs baseline: 1.0099x; 1.0099x over previous
; __device__ __forceinline__ float dot4(f32x4 a) { return (a.x * a.x + a.y * a.y) + (a.z * a.z + a.w * a.w); }
; __device__ __forceinline__ void rowwise_phase(const Params& P, int mrows, bool first, int l_post, int j_post, int gate_idx, float coef, bool final_, int l_pre, int j_pre, int shift_idx, int scale_idx) {
;     ...
;         const int b = row < MLAT ? (row >> 11) : 4;
;     ...
;             const float* gp = P.norm_post + (size_t)(l_post * 3 + j_post) * DM; const float* mg = MOD + (size_t)(l_post * 5 + b) * NMODV + gate_idx * DM;
;             float sxx = 0.f, sxt = 0.f, stt = 0.f;
; #pragma unroll
;             for (int j = 0; j < 8; ++j) { const int c = 4 * lane + 256 * j; xv[j] = *(const f32x4*)(xr + c); const f32x4 g4 = *(const f32x4*)(gp + c), m4 = *(const f32x4*)(mg + c);
;                 ss += dot4(yv[j]); yv[j] = yv[j] * g4 * m4; sxx += dot4(xv[j]); stt += dot4(yv[j]);
;                 const f32x4 xt = xv[j] * yv[j]; sxt += (xt.x + xt.y) + (xt.z + xt.w); }
.LBB0_25:
	v_lshl_add_u64 v[120:121], s[94:95], 0, v[116:117]
	s_mov_b32 s3, 0x14e01000
	v_add_co_u32_e32 v122, vcc, s3, v120
	global_load_dwordx4 v[56:59], v[92:93], off
	s_nop 0
	v_addc_co_u32_e32 v123, vcc, 0, v121, vcc
	s_mov_b32 s3, 0x14e00000
	s_min_i32 s5, s4, 0x2000
	v_readlane_b32 s14, v255, 14
	v_add_co_u32_e32 v52, vcc, s3, v120
	s_ashr_i32 s5, s5, 11
	s_mul_i32 s9, s14, 5
	global_load_dwordx4 v[60:63], v[92:93], off offset:1024
	global_load_dwordx4 v[76:79], v[92:93], off offset:2048
	global_load_dwordx4 v[40:43], v[122:123], off offset:-4096
	v_addc_co_u32_e32 v53, vcc, 0, v121, vcc
	s_add_i32 s5, s5, s9
	global_load_dwordx4 v[44:47], v[52:53], off offset:1024
	global_load_dwordx4 v[36:39], v[52:53], off offset:2048
	s_mul_i32 s14, s5, 0x12000
	v_readlane_b32 s15, v255, 15
	s_mul_hi_i32 s9, s5, 0x12000
	s_add_u32 s14, s20, s14
	v_lshlrev_b32_e32 v145, 2, v0
	s_addc_u32 s15, s21, s9
	s_nop 0
	global_load_dwordx4 v[72:75], v145, s[14:15]
	global_load_dwordx4 v[68:71], v145, s[14:15] offset:1024
	global_load_dwordx4 v[64:67], v145, s[14:15] offset:2048
	s_waitcnt vmcnt(0)
	v_pk_mul_f32 v[48:49], v[18:19], v[18:19]
	v_pk_mul_f32 v[50:51], v[16:17], v[16:17]
	s_waitcnt lgkmcnt(0)
	global_load_dwordx4 v[80:83], v[92:93], off offset:3072
	global_load_dwordx4 v[84:87], v[94:95], off
	v_pk_mov_b32 v[54:55], v[50:51], v[48:49] op_sel:[1,0]
	v_mov_b32_e32 v51, v49
	v_pk_add_f32 v[54:55], v[54:55], v[50:51]
	global_load_dwordx4 v[48:51], v[122:123], off
	v_pk_add_f32 v[128:129], v[54:55], v[54:55] op_sel_hi:[0,1]
	global_load_dwordx4 v[52:55], v[52:53], off offset:3072
	s_nop 0
	global_load_dwordx4 v[146:149], v145, s[14:15] offset:3072
	global_load_dwordx4 v[88:91], v138, s[14:15]
	global_load_dwordx4 v[150:153], v141, s[14:15]
	v_mov_b32_e32 v125, v4
	v_mov_b32_e32 v127, v6
	v_mov_b32_e32 v124, v8
	v_mov_b32_e32 v126, v10
	global_load_dwordx4 v[154:157], v139, s[14:15]
	v_mul_f32_e32 v128, v22, v22
	s_mov_b32 s3, 0x800000
	s_waitcnt vmcnt(16)
	v_pk_mul_f32 v[58:59], v[6:7], v[58:59]
	v_pk_mul_f32 v[56:57], v[4:5], v[56:57]
	v_mov_b32_e32 v4, v9
	v_mov_b32_e32 v6, v11
	v_pk_mul_f32 v[4:5], v[4:5], v[4:5]
	v_pk_mul_f32 v[6:7], v[6:7], v[6:7]
	v_pk_fma_f32 v[4:5], v[124:125], v[124:125], v[4:5]
	v_pk_fma_f32 v[6:7], v[126:127], v[126:127], v[6:7]
	s_waitcnt vmcnt(15)
	v_pk_mul_f32 v[62:63], v[10:11], v[62:63]
	v_pk_mul_f32 v[60:61], v[8:9], v[60:61]
	s_waitcnt vmcnt(13)
	v_mul_f32_e32 v2, v41, v41
	v_mul_f32_e32 v8, v42, v42
	v_fmac_f32_e32 v2, v40, v40
	s_waitcnt vmcnt(12)
	v_mul_f32_e32 v9, v45, v45
	v_mul_f32_e32 v10, v46, v46
	v_fmac_f32_e32 v8, v43, v43
	v_pk_add_f32 v[4:5], v[4:5], v[6:7]
	v_fmac_f32_e32 v9, v44, v44
	v_fmac_f32_e32 v10, v47, v47
	v_add_f32_e32 v2, v2, v8
	v_pk_add_f32 v[6:7], v[4:5], v[4:5] op_sel_hi:[0,1]
	v_add_f32_e32 v4, v9, v10
	v_pk_mul_f32 v[18:19], v[18:19], v[78:79]
	v_pk_mul_f32 v[76:77], v[16:17], v[76:77]
	v_add_f32_e32 v6, v2, v4
	s_waitcnt vmcnt(10)
	v_pk_mul_f32 v[4:5], v[74:75], v[58:59]
	v_pk_mul_f32 v[10:11], v[72:73], v[56:57]
	s_waitcnt vmcnt(9)
	v_pk_mul_f32 v[8:9], v[70:71], v[62:63]
	v_pk_mul_f32 v[68:69], v[68:69], v[60:61]
	s_waitcnt vmcnt(8)
	v_pk_mul_f32 v[16:17], v[66:67], v[18:19]
	v_pk_mul_f32 v[18:19], v[64:65], v[76:77]
	v_mul_f32_e32 v2, v5, v5
	v_pk_mul_f32 v[60:61], v[42:43], v[4:5]
	v_pk_mul_f32 v[62:63], v[40:41], v[10:11]
	v_pk_mul_f32 v[74:75], v[46:47], v[8:9]
	v_pk_mul_f32 v[76:77], v[44:45], v[68:69]
	v_mul_f32_e32 v56, v10, v10
	v_mul_f32_e32 v58, v11, v11
	v_mul_f32_e32 v64, v68, v68
	v_mul_f32_e32 v66, v69, v69
	v_mul_f32_e32 v70, v8, v8
	v_mul_f32_e32 v72, v9, v9
	v_pk_fma_f32 v[78:79], v[4:5], v[4:5], v[2:3] op_sel_hi:[1,1,0]
	v_add_f32_e32 v57, v62, v63
	v_add_f32_e32 v59, v60, v61
	v_mov_b32_e32 v65, v76
	v_mov_b32_e32 v67, v77
	v_mov_b32_e32 v71, v74
	v_mov_b32_e32 v73, v75
	v_mul_f32_e32 v124, v37, v37
	v_mul_f32_e32 v2, v38, v38
	v_pk_mul_f32 v[162:163], v[38:39], v[16:17]
	v_pk_mul_f32 v[164:165], v[36:37], v[18:19]
	v_pk_add_f32 v[56:57], v[56:57], v[58:59]
	v_mov_b32_e32 v79, v3
	v_pk_add_f32 v[58:59], v[64:65], v[66:67]
	v_pk_add_f32 v[64:65], v[70:71], v[72:73]
	v_fmac_f32_e32 v124, v36, v36
	v_fmac_f32_e32 v2, v39, v39
	v_mul_f32_e32 v60, v18, v18
	v_mul_f32_e32 v62, v19, v19
	v_mul_f32_e32 v158, v16, v16
	v_mul_f32_e32 v160, v17, v17
	v_pk_add_f32 v[56:57], v[56:57], v[78:79]
	v_pk_add_f32 v[58:59], v[58:59], v[64:65]
	v_mov_b32_e32 v61, v164
	v_mov_b32_e32 v63, v165
	v_mov_b32_e32 v159, v162
	v_mov_b32_e32 v161, v163
	v_add_f32_e32 v2, v124, v2
	v_pk_add_f32 v[64:65], v[56:57], v[58:59]
	global_load_dwordx4 v[56:59], v[122:123], off offset:1024
	v_pk_add_f32 v[60:61], v[60:61], v[62:63]
	v_pk_add_f32 v[62:63], v[158:159], v[160:161]
	v_add_f32_e32 v6, v6, v2
	v_pk_add_f32 v[60:61], v[60:61], v[62:63]
	v_mul_f32_e32 v2, v12, v12
	v_pk_add_f32 v[158:159], v[64:65], v[60:61]
	v_pk_fma_f32 v[64:65], v[12:13], v[12:13], v[2:3] op_sel_hi:[1,1,0]
	v_mul_f32_e32 v2, v14, v14
	v_pk_fma_f32 v[66:67], v[14:15], v[14:15], v[2:3] op_sel_hi:[1,1,0]
	s_waitcnt vmcnt(8)
	v_pk_mul_f32 v[14:15], v[14:15], v[82:83]
	v_pk_mul_f32 v[12:13], v[12:13], v[80:81]
	global_load_dwordx4 v[124:127], v[96:97], off
	s_waitcnt vmcnt(5)
; __device__ __forceinline__ float dot4(f32x4 a) { return (a.x * a.x + a.y * a.y) + (a.z * a.z + a.w * a.w); }
; __device__ __forceinline__ void rowwise_phase(const Params& P, int mrows, bool first, int l_post, int j_post, int gate_idx, float coef, bool final_, int l_pre, int j_pre, int shift_idx, int scale_idx) {
;     ...
;             for (int j = 0; j < 8; ++j) { const int c = 4 * lane + 256 * j; xv[j] = *(const f32x4*)(xr + c); const f32x4 g4 = *(const f32x4*)(gp + c), m4 = *(const f32x4*)(mg + c);
;                 ss += dot4(yv[j]); yv[j] = yv[j] * g4 * m4; sxx += dot4(xv[j]); stt += dot4(yv[j]);
;                 const f32x4 xt = xv[j] * yv[j]; sxt += (xt.x + xt.y) + (xt.z + xt.w); }
; #pragma unroll
;             for (int o = 1; o < 64; o <<= 1) { ss += __shfl_xor(ss, o); sxx += __shfl_xor(sxx, o); sxt += __shfl_xor(sxt, o); stt += __shfl_xor(stt, o); }
;             const float rs = rsqrtf(ss * (1.f / DM) + EPS) * coef;
	v_pk_mul_f32 v[70:71], v[148:149], v[14:15]
	v_pk_mul_f32 v[72:73], v[146:147], v[12:13]
	global_load_dwordx4 v[12:15], v[98:99], off
	global_load_dwordx4 v[78:81], v140, s[14:15]
	global_load_dwordx4 v[60:63], v[122:123], off offset:2048
	v_mul_f32_e32 v2, v53, v53
	v_mul_f32_e32 v64, v54, v54
	v_pk_mul_f32 v[148:149], v[54:55], v[70:71]
	v_pk_mul_f32 v[160:161], v[52:53], v[72:73]
	v_fmac_f32_e32 v2, v52, v52
	v_fmac_f32_e32 v64, v55, v55
	v_mul_f32_e32 v74, v72, v72
	v_mul_f32_e32 v76, v73, v73
	v_mul_f32_e32 v82, v70, v70
	v_mul_f32_e32 v146, v71, v71
	v_mov_b32_e32 v75, v160
	v_mov_b32_e32 v77, v161
	v_mov_b32_e32 v83, v148
	v_mov_b32_e32 v147, v149
	v_add_f32_e32 v2, v2, v64
	v_pk_add_f32 v[74:75], v[74:75], v[76:77]
	v_pk_add_f32 v[76:77], v[82:83], v[146:147]
	v_mul_f32_e32 v64, v20, v20
	v_mul_f32_e32 v66, v21, v21
	global_load_dwordx4 v[146:149], v[100:101], off
	v_pk_add_f32 v[82:83], v[74:75], v[76:77]
	v_pk_add_f32 v[74:75], v[64:65], v[66:67]
	global_load_dwordx4 v[64:67], v[122:123], off offset:3072
	v_add_f32_e32 v2, v6, v2
	v_mul_f32_e32 v6, v23, v23
	v_pk_add_f32 v[6:7], v[128:129], v[6:7]
	v_pk_mul_f32 v[22:23], v[22:23], v[86:87]
	v_pk_add_f32 v[6:7], v[74:75], v[6:7]
	v_pk_mul_f32 v[20:21], v[20:21], v[84:85]
	v_pk_add_f32 v[6:7], v[6:7], v[6:7] op_sel_hi:[0,1]
	s_waitcnt vmcnt(9)
	v_pk_mul_f32 v[74:75], v[90:91], v[22:23]
	v_pk_mul_f32 v[76:77], v[88:89], v[20:21]
	v_mul_f32_e32 v6, v49, v49
	v_mul_f32_e32 v20, v50, v50
	v_fmac_f32_e32 v6, v48, v48
	v_fmac_f32_e32 v20, v51, v51
	v_pk_mul_f32 v[88:89], v[50:51], v[74:75]
	v_pk_mul_f32 v[90:91], v[48:49], v[76:77]
	v_add_f32_e32 v6, v6, v20
	v_mul_f32_e32 v20, v76, v76
	v_mul_f32_e32 v22, v77, v77
	v_mul_f32_e32 v84, v74, v74
	v_mul_f32_e32 v86, v75, v75
	v_mov_b32_e32 v21, v90
	v_mov_b32_e32 v23, v91
	v_mov_b32_e32 v85, v88
	v_mov_b32_e32 v87, v89
	v_pk_add_f32 v[20:21], v[20:21], v[22:23]
	v_pk_add_f32 v[22:23], v[84:85], v[86:87]
	v_pk_mul_f32 v[84:85], v[26:27], v[26:27]
	v_pk_mul_f32 v[86:87], v[24:25], v[24:25]
	v_add_f32_e32 v2, v2, v6
	v_pk_mov_b32 v[88:89], v[86:87], v[84:85] op_sel:[1,0]
	v_mov_b32_e32 v87, v85
	v_pk_add_f32 v[84:85], v[88:89], v[86:87]
	v_pk_add_f32 v[82:83], v[158:159], v[82:83]
	v_pk_add_f32 v[84:85], v[84:85], v[84:85] op_sel_hi:[0,1]
	v_pk_add_f32 v[20:21], v[20:21], v[22:23]
	s_mov_b64 s[14:15], -1
	v_pk_add_f32 v[20:21], v[82:83], v[20:21]
	s_waitcnt vmcnt(6)
	v_mul_f32_e32 v6, v57, v57
	v_mul_f32_e32 v84, v58, v58
	v_fmac_f32_e32 v6, v56, v56
	v_fmac_f32_e32 v84, v59, v59
	v_add_f32_e32 v6, v6, v84
	v_add_f32_e32 v6, v2, v6
	v_mul_f32_e32 v2, v28, v28
	v_pk_fma_f32 v[128:129], v[28:29], v[28:29], v[2:3] op_sel_hi:[1,1,0]
	v_mul_f32_e32 v2, v30, v30
	v_mul_f32_e32 v128, v32, v32
	v_mul_f32_e32 v84, v34, v34
	s_waitcnt vmcnt(5)
	v_pk_mul_f32 v[26:27], v[26:27], v[126:127]
	v_pk_mul_f32 v[24:25], v[24:25], v[124:125]
	v_pk_mul_f32 v[26:27], v[156:157], v[26:27]
	s_waitcnt vmcnt(4)
	v_pk_mul_f32 v[12:13], v[28:29], v[12:13]
	v_pk_mul_f32 v[24:25], v[154:155], v[24:25]
	v_pk_fma_f32 v[154:155], v[30:31], v[30:31], v[2:3] op_sel_hi:[1,1,0]
	s_waitcnt vmcnt(3)
	v_pk_mul_f32 v[156:157], v[78:79], v[12:13]
	s_waitcnt vmcnt(2)
	v_mul_f32_e32 v2, v61, v61
	v_mul_f32_e32 v12, v62, v62
	v_fmac_f32_e32 v2, v60, v60
	v_fmac_f32_e32 v12, v63, v63
	v_add_f32_e32 v2, v2, v12
	v_add_f32_e32 v2, v6, v2
	v_mul_f32_e32 v154, v33, v33
	v_mul_f32_e32 v6, v35, v35
	v_pk_add_f32 v[128:129], v[128:129], v[154:155]
	v_pk_add_f32 v[6:7], v[84:85], v[6:7]
	v_pk_mul_f32 v[14:15], v[30:31], v[14:15]
	v_pk_add_f32 v[6:7], v[128:129], v[6:7]
	v_pk_mul_f32 v[124:125], v[58:59], v[26:27]
	v_add_f32_e32 v13, v6, v7
	v_pk_mul_f32 v[126:127], v[56:57], v[24:25]
	v_pk_mul_f32 v[28:29], v[80:81], v[14:15]
	v_mul_f32_e32 v86, v24, v24
	v_mul_f32_e32 v88, v25, v25
	s_waitcnt vmcnt(1)
	v_pk_mul_f32 v[6:7], v[34:35], v[148:149]
	v_pk_mul_f32 v[32:33], v[32:33], v[146:147]
	v_pk_mul_f32 v[34:35], v[152:153], v[6:7]
	s_waitcnt vmcnt(0)
	v_mul_f32_e32 v6, v65, v65
	v_mul_f32_e32 v7, v66, v66
	v_fmac_f32_e32 v6, v64, v64
	v_fmac_f32_e32 v7, v67, v67
	v_add_f32_e32 v6, v6, v7
	v_mul_f32_e32 v90, v26, v26
	v_mul_f32_e32 v122, v27, v27
	v_pk_mul_f32 v[80:81], v[62:63], v[28:29]
	v_pk_mul_f32 v[160:161], v[60:61], v[156:157]
	v_pk_mul_f32 v[32:33], v[150:151], v[32:33]
	v_mov_b32_e32 v87, v126
	v_mov_b32_e32 v89, v127
	v_mov_b32_e32 v91, v124
	v_mov_b32_e32 v123, v125
	v_mul_f32_e32 v12, v156, v156
	v_mul_f32_e32 v14, v157, v157
	v_mul_f32_e32 v30, v28, v28
	v_mul_f32_e32 v78, v29, v29
	v_pk_mul_f32 v[148:149], v[66:67], v[34:35]
	v_pk_mul_f32 v[150:151], v[64:65], v[32:33]
	s_waitcnt lgkmcnt(0)
	v_add_f32_dpp v132, v13, v13 quad_perm:[1,0,3,2] row_mask:0xf bank_mask:0xf
	v_pk_add_f32 v[22:23], v[86:87], v[88:89]
	v_pk_add_f32 v[82:83], v[90:91], v[122:123]
	v_mov_b32_e32 v13, v160
	v_mov_b32_e32 v15, v161
	v_mov_b32_e32 v31, v80
	v_mov_b32_e32 v79, v81
	v_add_f32_e32 v2, v2, v6
	v_mul_f32_e32 v6, v32, v32
	v_mul_f32_e32 v84, v33, v33
	v_mul_f32_e32 v128, v34, v34
	v_mul_f32_e32 v146, v35, v35
	v_pk_add_f32 v[22:23], v[22:23], v[82:83]
	v_pk_add_f32 v[12:13], v[12:13], v[14:15]
	v_pk_add_f32 v[14:15], v[30:31], v[78:79]
	v_mov_b32_e32 v7, v150
	v_mov_b32_e32 v85, v151
	v_mov_b32_e32 v129, v148
	v_mov_b32_e32 v147, v149
	v_pk_add_f32 v[20:21], v[20:21], v[22:23]
	v_pk_add_f32 v[12:13], v[12:13], v[14:15]
	v_pk_add_f32 v[6:7], v[6:7], v[84:85]
	v_pk_add_f32 v[14:15], v[128:129], v[146:147]
	v_pk_add_f32 v[12:13], v[20:21], v[12:13]
	v_pk_add_f32 v[6:7], v[6:7], v[14:15]
	v_pk_add_f32 v[6:7], v[12:13], v[6:7]
	s_waitcnt lgkmcnt(0)
	v_add_f32_dpp v14, v132, v132 quad_perm:[2,3,0,1] row_mask:0xf bank_mask:0xf
	s_waitcnt lgkmcnt(0)
; __device__ __forceinline__ unsigned pk2(float lo, float hi) { return f2bf(lo) | (f2bf(hi) << 16); }
; __device__ __forceinline__ float dot4(f32x4 a) { return (a.x * a.x + a.y * a.y) + (a.z * a.z + a.w * a.w); }
; __device__ __forceinline__ void rowwise_phase(const Params& P, int mrows, bool first, int l_post, int j_post, int gate_idx, float coef, bool final_, int l_pre, int j_pre, int shift_idx, int scale_idx) {
;     ...
; #pragma unroll
;             for (int o = 1; o < 64; o <<= 1) { ss += __shfl_xor(ss, o); sxx += __shfl_xor(sxx, o); sxt += __shfl_xor(sxt, o); stt += __shfl_xor(stt, o); }
;             const float rs = rsqrtf(ss * (1.f / DM) + EPS) * coef;
;             ss_new = sxx + 2.f * rs * sxt + rs * rs * stt;
; #pragma unroll
;             for (int j = 0; j < 8; ++j) xv[j] += yv[j] * rs;
;     ...
;             float* xr = X + (size_t)row * DM; float ss = 0.f;
; #pragma unroll
;             for (int j = 0; j < 8; ++j) { if (!first) *(f32x4*)(xr + 4 * lane + 256 * j) = xv[j]; else ss += dot4(xv[j]); }
;             if (first) ss = wave_sum(ss); else ss = ss_new;
;             const float rs = rsqrtf(ss * (1.f / DM) + EPS);
;             const float* gp = P.norm_pre + (size_t)(l_pre * 3 + j_pre) * DM; const float* mb = MOD + (size_t)(l_pre * 5 + b) * NMODV;
;             bf16* hr = H + (size_t)row * DM;
; #pragma unroll
;             for (int j = 0; j < 8; ++j) { const int c = 4 * lane + 256 * j; const f32x4 g4 = *(const f32x4*)(gp + c), sh = *(const f32x4*)(mb + shift_idx * DM + c), scl = *(const f32x4*)(mb + scale_idx * DM + c);
;                 const f32x4 h = (xv[j] * rs) * g4 * (scl + 1.f) + sh; u32x2 w; w.x = pk2(h.x, h.y); w.y = pk2(h.z, h.w); *(u32x2*)(hr + c) = w; }
	s_nop 0
	v_add_f32_dpp v6, v6, v6 quad_perm:[1,0,3,2] row_mask:0xf bank_mask:0xf
	v_add_f32_dpp v7, v7, v7 quad_perm:[1,0,3,2] row_mask:0xf bank_mask:0xf
	s_waitcnt lgkmcnt(0)
	v_add_f32_dpp v2, v2, v2 quad_perm:[1,0,3,2] row_mask:0xf bank_mask:0xf
	s_waitcnt lgkmcnt(0)
	v_add_f32_dpp v14, v14, v14 row_half_mirror row_mask:0xf bank_mask:0xf
	s_waitcnt lgkmcnt(0)
	v_add_f32_dpp v6, v6, v6 quad_perm:[2,3,0,1] row_mask:0xf bank_mask:0xf
	v_add_f32_dpp v7, v7, v7 quad_perm:[2,3,0,1] row_mask:0xf bank_mask:0xf
	s_waitcnt lgkmcnt(0)
	v_add_f32_dpp v2, v2, v2 quad_perm:[2,3,0,1] row_mask:0xf bank_mask:0xf
	s_waitcnt lgkmcnt(0)
	v_add_f32_dpp v14, v14, v14 row_mirror row_mask:0xf bank_mask:0xf
	ds_bpermute_b32 v20, v136, v14
	s_waitcnt lgkmcnt(0)
	v_add_f32_dpp v6, v6, v6 row_half_mirror row_mask:0xf bank_mask:0xf
	v_add_f32_dpp v7, v7, v7 row_half_mirror row_mask:0xf bank_mask:0xf
	s_waitcnt lgkmcnt(0)
	v_add_f32_dpp v2, v2, v2 row_half_mirror row_mask:0xf bank_mask:0xf
	s_waitcnt lgkmcnt(0)
	v_add_f32_e32 v14, v14, v20
	ds_bpermute_b32 v20, v137, v14
	s_waitcnt lgkmcnt(0)
	v_add_f32_dpp v6, v6, v6 row_mirror row_mask:0xf bank_mask:0xf
	v_add_f32_dpp v7, v7, v7 row_mirror row_mask:0xf bank_mask:0xf
	ds_bpermute_b32 v13, v136, v7
	ds_bpermute_b32 v12, v136, v6
	s_waitcnt lgkmcnt(0)
	v_add_f32_dpp v2, v2, v2 row_mirror row_mask:0xf bank_mask:0xf
	ds_bpermute_b32 v15, v136, v2
	s_waitcnt lgkmcnt(0)
	v_pk_add_f32 v[78:79], v[6:7], v[12:13]
	v_add_f32_e32 v6, v14, v20
	v_fmamk_f32 v6, v6, 0x3a000000, v169
	v_mul_f32_e32 v7, 0x4b800000, v6
	v_cmp_gt_f32_e32 vcc, s3, v6
	s_waitcnt lgkmcnt(0)
	v_add_f32_e32 v2, v2, v15
	ds_bpermute_b32 v82, v137, v2
	v_cndmask_b32_e32 v6, v6, v7, vcc
	v_rsq_f32_e32 v6, v6
	ds_bpermute_b32 v81, v137, v79
	ds_bpermute_b32 v80, v137, v78
	v_mul_f32_e32 v7, 0x45800000, v6
	v_cndmask_b32_e32 v6, v6, v7, vcc
	v_mul_f32_e32 v132, 0.5, v6
	v_pk_fma_f32 v[6:7], v[4:5], v[132:133], v[42:43] op_sel_hi:[1,0,1]
	v_pk_fma_f32 v[4:5], v[10:11], v[132:133], v[40:41] op_sel_hi:[1,0,1]
	v_pk_fma_f32 v[10:11], v[8:9], v[132:133], v[46:47] op_sel_hi:[1,0,1]
	v_pk_fma_f32 v[8:9], v[68:69], v[132:133], v[44:45] op_sel_hi:[1,0,1]
	v_pk_fma_f32 v[14:15], v[16:17], v[132:133], v[38:39] op_sel_hi:[1,0,1]
	v_pk_fma_f32 v[12:13], v[18:19], v[132:133], v[36:37] op_sel_hi:[1,0,1]
	v_pk_fma_f32 v[22:23], v[70:71], v[132:133], v[54:55] op_sel_hi:[1,0,1]
	v_pk_fma_f32 v[20:21], v[72:73], v[132:133], v[52:53] op_sel_hi:[1,0,1]
	v_pk_fma_f32 v[18:19], v[74:75], v[132:133], v[50:51] op_sel_hi:[1,0,1]
	v_pk_fma_f32 v[16:17], v[76:77], v[132:133], v[48:49] op_sel_hi:[1,0,1]
	v_pk_fma_f32 v[26:27], v[26:27], v[132:133], v[58:59] op_sel_hi:[1,0,1]
	v_pk_fma_f32 v[24:25], v[24:25], v[132:133], v[56:57] op_sel_hi:[1,0,1]
	v_pk_fma_f32 v[30:31], v[28:29], v[132:133], v[62:63] op_sel_hi:[1,0,1]
	v_pk_fma_f32 v[28:29], v[156:157], v[132:133], v[60:61] op_sel_hi:[1,0,1]
	v_pk_fma_f32 v[34:35], v[34:35], v[132:133], v[66:67] op_sel_hi:[1,0,1]
	v_pk_fma_f32 v[32:33], v[32:33], v[132:133], v[64:65] op_sel_hi:[1,0,1]
	s_and_b64 vcc, exec, s[6:7]
	s_cbranch_vccz .LBB0_27
	s_mov_b64 s[14:15], 0x14e00000
	v_lshl_add_u64 v[36:37], v[120:121], 0, s[14:15]
	s_mov_b64 s[14:15], 0x14e00400
	v_lshl_add_u64 v[38:39], v[120:121], 0, s[14:15]
	s_mov_b64 s[14:15], 0x14e00800
	v_lshl_add_u64 v[40:41], v[120:121], 0, s[14:15]
	s_mov_b64 s[14:15], 0x14e00c00
	v_pk_mul_f32 v[52:53], v[132:133], v[132:133] op_sel_hi:[0,1]
	s_waitcnt lgkmcnt(0)
	v_pk_add_f32 v[54:55], v[78:79], v[80:81]
	v_lshl_add_u64 v[42:43], v[120:121], 0, s[14:15]
	s_mov_b64 s[14:15], 0x14e01000
	v_add_f32_e32 v2, v2, v82
	v_pk_mul_f32 v[52:53], v[54:55], v[52:53]
	v_lshl_add_u64 v[44:45], v[120:121], 0, s[14:15]
	s_mov_b64 s[14:15], 0x14e01400
	v_add_f32_e32 v2, v2, v53
	v_lshl_add_u64 v[46:47], v[120:121], 0, s[14:15]
	s_mov_b64 s[14:15], 0x14e01800
	v_add_f32_e32 v2, v52, v2
	v_lshl_add_u64 v[48:49], v[120:121], 0, s[14:15]
	s_mov_b64 s[14:15], 0x14e01c00
	v_fmamk_f32 v2, v2, 0x3a000000, v169
	v_lshl_add_u64 v[50:51], v[120:121], 0, s[14:15]
	global_store_dwordx4 v[36:37], v[4:7], off
	global_store_dwordx4 v[38:39], v[8:11], off
	global_store_dwordx4 v[40:41], v[12:15], off
	global_store_dwordx4 v[42:43], v[20:23], off
	global_store_dwordx4 v[44:45], v[16:19], off
	global_store_dwordx4 v[46:47], v[24:27], off
	global_store_dwordx4 v[48:49], v[28:31], off
	global_store_dwordx4 v[50:51], v[32:35], off
	v_cmp_gt_f32_e32 vcc, s3, v2
	v_mul_f32_e32 v36, 0x4b800000, v2
	s_add_i32 s5, s5, 5
	v_cndmask_b32_e32 v2, v2, v36, vcc
	v_rsq_f32_e32 v2, v2
	s_mul_hi_i32 s9, s5, 0x12000
	s_mul_i32 s5, s5, 0x12000
	s_add_u32 s16, s18, s5
	s_addc_u32 s17, s19, s9
	v_mul_f32_e32 v36, 0x45800000, v2
	s_add_u32 s14, s16, 0x2000
	v_cndmask_b32_e32 v2, v2, v36, vcc
	s_addc_u32 s15, s17, 0
	global_load_dwordx4 v[36:39], v[104:105], off
	global_load_dwordx4 v[40:43], v145, s[16:17]
	global_load_dwordx4 v[44:47], v145, s[14:15]
	v_pk_mul_f32 v[50:51], v[4:5], v[2:3] op_sel_hi:[1,0]
	v_pk_mul_f32 v[48:49], v[6:7], v[2:3] op_sel_hi:[1,0]
	s_mov_b32 s3, 0x19600000
	v_pk_mul_f32 v[52:53], v[8:9], v[2:3] op_sel_hi:[1,0]
	s_waitcnt vmcnt(2)
	v_pk_mul_f32 v[36:37], v[50:51], v[36:37]
	v_pk_mul_f32 v[38:39], v[48:49], v[38:39]
	s_waitcnt vmcnt(0)
; __device__ __forceinline__ unsigned pk2(float lo, float hi) { return f2bf(lo) | (f2bf(hi) << 16); }
; __device__ __forceinline__ void rowwise_phase(const Params& P, int mrows, bool first, int l_post, int j_post, int gate_idx, float coef, bool final_, int l_pre, int j_pre, int shift_idx, int scale_idx) {
;     ...
;             const float rs = rsqrtf(ss * (1.f / DM) + EPS);
;             const float* gp = P.norm_pre + (size_t)(l_pre * 3 + j_pre) * DM; const float* mb = MOD + (size_t)(l_pre * 5 + b) * NMODV;
;             bf16* hr = H + (size_t)row * DM;
; #pragma unroll
;             for (int j = 0; j < 8; ++j) { const int c = 4 * lane + 256 * j; const f32x4 g4 = *(const f32x4*)(gp + c), sh = *(const f32x4*)(mb + shift_idx * DM + c), scl = *(const f32x4*)(mb + scale_idx * DM + c);
;                 const f32x4 h = (xv[j] * rs) * g4 * (scl + 1.f) + sh; u32x2 w; w.x = pk2(h.x, h.y); w.y = pk2(h.z, h.w); *(u32x2*)(hr + c) = w; }
	v_pk_add_f32 v[44:45], v[44:45], 1.0 op_sel_hi:[1,0]
	v_pk_add_f32 v[46:47], v[46:47], 1.0 op_sel_hi:[1,0]
	v_pk_fma_f32 v[36:37], v[36:37], v[44:45], v[40:41]
	v_pk_fma_f32 v[38:39], v[38:39], v[46:47], v[42:43]
	v_bfe_u32 v40, v36, 16, 1
	v_add3_u32 v36, v36, v40, s71
	v_bfe_u32 v40, v37, 16, 1
	v_lshrrev_b32_e32 v36, 16, v36
	v_add3_u32 v37, v37, v40, s71
	v_and_or_b32 v40, v37, s70, v36
	v_bfe_u32 v36, v38, 16, 1
	v_add3_u32 v36, v38, v36, s71
	v_bfe_u32 v37, v39, 16, 1
	v_lshrrev_b32_e32 v36, 16, v36
	v_add3_u32 v37, v39, v37, s71
	v_and_or_b32 v41, v37, s70, v36
	v_add_co_u32_e32 v36, vcc, s3, v118
	v_pk_mul_f32 v[50:51], v[10:11], v[2:3] op_sel_hi:[1,0]
	s_nop 0
	v_addc_co_u32_e32 v37, vcc, 0, v119, vcc
	global_store_dwordx2 v[36:37], v[40:41], off
	global_load_dwordx4 v[196:199], v[104:105], off offset:1024
	global_load_dwordx4 v[200:203], v145, s[16:17] offset:1024
	global_load_dwordx4 v[204:207], v142, s[14:15]
	global_load_dwordx4 v[208:211], v[104:105], off offset:2048
	global_load_dwordx4 v[212:215], v145, s[16:17] offset:2048
	global_load_dwordx4 v[216:219], v143, s[14:15]
	global_load_dwordx4 v[220:223], v[104:105], off offset:3072
	global_load_dwordx4 v[224:227], v145, s[16:17] offset:3072
	global_load_dwordx4 v[228:231], v144, s[14:15]
	global_load_dwordx4 v[232:235], v[106:107], off
	global_load_dwordx4 v[236:239], v138, s[16:17]
	global_load_dwordx4 v[240:243], v138, s[14:15]
	s_nop 0
	s_waitcnt vmcnt(11)
	v_pk_mul_f32 v[38:39], v[52:53], v[196:197]
	v_pk_mul_f32 v[40:41], v[50:51], v[198:199]
	s_waitcnt vmcnt(9)
	v_pk_add_f32 v[46:47], v[204:205], 1.0 op_sel_hi:[1,0]
	v_pk_add_f32 v[48:49], v[206:207], 1.0 op_sel_hi:[1,0]
	v_pk_fma_f32 v[38:39], v[38:39], v[46:47], v[200:201]
	v_pk_fma_f32 v[40:41], v[40:41], v[48:49], v[202:203]
	v_bfe_u32 v42, v38, 16, 1
	v_add3_u32 v38, v38, v42, s71
	v_bfe_u32 v42, v39, 16, 1
	v_lshrrev_b32_e32 v38, 16, v38
	v_add3_u32 v39, v39, v42, s71
	v_and_or_b32 v38, v39, s70, v38
	v_bfe_u32 v39, v40, 16, 1
	v_add3_u32 v39, v40, v39, s71
	v_bfe_u32 v40, v41, 16, 1
	v_lshrrev_b32_e32 v39, 16, v39
	v_add3_u32 v40, v41, v40, s71
	v_and_or_b32 v39, v40, s70, v39
	global_store_dwordx2 v[36:37], v[38:39], off offset:512
	global_load_dwordx4 v[196:199], v[108:109], off
	global_load_dwordx4 v[200:203], v139, s[16:17]
	global_load_dwordx4 v[204:207], v139, s[14:15]
	s_nop 0
	v_pk_mul_f32 v[52:53], v[12:13], v[2:3] op_sel_hi:[1,0]
	v_pk_mul_f32 v[50:51], v[14:15], v[2:3] op_sel_hi:[1,0]
	s_waitcnt vmcnt(12)
	v_pk_mul_f32 v[38:39], v[52:53], v[208:209]
	v_pk_mul_f32 v[40:41], v[50:51], v[210:211]
	s_waitcnt vmcnt(10)
	v_pk_add_f32 v[46:47], v[216:217], 1.0 op_sel_hi:[1,0]
	v_pk_add_f32 v[48:49], v[218:219], 1.0 op_sel_hi:[1,0]
	v_pk_fma_f32 v[38:39], v[38:39], v[46:47], v[212:213]
	v_pk_fma_f32 v[40:41], v[40:41], v[48:49], v[214:215]
	v_bfe_u32 v42, v38, 16, 1
	v_add3_u32 v38, v38, v42, s71
	v_bfe_u32 v42, v39, 16, 1
	v_lshrrev_b32_e32 v38, 16, v38
	v_add3_u32 v39, v39, v42, s71
	v_and_or_b32 v38, v39, s70, v38
	v_bfe_u32 v39, v40, 16, 1
	v_add3_u32 v39, v40, v39, s71
	v_bfe_u32 v40, v41, 16, 1
	v_lshrrev_b32_e32 v39, 16, v39
	v_add3_u32 v40, v41, v40, s71
	v_and_or_b32 v39, v40, s70, v39
	global_store_dwordx2 v[36:37], v[38:39], off offset:1024
	global_load_dwordx4 v[208:211], v[110:111], off
	global_load_dwordx4 v[212:215], v140, s[16:17]
	global_load_dwordx4 v[216:219], v140, s[14:15]
	s_nop 0
	v_pk_mul_f32 v[52:53], v[20:21], v[2:3] op_sel_hi:[1,0]
	v_pk_mul_f32 v[50:51], v[22:23], v[2:3] op_sel_hi:[1,0]
	s_waitcnt vmcnt(13)
	v_pk_mul_f32 v[38:39], v[52:53], v[220:221]
	v_pk_mul_f32 v[40:41], v[50:51], v[222:223]
	s_waitcnt vmcnt(11)
; __device__ __forceinline__ unsigned pk2(float lo, float hi) { return f2bf(lo) | (f2bf(hi) << 16); }
; __device__ __forceinline__ void rowwise_phase(const Params& P, int mrows, bool first, int l_post, int j_post, int gate_idx, float coef, bool final_, int l_pre, int j_pre, int shift_idx, int scale_idx) {
;     ...
; #pragma unroll
;             for (int j = 0; j < 8; ++j) { const int c = 4 * lane + 256 * j; const f32x4 g4 = *(const f32x4*)(gp + c), sh = *(const f32x4*)(mb + shift_idx * DM + c), scl = *(const f32x4*)(mb + scale_idx * DM + c);
;                 const f32x4 h = (xv[j] * rs) * g4 * (scl + 1.f) + sh; u32x2 w; w.x = pk2(h.x, h.y); w.y = pk2(h.z, h.w); *(u32x2*)(hr + c) = w; }
	v_pk_add_f32 v[46:47], v[228:229], 1.0 op_sel_hi:[1,0]
	v_pk_add_f32 v[48:49], v[230:231], 1.0 op_sel_hi:[1,0]
	v_pk_fma_f32 v[38:39], v[38:39], v[46:47], v[224:225]
	v_pk_fma_f32 v[40:41], v[40:41], v[48:49], v[226:227]
	v_bfe_u32 v42, v38, 16, 1
	v_add3_u32 v38, v38, v42, s71
	v_bfe_u32 v42, v39, 16, 1
	v_lshrrev_b32_e32 v38, 16, v38
	v_add3_u32 v39, v39, v42, s71
	v_and_or_b32 v38, v39, s70, v38
	v_bfe_u32 v39, v40, 16, 1
	v_add3_u32 v39, v40, v39, s71
	v_bfe_u32 v40, v41, 16, 1
	v_lshrrev_b32_e32 v39, 16, v39
	v_add3_u32 v40, v41, v40, s71
	v_and_or_b32 v39, v40, s70, v39
	global_store_dwordx2 v[36:37], v[38:39], off offset:1536
	global_load_dwordx4 v[220:223], v[112:113], off
	global_load_dwordx4 v[224:227], v141, s[16:17]
	global_load_dwordx4 v[228:231], v141, s[14:15]
	s_nop 0
	v_pk_mul_f32 v[52:53], v[16:17], v[2:3] op_sel_hi:[1,0]
	v_pk_mul_f32 v[50:51], v[18:19], v[2:3] op_sel_hi:[1,0]
	s_waitcnt vmcnt(14)
	v_pk_mul_f32 v[38:39], v[52:53], v[232:233]
	v_pk_mul_f32 v[40:41], v[50:51], v[234:235]
	s_waitcnt vmcnt(12)
	v_pk_add_f32 v[46:47], v[240:241], 1.0 op_sel_hi:[1,0]
	v_pk_add_f32 v[48:49], v[242:243], 1.0 op_sel_hi:[1,0]
	v_pk_fma_f32 v[38:39], v[38:39], v[46:47], v[236:237]
	v_pk_fma_f32 v[40:41], v[40:41], v[48:49], v[238:239]
	v_bfe_u32 v42, v38, 16, 1
	v_add3_u32 v38, v38, v42, s71
	v_bfe_u32 v42, v39, 16, 1
	v_lshrrev_b32_e32 v38, 16, v38
	v_add3_u32 v39, v39, v42, s71
	v_and_or_b32 v38, v39, s70, v38
	v_bfe_u32 v39, v40, 16, 1
	v_add3_u32 v39, v40, v39, s71
	v_bfe_u32 v40, v41, 16, 1
	v_lshrrev_b32_e32 v39, 16, v39
	v_add3_u32 v40, v41, v40, s71
	v_and_or_b32 v39, v40, s70, v39
	global_store_dwordx2 v[36:37], v[38:39], off offset:2048
	s_nop 0
	v_pk_mul_f32 v[52:53], v[24:25], v[2:3] op_sel_hi:[1,0]
	v_pk_mul_f32 v[50:51], v[26:27], v[2:3] op_sel_hi:[1,0]
	s_waitcnt vmcnt(11)
	v_pk_mul_f32 v[38:39], v[52:53], v[196:197]
	v_pk_mul_f32 v[40:41], v[50:51], v[198:199]
	s_waitcnt vmcnt(9)
	v_pk_add_f32 v[46:47], v[204:205], 1.0 op_sel_hi:[1,0]
	v_pk_add_f32 v[48:49], v[206:207], 1.0 op_sel_hi:[1,0]
	v_pk_fma_f32 v[38:39], v[38:39], v[46:47], v[200:201]
	v_pk_fma_f32 v[40:41], v[40:41], v[48:49], v[202:203]
	v_bfe_u32 v42, v38, 16, 1
	v_add3_u32 v38, v38, v42, s71
	v_bfe_u32 v42, v39, 16, 1
	v_lshrrev_b32_e32 v38, 16, v38
	v_add3_u32 v39, v39, v42, s71
	v_and_or_b32 v38, v39, s70, v38
	v_bfe_u32 v39, v40, 16, 1
	v_add3_u32 v39, v40, v39, s71
	v_bfe_u32 v40, v41, 16, 1
	v_lshrrev_b32_e32 v39, 16, v39
	v_add3_u32 v40, v41, v40, s71
	v_and_or_b32 v39, v40, s70, v39
	global_store_dwordx2 v[36:37], v[38:39], off offset:2560
	s_nop 0
	v_pk_mul_f32 v[52:53], v[28:29], v[2:3] op_sel_hi:[1,0]
	v_pk_mul_f32 v[50:51], v[30:31], v[2:3] op_sel_hi:[1,0]
	s_waitcnt vmcnt(8)
	v_pk_mul_f32 v[38:39], v[52:53], v[208:209]
	v_pk_mul_f32 v[40:41], v[50:51], v[210:211]
	s_waitcnt vmcnt(6)
	v_pk_add_f32 v[46:47], v[216:217], 1.0 op_sel_hi:[1,0]
	v_pk_add_f32 v[48:49], v[218:219], 1.0 op_sel_hi:[1,0]
	v_pk_fma_f32 v[38:39], v[38:39], v[46:47], v[212:213]
	v_pk_fma_f32 v[40:41], v[40:41], v[48:49], v[214:215]
	v_bfe_u32 v42, v38, 16, 1
	v_add3_u32 v38, v38, v42, s71
	v_bfe_u32 v42, v39, 16, 1
	v_lshrrev_b32_e32 v38, 16, v38
	v_add3_u32 v39, v39, v42, s71
	v_and_or_b32 v38, v39, s70, v38
	v_bfe_u32 v39, v40, 16, 1
	v_add3_u32 v39, v40, v39, s71
	v_bfe_u32 v40, v41, 16, 1
	v_lshrrev_b32_e32 v39, 16, v39
	v_add3_u32 v40, v41, v40, s71
	v_and_or_b32 v39, v40, s70, v39
	global_store_dwordx2 v[36:37], v[38:39], off offset:3072
	s_nop 0
	v_pk_mul_f32 v[52:53], v[2:3], v[32:33] op_sel_hi:[0,1]
	v_pk_mul_f32 v[50:51], v[2:3], v[34:35] op_sel_hi:[0,1]
	s_mov_b64 s[14:15], 0
	s_waitcnt vmcnt(5)
	v_pk_mul_f32 v[38:39], v[52:53], v[220:221]
	v_pk_mul_f32 v[40:41], v[50:51], v[222:223]
	s_waitcnt vmcnt(3)
	v_pk_add_f32 v[46:47], v[228:229], 1.0 op_sel_hi:[1,0]
	v_pk_add_f32 v[48:49], v[230:231], 1.0 op_sel_hi:[1,0]
	v_pk_fma_f32 v[38:39], v[38:39], v[46:47], v[224:225]
	v_pk_fma_f32 v[40:41], v[40:41], v[48:49], v[226:227]
	v_bfe_u32 v2, v38, 16, 1
	v_add3_u32 v2, v38, v2, s71
	v_bfe_u32 v38, v39, 16, 1
	v_lshrrev_b32_e32 v2, 16, v2
	v_add3_u32 v38, v39, v38, s71
	v_and_or_b32 v38, v38, s70, v2
	v_bfe_u32 v2, v40, 16, 1
	v_add3_u32 v2, v40, v2, s71
	v_bfe_u32 v39, v41, 16, 1
	v_lshrrev_b32_e32 v2, 16, v2
	v_add3_u32 v39, v41, v39, s71
	v_and_or_b32 v39, v39, s70, v2
	global_store_dwordx2 v[36:37], v[38:39], off offset:3584

; __device__ __forceinline__ float dot4(f32x4 a) { return (a.x * a.x + a.y * a.y) + (a.z * a.z + a.w * a.w); }
; __device__ __forceinline__ void rowwise_phase(const Params& P, int mrows, bool first, int l_post, int j_post, int gate_idx, float coef, bool final_, int l_pre, int j_pre, int shift_idx, int scale_idx) {
;     ...
;         const int b = row < MLAT ? (row >> 11) : 4;
;     ...
;             const float* gp = P.norm_post + (size_t)(l_post * 3 + j_post) * DM; const float* mg = MOD + (size_t)(l_post * 5 + b) * NMODV + gate_idx * DM;
;             float sxx = 0.f, sxt = 0.f, stt = 0.f;
; #pragma unroll
;             for (int j = 0; j < 8; ++j) { const int c = 4 * lane + 256 * j; xv[j] = *(const f32x4*)(xr + c); const f32x4 g4 = *(const f32x4*)(gp + c), m4 = *(const f32x4*)(mg + c);
;                 ss += dot4(yv[j]); yv[j] = yv[j] * g4 * m4; sxx += dot4(xv[j]); stt += dot4(yv[j]);
;                 const f32x4 xt = xv[j] * yv[j]; sxt += (xt.x + xt.y) + (xt.z + xt.w); }
.LBB0_36:
	v_lshl_add_u64 v[36:37], s[94:95], 0, v[110:111]
	s_mov_b32 s1, 0x14e00000
	v_add_co_u32_e32 v116, vcc, s1, v36
	s_mov_b32 s1, 0x14e01000
	s_nop 0
	v_addc_co_u32_e32 v117, vcc, 0, v37, vcc
	global_load_dwordx4 v[56:59], v[0:1], off
	v_add_co_u32_e32 v114, vcc, s1, v36
	s_min_i32 s1, s0, 0x2000
	v_readlane_b32 s10, v255, 14
	v_addc_co_u32_e32 v115, vcc, 0, v37, vcc
	s_ashr_i32 s1, s1, 11
	s_mul_i32 s5, s10, 5
	global_load_dwordx4 v[60:63], v[0:1], off offset:1024
	global_load_dwordx4 v[64:67], v[0:1], off offset:2048
	global_load_dwordx4 v[40:43], v[114:115], off offset:-4096
	global_load_dwordx4 v[36:39], v[116:117], off offset:1024
	s_add_i32 s5, s1, s5
	s_mul_hi_i32 s1, s5, 0x12000
	s_mul_i32 s5, s5, 0x12000
	v_readlane_b32 s11, v255, 15
	s_add_u32 s10, s18, s5
	s_addc_u32 s11, s19, s1
	s_nop 2
	global_load_dwordx4 v[76:79], v128, s[10:11]
	global_load_dwordx4 v[72:75], v128, s[10:11] offset:1024
	global_load_dwordx4 v[68:71], v128, s[10:11] offset:2048
	global_load_dwordx4 v[44:47], v[116:117], off offset:2048
	global_load_dwordx4 v[80:83], v[0:1], off offset:3072
	global_load_dwordx4 v[84:87], v[88:89], off
	s_waitcnt vmcnt(0)
	v_pk_mul_f32 v[48:49], v[18:19], v[18:19]
	v_pk_mul_f32 v[50:51], v[16:17], v[16:17]
	v_mov_b32_e32 v119, v4
	v_pk_mov_b32 v[52:53], v[50:51], v[48:49] op_sel:[1,0]
	v_mov_b32_e32 v51, v49
	v_pk_add_f32 v[52:53], v[52:53], v[50:51]
	global_load_dwordx4 v[48:51], v[114:115], off
	v_pk_add_f32 v[152:153], v[52:53], v[52:53] op_sel_hi:[0,1]
	global_load_dwordx4 v[52:55], v[116:117], off offset:3072
	global_load_dwordx4 v[140:143], v128, s[10:11] offset:3072
	global_load_dwordx4 v[144:147], v129, s[10:11]
	global_load_dwordx4 v[148:151], v135, s[10:11]
	v_mov_b32_e32 v121, v6
	v_mov_b32_e32 v118, v8
	v_mov_b32_e32 v120, v10
	v_mul_f32_e32 v152, v22, v22
	s_mov_b32 s3, 0x800000
	s_add_u32 s5, s16, s5
	s_addc_u32 s1, s17, s1
	v_lshl_add_u64 v[108:109], v[108:109], 0, s[6:7]
	v_lshl_add_u64 v[110:111], v[110:111], 0, s[8:9]
	s_waitcnt vmcnt(15)
	v_pk_mul_f32 v[58:59], v[6:7], v[58:59]
	v_pk_mul_f32 v[56:57], v[4:5], v[56:57]
	v_mov_b32_e32 v4, v9
	v_mov_b32_e32 v6, v11
	v_pk_mul_f32 v[4:5], v[4:5], v[4:5]
	v_pk_mul_f32 v[6:7], v[6:7], v[6:7]
	v_pk_fma_f32 v[4:5], v[118:119], v[118:119], v[4:5]
	v_pk_fma_f32 v[6:7], v[120:121], v[120:121], v[6:7]
	s_waitcnt vmcnt(14)
	v_pk_mul_f32 v[10:11], v[10:11], v[62:63]
	v_pk_mul_f32 v[8:9], v[8:9], v[60:61]
	s_waitcnt vmcnt(13)
	v_pk_mul_f32 v[60:61], v[18:19], v[66:67]
	v_pk_mul_f32 v[62:63], v[16:17], v[64:65]
	s_waitcnt vmcnt(12)
	v_mov_b32_e32 v18, v41
	s_waitcnt vmcnt(11)
	v_mov_b32_e32 v19, v37
	v_mov_b32_e32 v64, v42
	v_mov_b32_e32 v65, v38
	v_mov_b32_e32 v16, v40
	v_mov_b32_e32 v17, v36
	v_mov_b32_e32 v66, v43
	v_mov_b32_e32 v67, v39
	v_pk_add_f32 v[4:5], v[4:5], v[6:7]
	v_pk_mul_f32 v[6:7], v[18:19], v[18:19]
	v_pk_mul_f32 v[18:19], v[64:65], v[64:65]
	v_pk_add_f32 v[64:65], v[4:5], v[4:5] op_sel_hi:[0,1]
	v_pk_fma_f32 v[4:5], v[16:17], v[16:17], v[6:7]
	v_pk_fma_f32 v[6:7], v[66:67], v[66:67], v[18:19]
	s_waitcnt vmcnt(10)
	v_pk_mul_f32 v[16:17], v[78:79], v[58:59]
	v_pk_mul_f32 v[18:19], v[76:77], v[56:57]
	s_waitcnt vmcnt(9)
	v_pk_mul_f32 v[56:57], v[74:75], v[10:11]
	v_pk_mul_f32 v[58:59], v[72:73], v[8:9]
	v_mul_f32_e32 v2, v17, v17
	v_pk_mul_f32 v[8:9], v[42:43], v[16:17]
	v_pk_mul_f32 v[10:11], v[40:41], v[18:19]
	v_pk_mul_f32 v[74:75], v[38:39], v[56:57]
	v_pk_mul_f32 v[76:77], v[36:37], v[58:59]
	v_pk_add_f32 v[154:155], v[4:5], v[6:7]
	s_waitcnt vmcnt(8)
	v_pk_mul_f32 v[60:61], v[70:71], v[60:61]
	v_pk_mul_f32 v[62:63], v[68:69], v[62:63]
	v_mul_f32_e32 v4, v18, v18
	v_mul_f32_e32 v6, v19, v19
	v_mul_f32_e32 v66, v58, v58
	v_mul_f32_e32 v68, v59, v59
	v_mul_f32_e32 v70, v56, v56
	v_mul_f32_e32 v72, v57, v57
	v_pk_fma_f32 v[78:79], v[16:17], v[16:17], v[2:3] op_sel_hi:[1,1,0]
	v_add_f32_e32 v5, v10, v11
	v_add_f32_e32 v7, v8, v9
	s_waitcnt vmcnt(7)
	v_pk_mul_f32 v[8:9], v[46:47], v[46:47]
	v_pk_mul_f32 v[10:11], v[44:45], v[44:45]
	v_mov_b32_e32 v67, v76
	v_mov_b32_e32 v69, v77
	v_mov_b32_e32 v71, v74
	v_mov_b32_e32 v73, v75
	v_pk_mov_b32 v[118:119], v[10:11], v[8:9] op_sel:[1,0]
	v_mov_b32_e32 v11, v9
	v_pk_mul_f32 v[158:159], v[46:47], v[60:61]
	v_pk_mul_f32 v[160:161], v[44:45], v[62:63]
	v_pk_add_f32 v[4:5], v[4:5], v[6:7]
	v_mov_b32_e32 v79, v3
	v_pk_add_f32 v[6:7], v[66:67], v[68:69]
	v_pk_add_f32 v[66:67], v[70:71], v[72:73]
	v_pk_add_f32 v[156:157], v[10:11], v[118:119]
	v_mul_f32_e32 v8, v62, v62
	v_mul_f32_e32 v10, v63, v63
	v_mul_f32_e32 v118, v60, v60
	v_mul_f32_e32 v120, v61, v61
	v_pk_add_f32 v[4:5], v[4:5], v[78:79]
	v_pk_add_f32 v[6:7], v[6:7], v[66:67]
	v_mov_b32_e32 v9, v160
	v_mov_b32_e32 v11, v161
	v_mov_b32_e32 v119, v158
	global_load_dwordx4 v[68:71], v[90:91], off
	global_load_dwordx4 v[76:79], v[92:93], off
	v_mov_b32_e32 v121, v159
	v_pk_add_f32 v[66:67], v[4:5], v[6:7]
	v_pk_add_f32 v[8:9], v[8:9], v[10:11]
	global_load_dwordx4 v[72:75], v130, s[10:11]
	v_pk_add_f32 v[10:11], v[118:119], v[120:121]
	global_load_dwordx4 v[4:7], v[114:115], off offset:1024
	v_pk_add_f32 v[8:9], v[8:9], v[10:11]
	v_mul_f32_e32 v2, v12, v12
	v_pk_add_f32 v[158:159], v[66:67], v[8:9]
	v_pk_fma_f32 v[8:9], v[12:13], v[12:13], v[2:3] op_sel_hi:[1,1,0]
	v_mul_f32_e32 v2, v14, v14
	v_pk_fma_f32 v[10:11], v[14:15], v[14:15], v[2:3] op_sel_hi:[1,1,0]
	s_waitcnt vmcnt(10)
	v_pk_mul_f32 v[14:15], v[14:15], v[82:83]
	v_pk_mul_f32 v[66:67], v[12:13], v[80:81]
	global_load_dwordx4 v[80:83], v131, s[10:11]
	s_waitcnt vmcnt(7)
; __device__ __forceinline__ float dot4(f32x4 a) { return (a.x * a.x + a.y * a.y) + (a.z * a.z + a.w * a.w); }
; __device__ __forceinline__ void rowwise_phase(const Params& P, int mrows, bool first, int l_post, int j_post, int gate_idx, float coef, bool final_, int l_pre, int j_pre, int shift_idx, int scale_idx) {
;     ...
;             for (int j = 0; j < 8; ++j) { const int c = 4 * lane + 256 * j; xv[j] = *(const f32x4*)(xr + c); const f32x4 g4 = *(const f32x4*)(gp + c), m4 = *(const f32x4*)(mg + c);
;                 ss += dot4(yv[j]); yv[j] = yv[j] * g4 * m4; sxx += dot4(xv[j]); stt += dot4(yv[j]);
;                 const f32x4 xt = xv[j] * yv[j]; sxt += (xt.x + xt.y) + (xt.z + xt.w); }
; #pragma unroll
;             for (int o = 1; o < 64; o <<= 1) { ss += __shfl_xor(ss, o); sxx += __shfl_xor(sxx, o); sxt += __shfl_xor(sxt, o); stt += __shfl_xor(stt, o); }
;             const float rs = rsqrtf(ss * (1.f / DM) + EPS) * coef;
	v_pk_mul_f32 v[12:13], v[142:143], v[14:15]
	v_pk_mul_f32 v[14:15], v[140:141], v[66:67]
	v_pk_mul_f32 v[142:143], v[54:55], v[12:13]
	v_pk_mul_f32 v[160:161], v[52:53], v[14:15]
	v_mul_f32_e32 v66, v14, v14
	v_mul_f32_e32 v118, v15, v15
	v_mul_f32_e32 v120, v12, v12
	v_mul_f32_e32 v140, v13, v13
	v_mov_b32_e32 v67, v160
	v_mov_b32_e32 v119, v161
	v_mov_b32_e32 v121, v142
	v_mov_b32_e32 v141, v143
	v_pk_add_f32 v[66:67], v[66:67], v[118:119]
	v_pk_add_f32 v[118:119], v[120:121], v[140:141]
	v_mul_f32_e32 v8, v20, v20
	v_mul_f32_e32 v10, v21, v21
	v_mul_f32_e32 v64, v23, v23
	v_pk_add_f32 v[140:141], v[66:67], v[118:119]
	v_pk_add_f32 v[66:67], v[8:9], v[10:11]
	v_pk_add_f32 v[64:65], v[152:153], v[64:65]
	global_load_dwordx4 v[118:121], v[94:95], off
	v_pk_add_f32 v[64:65], v[66:67], v[64:65]
	v_pk_mul_f32 v[22:23], v[22:23], v[86:87]
	v_pk_mul_f32 v[20:21], v[20:21], v[84:85]
	v_pk_add_f32 v[142:143], v[64:65], v[64:65] op_sel_hi:[0,1]
	s_waitcnt vmcnt(7)
	v_pk_mul_f32 v[64:65], v[146:147], v[22:23]
	v_pk_mul_f32 v[66:67], v[144:145], v[20:21]
	global_load_dwordx4 v[20:23], v[114:115], off offset:3072
	global_load_dwordx4 v[8:11], v[114:115], off offset:2048
	v_mul_f32_e32 v2, v48, v48
	v_mul_f32_e32 v132, v49, v49
	v_pk_add_f32 v[84:85], v[154:155], v[154:155] op_sel:[0,1] op_sel_hi:[1,0]
	v_pk_add_f32 v[86:87], v[156:157], v[156:157] op_sel:[0,1] op_sel_hi:[1,0]
	v_mov_b32_e32 v85, v2
	v_mov_b32_e32 v87, v132
	v_mul_f32_e32 v2, v53, v53
	v_pk_add_f32 v[84:85], v[84:85], v[86:87]
	v_pk_fma_f32 v[86:87], v[52:53], v[52:53], v[2:3] op_sel_hi:[1,1,0]
	v_mul_f32_e32 v2, v55, v55
	v_mul_f32_e32 v139, v50, v50
	v_mul_f32_e32 v142, v51, v51
	v_pk_fma_f32 v[144:145], v[54:55], v[54:55], v[2:3] op_sel_hi:[1,1,0]
	v_mov_b32_e32 v87, v142
	v_mov_b32_e32 v145, v139
	v_pk_add_f32 v[86:87], v[86:87], v[144:145]
	v_pk_mul_f32 v[154:155], v[50:51], v[64:65]
	v_pk_mul_f32 v[156:157], v[48:49], v[66:67]
	v_pk_add_f32 v[84:85], v[84:85], v[86:87]
	v_mul_f32_e32 v86, v66, v66
	v_mul_f32_e32 v144, v67, v67
	v_mul_f32_e32 v146, v64, v64
	v_mul_f32_e32 v152, v65, v65
	v_mov_b32_e32 v87, v156
	v_mov_b32_e32 v145, v157
	v_mov_b32_e32 v147, v154
	v_mov_b32_e32 v153, v155
	v_pk_add_f32 v[86:87], v[86:87], v[144:145]
	v_pk_add_f32 v[144:145], v[146:147], v[152:153]
	v_pk_mul_f32 v[146:147], v[26:27], v[26:27]
	v_pk_mul_f32 v[152:153], v[24:25], v[24:25]
	v_mul_f32_e32 v2, v28, v28
	v_pk_mov_b32 v[154:155], v[152:153], v[146:147] op_sel:[1,0]
	v_mov_b32_e32 v153, v147
	s_waitcnt vmcnt(7)
	v_pk_mul_f32 v[26:27], v[26:27], v[70:71]
	v_pk_mul_f32 v[24:25], v[24:25], v[68:69]
	v_pk_add_f32 v[146:147], v[154:155], v[152:153]
	v_pk_fma_f32 v[164:165], v[28:29], v[28:29], v[2:3] op_sel_hi:[1,1,0]
	v_mul_f32_e32 v2, v30, v30
	s_waitcnt vmcnt(5)
	v_pk_mul_f32 v[68:69], v[74:75], v[26:27]
	v_pk_mul_f32 v[70:71], v[72:73], v[24:25]
	s_waitcnt vmcnt(4)
	v_pk_mul_f32 v[24:25], v[6:7], v[6:7]
	v_pk_mul_f32 v[26:27], v[4:5], v[4:5]
	v_pk_add_f32 v[146:147], v[146:147], v[146:147] op_sel_hi:[0,1]
	v_pk_mov_b32 v[72:73], v[26:27], v[24:25] op_sel:[1,0]
	v_mov_b32_e32 v27, v25
	v_pk_fma_f32 v[166:167], v[30:31], v[30:31], v[2:3] op_sel_hi:[1,1,0]
	v_pk_add_f32 v[72:73], v[26:27], v[72:73]
	v_pk_mul_f32 v[24:25], v[30:31], v[78:79]
	v_pk_mul_f32 v[26:27], v[28:29], v[76:77]
	v_mul_f32_e32 v164, v32, v32
	v_mul_f32_e32 v166, v33, v33
	v_mul_f32_e32 v146, v34, v34
	v_mul_f32_e32 v142, v35, v35
	s_waitcnt vmcnt(3)
	v_pk_mul_f32 v[76:77], v[82:83], v[24:25]
	v_pk_mul_f32 v[78:79], v[80:81], v[26:27]
	v_pk_add_f32 v[80:81], v[164:165], v[166:167]
	v_pk_add_f32 v[82:83], v[146:147], v[142:143]
	s_add_u32 s10, s5, 0xc000
	v_pk_add_f32 v[80:81], v[80:81], v[82:83]
	s_addc_u32 s11, s1, 0
	v_add_f32_e32 v2, v80, v81
	v_pk_mul_f32 v[160:161], v[6:7], v[68:69]
	v_pk_mul_f32 v[162:163], v[4:5], v[70:71]
	s_add_u32 s12, s5, 0xe000
	s_addc_u32 s13, s1, 0
	s_waitcnt lgkmcnt(0)
	v_add_f32_dpp v2, v2, v2 quad_perm:[1,0,3,2] row_mask:0xf bank_mask:0xf
	v_mul_f32_e32 v74, v70, v70
	v_mul_f32_e32 v152, v71, v71
	s_waitcnt vmcnt(2)
	v_pk_mul_f32 v[32:33], v[32:33], v[118:119]
	v_pk_mul_f32 v[34:35], v[34:35], v[120:121]
	s_waitcnt lgkmcnt(0)
	v_add_f32_dpp v2, v2, v2 quad_perm:[2,3,0,1] row_mask:0xf bank_mask:0xf
	v_pk_mul_f32 v[120:121], v[148:149], v[32:33]
	v_pk_add_f32 v[32:33], v[84:85], v[84:85] op_sel:[0,1] op_sel_hi:[1,0]
	v_pk_mul_f32 v[118:119], v[150:151], v[34:35]
	s_waitcnt vmcnt(1)
	v_mul_f32_e32 v27, v20, v20
	s_waitcnt lgkmcnt(0)
	v_add_f32_dpp v25, v2, v2 row_half_mirror row_mask:0xf bank_mask:0xf
	v_mov_b32_e32 v33, v27
	s_waitcnt vmcnt(0)
	v_mul_f32_e32 v2, v9, v9
	v_pk_fma_f32 v[84:85], v[8:9], v[8:9], v[2:3] op_sel_hi:[1,1,0]
	v_mul_f32_e32 v2, v11, v11
	v_pk_fma_f32 v[142:143], v[10:11], v[10:11], v[2:3] op_sel_hi:[1,1,0]
	s_waitcnt lgkmcnt(0)
	v_add_f32_dpp v25, v25, v25 row_mirror row_mask:0xf bank_mask:0xf
	ds_bpermute_b32 v27, v126, v25
	v_mul_f32_e32 v29, v21, v21
	v_pk_add_f32 v[34:35], v[72:73], v[72:73] op_sel:[0,1] op_sel_hi:[1,0]
	v_pk_mul_f32 v[80:81], v[10:11], v[76:77]
	v_mov_b32_e32 v35, v29
	s_waitcnt lgkmcnt(0)
	v_add_f32_e32 v2, v25, v27
	ds_bpermute_b32 v25, v127, v2
	v_pk_add_f32 v[72:73], v[32:33], v[34:35]
	v_pk_add_f32 v[32:33], v[158:159], v[140:141]
	v_pk_add_f32 v[34:35], v[86:87], v[144:145]
	v_pk_mul_f32 v[82:83], v[8:9], v[78:79]
	s_waitcnt lgkmcnt(0)
; __device__ __forceinline__ float dot4(f32x4 a) { return (a.x * a.x + a.y * a.y) + (a.z * a.z + a.w * a.w); }
; __device__ __forceinline__ void rowwise_phase(const Params& P, int mrows, bool first, int l_post, int j_post, int gate_idx, float coef, bool final_, int l_pre, int j_pre, int shift_idx, int scale_idx) {
;     ...
; #pragma unroll
;             for (int o = 1; o < 64; o <<= 1) { ss += __shfl_xor(ss, o); sxx += __shfl_xor(sxx, o); sxt += __shfl_xor(sxt, o); stt += __shfl_xor(stt, o); }
;             const float rs = rsqrtf(ss * (1.f / DM) + EPS) * coef;
;             ss_new = sxx + 2.f * rs * sxt + rs * rs * stt;
; #pragma unroll
;             for (int j = 0; j < 8; ++j) xv[j] += yv[j] * rs;
;     ...
;             for (int j = 0; j < 8; ++j) { if (!first) *(f32x4*)(xr + 4 * lane + 256 * j) = xv[j]; else ss += dot4(xv[j]); }
;             if (first) ss = wave_sum(ss); else ss = ss_new;
;             const float rs = rsqrtf(ss * (1.f / DM) + EPS);
	v_add_f32_e32 v2, v2, v25
	v_fmamk_f32 v2, v2, 0x3a000000, v169
	v_mul_f32_e32 v25, 0x4b800000, v2
	v_cmp_gt_f32_e32 vcc, s3, v2
	v_pk_add_f32 v[86:87], v[32:33], v[34:35]
	v_mul_f32_e32 v31, v22, v22
	v_cndmask_b32_e32 v2, v2, v25, vcc
	v_rsq_f32_e32 v2, v2
	v_mul_f32_e32 v75, v23, v23
	v_pk_mul_f32 v[166:167], v[22:23], v[118:119]
	v_pk_mul_f32 v[194:195], v[20:21], v[120:121]
	v_mul_f32_e32 v25, 0x45800000, v2
	v_cndmask_b32_e32 v132, v2, v25, vcc
	v_pk_fma_f32 v[34:35], v[16:17], v[132:133], v[42:43] op_sel_hi:[1,0,1]
	v_pk_fma_f32 v[32:33], v[18:19], v[132:133], v[40:41] op_sel_hi:[1,0,1]
	v_pk_fma_f32 v[38:39], v[56:57], v[132:133], v[38:39] op_sel_hi:[1,0,1]
	v_pk_fma_f32 v[36:37], v[58:59], v[132:133], v[36:37] op_sel_hi:[1,0,1]
	v_pk_fma_f32 v[42:43], v[60:61], v[132:133], v[46:47] op_sel_hi:[1,0,1]
	v_pk_fma_f32 v[40:41], v[62:63], v[132:133], v[44:45] op_sel_hi:[1,0,1]
	v_pk_fma_f32 v[46:47], v[12:13], v[132:133], v[54:55] op_sel_hi:[1,0,1]
	v_pk_fma_f32 v[44:45], v[14:15], v[132:133], v[52:53] op_sel_hi:[1,0,1]
	v_pk_fma_f32 v[18:19], v[64:65], v[132:133], v[50:51] op_sel_hi:[1,0,1]
	v_pk_fma_f32 v[16:17], v[66:67], v[132:133], v[48:49] op_sel_hi:[1,0,1]
	v_pk_fma_f32 v[14:15], v[68:69], v[132:133], v[6:7] op_sel_hi:[1,0,1]
	v_pk_fma_f32 v[12:13], v[70:71], v[132:133], v[4:5] op_sel_hi:[1,0,1]
	v_pk_fma_f32 v[10:11], v[76:77], v[132:133], v[10:11] op_sel_hi:[1,0,1]
	v_pk_fma_f32 v[8:9], v[78:79], v[132:133], v[8:9] op_sel_hi:[1,0,1]
	v_pk_fma_f32 v[6:7], v[118:119], v[132:133], v[22:23] op_sel_hi:[1,0,1]
	v_pk_fma_f32 v[4:5], v[120:121], v[132:133], v[20:21] op_sel_hi:[1,0,1]
	global_store_dwordx4 v[114:115], v[32:35], off offset:-4096
	global_store_dwordx4 v[116:117], v[36:39], off offset:1024
	global_store_dwordx4 v[116:117], v[40:43], off offset:2048
	global_store_dwordx4 v[116:117], v[44:47], off offset:3072
	global_store_dwordx4 v[114:115], v[16:19], off
	global_store_dwordx4 v[114:115], v[12:15], off offset:1024
	global_store_dwordx4 v[114:115], v[8:11], off offset:2048
	global_store_dwordx4 v[114:115], v[4:7], off offset:3072
	global_load_dwordx4 v[20:23], v[96:97], off
	global_load_dwordx4 v[48:51], v128, s[10:11]
	global_load_dwordx4 v[52:55], v128, s[12:13]
	v_mul_f32_e32 v154, v68, v68
	v_mul_f32_e32 v156, v69, v69
	v_mov_b32_e32 v85, v75
	v_mov_b32_e32 v75, v162
	v_mov_b32_e32 v153, v163
	v_mov_b32_e32 v155, v160
	v_mov_b32_e32 v157, v161
	v_mul_f32_e32 v28, v78, v78
	v_mul_f32_e32 v30, v79, v79
	v_mul_f32_e32 v24, v76, v76
	v_mul_f32_e32 v26, v77, v77
	v_mov_b32_e32 v143, v31
	v_pk_add_f32 v[74:75], v[74:75], v[152:153]
	v_pk_add_f32 v[140:141], v[154:155], v[156:157]
	v_mov_b32_e32 v29, v82
	v_mov_b32_e32 v31, v83
	v_mov_b32_e32 v25, v80
	v_mov_b32_e32 v27, v81
	v_mul_f32_e32 v146, v120, v120
	v_mul_f32_e32 v148, v121, v121
	v_mul_f32_e32 v150, v118, v118
	v_mul_f32_e32 v164, v119, v119
	v_pk_add_f32 v[56:57], v[74:75], v[140:141]
	v_pk_add_f32 v[28:29], v[28:29], v[30:31]
	v_pk_add_f32 v[24:25], v[24:25], v[26:27]
	v_mov_b32_e32 v147, v194
	v_mov_b32_e32 v149, v195
	v_mov_b32_e32 v151, v166
	v_mov_b32_e32 v165, v167
	v_pk_add_f32 v[56:57], v[86:87], v[56:57]
	v_pk_add_f32 v[24:25], v[28:29], v[24:25]
	v_pk_add_f32 v[26:27], v[146:147], v[148:149]
	v_pk_add_f32 v[28:29], v[150:151], v[164:165]
	v_pk_add_f32 v[24:25], v[56:57], v[24:25]
	v_pk_add_f32 v[26:27], v[26:27], v[28:29]
	v_pk_add_f32 v[28:29], v[84:85], v[142:143]
	v_pk_add_f32 v[24:25], v[24:25], v[26:27]
	v_pk_add_f32 v[28:29], v[72:73], v[28:29]
	v_add_f32_e32 v2, v28, v29
	s_mov_b32 s1, 0x19600000
	s_add_i32 s0, s0, s4
	s_waitcnt lgkmcnt(0)
	v_add_f32_dpp v24, v24, v24 quad_perm:[1,0,3,2] row_mask:0xf bank_mask:0xf
	v_add_f32_dpp v25, v25, v25 quad_perm:[1,0,3,2] row_mask:0xf bank_mask:0xf
	s_waitcnt lgkmcnt(0)
	v_add_f32_dpp v2, v2, v2 quad_perm:[1,0,3,2] row_mask:0xf bank_mask:0xf
	s_waitcnt lgkmcnt(0)
	v_add_f32_dpp v24, v24, v24 quad_perm:[2,3,0,1] row_mask:0xf bank_mask:0xf
	v_add_f32_dpp v25, v25, v25 quad_perm:[2,3,0,1] row_mask:0xf bank_mask:0xf
	s_waitcnt lgkmcnt(0)
	v_add_f32_dpp v2, v2, v2 quad_perm:[2,3,0,1] row_mask:0xf bank_mask:0xf
	s_waitcnt lgkmcnt(0)
	v_add_f32_dpp v24, v24, v24 row_half_mirror row_mask:0xf bank_mask:0xf
	v_add_f32_dpp v25, v25, v25 row_half_mirror row_mask:0xf bank_mask:0xf
	s_waitcnt lgkmcnt(0)
	v_add_f32_dpp v2, v2, v2 row_half_mirror row_mask:0xf bank_mask:0xf
	s_waitcnt lgkmcnt(0)
	v_add_f32_dpp v24, v24, v24 row_mirror row_mask:0xf bank_mask:0xf
	v_add_f32_dpp v25, v25, v25 row_mirror row_mask:0xf bank_mask:0xf
	ds_bpermute_b32 v27, v126, v25
	ds_bpermute_b32 v26, v126, v24
	s_waitcnt lgkmcnt(0)
	v_add_f32_dpp v2, v2, v2 row_mirror row_mask:0xf bank_mask:0xf
	ds_bpermute_b32 v28, v126, v2
	s_waitcnt lgkmcnt(0)
	v_pk_add_f32 v[24:25], v[24:25], v[26:27]
	ds_bpermute_b32 v27, v127, v25
	ds_bpermute_b32 v26, v127, v24
	s_waitcnt lgkmcnt(0)
	v_add_f32_e32 v2, v2, v28
	ds_bpermute_b32 v28, v127, v2
	s_waitcnt lgkmcnt(0)
	v_pk_add_f32 v[24:25], v[24:25], v[26:27]
	v_pk_mul_f32 v[26:27], v[132:133], v[132:133] op_sel_hi:[0,1]
	v_pk_mul_f32 v[24:25], v[24:25], v[26:27]
	s_waitcnt lgkmcnt(0)
	v_add_f32_e32 v2, v2, v28
	v_add_f32_e32 v2, v2, v25
	v_add_f32_e32 v2, v24, v2
	v_fmamk_f32 v2, v2, 0x3a000000, v169
	v_mul_f32_e32 v24, 0x4b800000, v2
	v_cmp_gt_f32_e32 vcc, s3, v2
	s_nop 1
	v_cndmask_b32_e32 v2, v2, v24, vcc
	v_rsq_f32_e32 v2, v2
	s_nop 0
	v_mul_f32_e32 v24, 0x45800000, v2
	v_cndmask_b32_e32 v2, v2, v24, vcc
	v_pk_mul_f32 v[26:27], v[32:33], v[2:3] op_sel_hi:[1,0]
	v_pk_mul_f32 v[24:25], v[34:35], v[2:3] op_sel_hi:[1,0]
	s_waitcnt vmcnt(2)
	v_pk_mul_f32 v[20:21], v[20:21], v[26:27]
	s_waitcnt vmcnt(0)
; __device__ __forceinline__ unsigned pk2(float lo, float hi) { return f2bf(lo) | (f2bf(hi) << 16); }
; __device__ __forceinline__ void rowwise_phase(const Params& P, int mrows, bool first, int l_post, int j_post, int gate_idx, float coef, bool final_, int l_pre, int j_pre, int shift_idx, int scale_idx) {
;     ...
;             const float rs = rsqrtf(ss * (1.f / DM) + EPS);
;             const float* gp = P.norm_pre + (size_t)(l_pre * 3 + j_pre) * DM; const float* mb = MOD + (size_t)(l_pre * 5 + b) * NMODV;
;             bf16* hr = H + (size_t)row * DM;
; #pragma unroll
;             for (int j = 0; j < 8; ++j) { const int c = 4 * lane + 256 * j; const f32x4 g4 = *(const f32x4*)(gp + c), sh = *(const f32x4*)(mb + shift_idx * DM + c), scl = *(const f32x4*)(mb + scale_idx * DM + c);
;                 const f32x4 h = (xv[j] * rs) * g4 * (scl + 1.f) + sh; u32x2 w; w.x = pk2(h.x, h.y); w.y = pk2(h.z, h.w); *(u32x2*)(hr + c) = w; }
	v_pk_add_f32 v[26:27], v[52:53], 1.0 op_sel_hi:[1,0]
	v_pk_mul_f32 v[22:23], v[22:23], v[24:25]
	v_pk_add_f32 v[24:25], v[54:55], 1.0 op_sel_hi:[1,0]
	v_pk_fma_f32 v[20:21], v[26:27], v[20:21], v[48:49]
	v_pk_fma_f32 v[22:23], v[24:25], v[22:23], v[50:51]
	v_bfe_u32 v24, v20, 16, 1
	v_add3_u32 v20, v20, v24, s71
	v_bfe_u32 v24, v21, 16, 1
	v_lshrrev_b32_e32 v20, 16, v20
	v_add3_u32 v21, v21, v24, s71
	v_and_or_b32 v24, v21, s70, v20
	v_bfe_u32 v20, v22, 16, 1
	v_add3_u32 v20, v22, v20, s71
	v_bfe_u32 v21, v23, 16, 1
	v_lshrrev_b32_e32 v20, 16, v20
	v_add3_u32 v21, v23, v21, s71
	v_and_or_b32 v25, v21, s70, v20
	v_add_co_u32_e32 v20, vcc, s1, v112
	v_pk_mul_f32 v[36:37], v[36:37], v[2:3] op_sel_hi:[1,0]
	s_nop 0
	v_addc_co_u32_e32 v21, vcc, 0, v113, vcc
	global_store_dwordx2 v[20:21], v[24:25], off
	global_load_dwordx4 v[196:199], v[96:97], off offset:1024
	global_load_dwordx4 v[200:203], v136, s[12:13]
	global_load_dwordx4 v[204:207], v136, s[10:11]
	global_load_dwordx4 v[208:211], v[96:97], off offset:2048
	global_load_dwordx4 v[212:215], v137, s[12:13]
	global_load_dwordx4 v[216:219], v137, s[10:11]
	global_load_dwordx4 v[220:223], v[96:97], off offset:3072
	global_load_dwordx4 v[224:227], v138, s[12:13]
	global_load_dwordx4 v[228:231], v138, s[10:11]
	global_load_dwordx4 v[232:235], v[98:99], off
	global_load_dwordx4 v[236:239], v129, s[12:13]
	global_load_dwordx4 v[240:243], v129, s[10:11]
	s_nop 0
	v_pk_mul_f32 v[34:35], v[38:39], v[2:3] op_sel_hi:[1,0]
	v_pk_mul_f32 v[18:19], v[18:19], v[2:3] op_sel_hi:[1,0]
	v_pk_mul_f32 v[16:17], v[16:17], v[2:3] op_sel_hi:[1,0]
	v_pk_mul_f32 v[14:15], v[14:15], v[2:3] op_sel_hi:[1,0]
	v_pk_mul_f32 v[12:13], v[12:13], v[2:3] op_sel_hi:[1,0]
	v_pk_mul_f32 v[10:11], v[10:11], v[2:3] op_sel_hi:[1,0]
	v_pk_mul_f32 v[8:9], v[8:9], v[2:3] op_sel_hi:[1,0]
	v_pk_mul_f32 v[6:7], v[6:7], v[2:3] op_sel_hi:[1,0]
	v_pk_mul_f32 v[4:5], v[4:5], v[2:3] op_sel_hi:[1,0]
	v_readlane_b32 s1, v255, 22
	s_cmp_ge_i32 s0, s1
	s_waitcnt vmcnt(11)
	v_pk_mul_f32 v[22:23], v[196:197], v[36:37]
	s_waitcnt vmcnt(10)
	v_pk_add_f32 v[26:27], v[200:201], 1.0 op_sel_hi:[1,0]
	v_pk_mul_f32 v[24:25], v[198:199], v[34:35]
	s_waitcnt vmcnt(9)
	v_pk_fma_f32 v[22:23], v[26:27], v[22:23], v[204:205]
	v_pk_add_f32 v[28:29], v[202:203], 1.0 op_sel_hi:[1,0]
	v_bfe_u32 v26, v22, 16, 1
	v_add3_u32 v22, v22, v26, s71
	v_bfe_u32 v26, v23, 16, 1
	v_pk_fma_f32 v[24:25], v[28:29], v[24:25], v[206:207]
	v_lshrrev_b32_e32 v22, 16, v22
	v_add3_u32 v23, v23, v26, s71
	v_and_or_b32 v22, v23, s70, v22
	v_bfe_u32 v23, v24, 16, 1
	v_add3_u32 v23, v24, v23, s71
	v_bfe_u32 v24, v25, 16, 1
	v_lshrrev_b32_e32 v23, 16, v23
	v_add3_u32 v24, v25, v24, s71
	v_and_or_b32 v23, v24, s70, v23
	global_store_dwordx2 v[20:21], v[22:23], off offset:512
	global_load_dwordx4 v[196:199], v[100:101], off
	global_load_dwordx4 v[200:203], v130, s[12:13]
	global_load_dwordx4 v[204:207], v130, s[10:11]
	s_nop 0
	v_pk_mul_f32 v[36:37], v[40:41], v[2:3] op_sel_hi:[1,0]
	v_pk_mul_f32 v[34:35], v[42:43], v[2:3] op_sel_hi:[1,0]
	s_waitcnt vmcnt(12)
	v_pk_mul_f32 v[22:23], v[208:209], v[36:37]
	s_waitcnt vmcnt(11)
	v_pk_add_f32 v[26:27], v[212:213], 1.0 op_sel_hi:[1,0]
	v_pk_mul_f32 v[24:25], v[210:211], v[34:35]
	s_waitcnt vmcnt(10)
	v_pk_fma_f32 v[22:23], v[26:27], v[22:23], v[216:217]
	v_pk_add_f32 v[28:29], v[214:215], 1.0 op_sel_hi:[1,0]
	v_bfe_u32 v26, v22, 16, 1
	v_add3_u32 v22, v22, v26, s71
	v_bfe_u32 v26, v23, 16, 1
	v_pk_fma_f32 v[24:25], v[28:29], v[24:25], v[218:219]
	v_lshrrev_b32_e32 v22, 16, v22
	v_add3_u32 v23, v23, v26, s71
	v_and_or_b32 v22, v23, s70, v22
	v_bfe_u32 v23, v24, 16, 1
	v_add3_u32 v23, v24, v23, s71
	v_bfe_u32 v24, v25, 16, 1
	v_lshrrev_b32_e32 v23, 16, v23
	v_add3_u32 v24, v25, v24, s71
	v_and_or_b32 v23, v24, s70, v23
	global_store_dwordx2 v[20:21], v[22:23], off offset:1024
	global_load_dwordx4 v[208:211], v[102:103], off
	global_load_dwordx4 v[212:215], v131, s[12:13]
	global_load_dwordx4 v[216:219], v131, s[10:11]
	s_nop 0
	v_pk_mul_f32 v[34:35], v[46:47], v[2:3] op_sel_hi:[1,0]
	v_pk_mul_f32 v[36:37], v[44:45], v[2:3] op_sel_hi:[1,0]
	s_waitcnt vmcnt(13)
; __device__ __forceinline__ unsigned pk2(float lo, float hi) { return f2bf(lo) | (f2bf(hi) << 16); }
; __device__ __forceinline__ void rowwise_phase(const Params& P, int mrows, bool first, int l_post, int j_post, int gate_idx, float coef, bool final_, int l_pre, int j_pre, int shift_idx, int scale_idx) {
;     ...
;     for (int row = gw; row < mrows; row += NGW) {
;     ...
; #pragma unroll
;             for (int j = 0; j < 8; ++j) { const int c = 4 * lane + 256 * j; const f32x4 g4 = *(const f32x4*)(gp + c), sh = *(const f32x4*)(mb + shift_idx * DM + c), scl = *(const f32x4*)(mb + scale_idx * DM + c);
;                 const f32x4 h = (xv[j] * rs) * g4 * (scl + 1.f) + sh; u32x2 w; w.x = pk2(h.x, h.y); w.y = pk2(h.z, h.w); *(u32x2*)(hr + c) = w; }
	v_pk_mul_f32 v[24:25], v[34:35], v[222:223]
	v_pk_mul_f32 v[22:23], v[36:37], v[220:221]
	s_waitcnt vmcnt(12)
	v_pk_add_f32 v[28:29], v[226:227], 1.0 op_sel_hi:[1,0]
	v_pk_add_f32 v[26:27], v[224:225], 1.0 op_sel_hi:[1,0]
	s_waitcnt vmcnt(11)
	v_pk_fma_f32 v[24:25], v[24:25], v[28:29], v[230:231]
	v_pk_fma_f32 v[22:23], v[22:23], v[26:27], v[228:229]
	v_bfe_u32 v28, v24, 16, 1
	v_bfe_u32 v26, v22, 16, 1
	v_bfe_u32 v27, v23, 16, 1
	v_bfe_u32 v29, v25, 16, 1
	v_add3_u32 v22, v22, v26, s71
	v_add3_u32 v24, v24, v28, s71
	v_add3_u32 v23, v23, v27, s71
	v_add3_u32 v25, v25, v29, s71
	v_lshrrev_b32_e32 v22, 16, v22
	v_lshrrev_b32_e32 v24, 16, v24
	v_and_or_b32 v22, v23, s70, v22
	v_and_or_b32 v23, v25, s70, v24
	global_store_dwordx2 v[20:21], v[22:23], off offset:1536
	global_load_dwordx4 v[220:223], v[104:105], off
	global_load_dwordx4 v[224:227], v135, s[12:13]
	global_load_dwordx4 v[228:231], v135, s[10:11]
	s_nop 0
	s_waitcnt vmcnt(14)
	v_pk_mul_f32 v[16:17], v[16:17], v[232:233]
	v_pk_mul_f32 v[18:19], v[18:19], v[234:235]
	s_waitcnt vmcnt(13)
	v_pk_add_f32 v[22:23], v[238:239], 1.0 op_sel_hi:[1,0]
	v_pk_add_f32 v[24:25], v[236:237], 1.0 op_sel_hi:[1,0]
	s_waitcnt vmcnt(12)
	v_pk_fma_f32 v[18:19], v[18:19], v[22:23], v[242:243]
	v_pk_fma_f32 v[16:17], v[16:17], v[24:25], v[240:241]
	v_bfe_u32 v24, v18, 16, 1
	v_bfe_u32 v22, v16, 16, 1
	v_bfe_u32 v23, v17, 16, 1
	v_bfe_u32 v25, v19, 16, 1
	v_add3_u32 v16, v16, v22, s71
	v_add3_u32 v18, v18, v24, s71
	v_add3_u32 v17, v17, v23, s71
	v_add3_u32 v19, v19, v25, s71
	v_lshrrev_b32_e32 v16, 16, v16
	v_lshrrev_b32_e32 v18, 16, v18
	v_and_or_b32 v16, v17, s70, v16
	v_and_or_b32 v17, v19, s70, v18
	global_store_dwordx2 v[20:21], v[16:17], off offset:2048
	s_nop 0
	s_waitcnt vmcnt(11)
	v_pk_mul_f32 v[12:13], v[12:13], v[196:197]
	v_pk_mul_f32 v[14:15], v[14:15], v[198:199]
	s_waitcnt vmcnt(10)
	v_pk_add_f32 v[16:17], v[202:203], 1.0 op_sel_hi:[1,0]
	v_pk_add_f32 v[18:19], v[200:201], 1.0 op_sel_hi:[1,0]
	s_waitcnt vmcnt(9)
	v_pk_fma_f32 v[14:15], v[14:15], v[16:17], v[206:207]
	v_pk_fma_f32 v[12:13], v[12:13], v[18:19], v[204:205]
	v_bfe_u32 v18, v14, 16, 1
	v_bfe_u32 v16, v12, 16, 1
	v_bfe_u32 v17, v13, 16, 1
	v_bfe_u32 v19, v15, 16, 1
	v_add3_u32 v12, v12, v16, s71
	v_add3_u32 v14, v14, v18, s71
	v_add3_u32 v13, v13, v17, s71
	v_add3_u32 v15, v15, v19, s71
	v_lshrrev_b32_e32 v12, 16, v12
	v_lshrrev_b32_e32 v14, 16, v14
	v_and_or_b32 v12, v13, s70, v12
	v_and_or_b32 v13, v15, s70, v14
	global_store_dwordx2 v[20:21], v[12:13], off offset:2560
	s_nop 0
	s_waitcnt vmcnt(8)
	v_pk_mul_f32 v[8:9], v[8:9], v[208:209]
	v_pk_mul_f32 v[10:11], v[10:11], v[210:211]
	s_waitcnt vmcnt(7)
	v_pk_add_f32 v[12:13], v[214:215], 1.0 op_sel_hi:[1,0]
	v_pk_add_f32 v[14:15], v[212:213], 1.0 op_sel_hi:[1,0]
	s_waitcnt vmcnt(6)
	v_pk_fma_f32 v[10:11], v[10:11], v[12:13], v[218:219]
	v_pk_fma_f32 v[8:9], v[8:9], v[14:15], v[216:217]
	v_bfe_u32 v14, v10, 16, 1
	v_bfe_u32 v12, v8, 16, 1
	v_bfe_u32 v13, v9, 16, 1
	v_bfe_u32 v15, v11, 16, 1
	v_add3_u32 v8, v8, v12, s71
	v_add3_u32 v10, v10, v14, s71
	v_add3_u32 v9, v9, v13, s71
	v_add3_u32 v11, v11, v15, s71
	v_lshrrev_b32_e32 v8, 16, v8
	v_lshrrev_b32_e32 v10, 16, v10
	v_and_or_b32 v8, v9, s70, v8
	v_and_or_b32 v9, v11, s70, v10
	global_store_dwordx2 v[20:21], v[8:9], off offset:3072
	s_nop 0
	s_waitcnt vmcnt(5)
	v_pk_mul_f32 v[4:5], v[4:5], v[220:221]
	v_pk_mul_f32 v[6:7], v[6:7], v[222:223]
	s_waitcnt vmcnt(4)
	v_pk_add_f32 v[8:9], v[226:227], 1.0 op_sel_hi:[1,0]
	v_pk_add_f32 v[10:11], v[224:225], 1.0 op_sel_hi:[1,0]
	s_waitcnt vmcnt(3)
	v_pk_fma_f32 v[6:7], v[6:7], v[8:9], v[230:231]
	v_pk_fma_f32 v[4:5], v[4:5], v[10:11], v[228:229]
	v_bfe_u32 v9, v6, 16, 1
	v_bfe_u32 v2, v4, 16, 1
	v_bfe_u32 v8, v5, 16, 1
	v_bfe_u32 v10, v7, 16, 1
	v_add3_u32 v2, v4, v2, s71
	v_add3_u32 v4, v5, v8, s71
	v_add3_u32 v5, v6, v9, s71
	v_add3_u32 v6, v7, v10, s71
	v_lshrrev_b32_e32 v2, 16, v2
	v_lshrrev_b32_e32 v5, 16, v5
	v_and_or_b32 v4, v4, s70, v2
	v_and_or_b32 v5, v6, s70, v5
	global_store_dwordx2 v[20:21], v[4:5], off offset:3584
	s_cbranch_scc1 .LBB0_43

; __device__ __forceinline__ float dot4(f32x4 a) { return (a.x * a.x + a.y * a.y) + (a.z * a.z + a.w * a.w); }
; __device__ __forceinline__ void rowwise_phase(const Params& P, int mrows, bool first, int l_post, int j_post, int gate_idx, float coef, bool final_, int l_pre, int j_pre, int shift_idx, int scale_idx) {
;     ...
;         const int b = row < MLAT ? (row >> 11) : 4;
;     ...
;             const float* gp = P.norm_post + (size_t)(l_post * 3 + j_post) * DM; const float* mg = MOD + (size_t)(l_post * 5 + b) * NMODV + gate_idx * DM;
;             float sxx = 0.f, sxt = 0.f, stt = 0.f;
; #pragma unroll
;             for (int j = 0; j < 8; ++j) { const int c = 4 * lane + 256 * j; xv[j] = *(const f32x4*)(xr + c); const f32x4 g4 = *(const f32x4*)(gp + c), m4 = *(const f32x4*)(mg + c);
;                 ss += dot4(yv[j]); yv[j] = yv[j] * g4 * m4; sxx += dot4(xv[j]); stt += dot4(yv[j]);
;                 const f32x4 xt = xv[j] * yv[j]; sxt += (xt.x + xt.y) + (xt.z + xt.w); }
.LBB0_284:
	s_lshl_b64 s[18:19], s[18:19], 13
	s_add_u32 s18, s20, s18
	s_addc_u32 s19, s21, s19
	s_min_i32 s20, s6, 0x2000
	v_readlane_b32 s24, v255, 14
	s_ashr_i32 s20, s20, 11
	v_readlane_b32 s25, v255, 15
	s_mul_i32 s21, s24, 5
	global_load_dwordx4 v[82:85], v[56:57], off
	global_load_dwordx4 v[86:89], v[56:57], off offset:1024
	global_load_dwordx4 v[90:93], v[56:57], off offset:2048
	s_add_i32 s25, s20, s21
	global_load_dwordx4 v[44:47], v106, s[18:19]
	global_load_dwordx4 v[40:43], v106, s[18:19] offset:1024
	global_load_dwordx4 v[36:39], v106, s[18:19] offset:2048
	s_mul_hi_i32 s24, s25, 0x12000
	s_mul_i32 s25, s25, 0x12000
	s_add_u32 s20, s28, s25
	s_addc_u32 s21, s29, s24
	global_load_dwordx4 v[94:97], v106, s[20:21]
	global_load_dwordx4 v[114:117], v106, s[20:21] offset:1024
	global_load_dwordx4 v[118:121], v106, s[20:21] offset:2048
	s_waitcnt vmcnt(9)
	v_pk_mul_f32 v[48:49], v[30:31], v[30:31]
	v_pk_mul_f32 v[50:51], v[28:29], v[28:29]
	global_load_dwordx4 v[122:125], v[56:57], off offset:3072
	global_load_dwordx4 v[126:129], v[58:59], off
	v_pk_mov_b32 v[52:53], v[50:51], v[48:49] op_sel:[1,0]
	v_mov_b32_e32 v51, v49
	v_pk_add_f32 v[48:49], v[52:53], v[50:51]
	v_mov_b32_e32 v99, v4
	v_pk_add_f32 v[144:145], v[48:49], v[48:49] op_sel_hi:[0,1]
	global_load_dwordx4 v[48:51], v106, s[18:19] offset:3072
	global_load_dwordx4 v[136:139], v106, s[20:21] offset:3072
	global_load_dwordx4 v[52:55], v107, s[18:19]
	global_load_dwordx4 v[140:143], v107, s[20:21]
	v_mov_b32_e32 v131, v6
	v_mov_b32_e32 v98, v20
	v_mov_b32_e32 v130, v22
	v_mul_f32_e32 v144, v10, v10
	s_mov_b32 s3, 0x800000
	v_lshl_add_u64 v[80:81], v[80:81], 0, s[16:17]
	s_waitcnt vmcnt(14)
	v_pk_mul_f32 v[84:85], v[6:7], v[84:85]
	v_pk_mul_f32 v[82:83], v[4:5], v[82:83]
	v_mov_b32_e32 v4, v21
	v_mov_b32_e32 v6, v23
	v_pk_mul_f32 v[4:5], v[4:5], v[4:5]
	v_pk_mul_f32 v[6:7], v[6:7], v[6:7]
	v_pk_fma_f32 v[4:5], v[98:99], v[98:99], v[4:5]
	v_pk_fma_f32 v[6:7], v[130:131], v[130:131], v[6:7]
	s_waitcnt vmcnt(13)
	v_pk_mul_f32 v[88:89], v[22:23], v[88:89]
	v_pk_mul_f32 v[86:87], v[20:21], v[86:87]
	s_waitcnt vmcnt(12)
	v_pk_mul_f32 v[30:31], v[30:31], v[92:93]
	v_pk_add_f32 v[4:5], v[4:5], v[6:7]
	s_waitcnt vmcnt(11)
	v_mov_b32_e32 v20, v45
	s_waitcnt vmcnt(10)
	v_mov_b32_e32 v21, v41
	v_mov_b32_e32 v22, v46
	v_mov_b32_e32 v23, v42
	s_waitcnt vmcnt(9)
	v_pk_mul_f32 v[92:93], v[38:39], v[38:39]
	v_pk_mul_f32 v[98:99], v[36:37], v[36:37]
	v_pk_mul_f32 v[28:29], v[28:29], v[90:91]
	v_mov_b32_e32 v6, v44
	v_mov_b32_e32 v7, v40
	v_mov_b32_e32 v90, v47
	v_mov_b32_e32 v91, v43
	v_pk_add_f32 v[130:131], v[4:5], v[4:5] op_sel_hi:[0,1]
	v_pk_mul_f32 v[4:5], v[20:21], v[20:21]
	v_pk_mul_f32 v[20:21], v[22:23], v[22:23]
	v_pk_mov_b32 v[22:23], v[98:99], v[92:93] op_sel:[1,0]
	v_mov_b32_e32 v99, v93
	v_pk_fma_f32 v[4:5], v[6:7], v[6:7], v[4:5]
	v_pk_fma_f32 v[6:7], v[90:91], v[90:91], v[20:21]
	v_pk_add_f32 v[146:147], v[98:99], v[22:23]
	s_waitcnt vmcnt(8)
	v_pk_mul_f32 v[20:21], v[96:97], v[84:85]
	v_pk_mul_f32 v[22:23], v[94:95], v[82:83]
	s_waitcnt vmcnt(7)
	v_pk_mul_f32 v[82:83], v[116:117], v[88:89]
	v_pk_mul_f32 v[84:85], v[114:115], v[86:87]
	s_waitcnt vmcnt(6)
	v_pk_mul_f32 v[86:87], v[120:121], v[30:31]
	v_pk_mul_f32 v[88:89], v[118:119], v[28:29]
	v_mul_f32_e32 v2, v21, v21
	v_pk_mul_f32 v[28:29], v[46:47], v[20:21]
	v_pk_mul_f32 v[30:31], v[44:45], v[22:23]
	v_pk_mul_f32 v[98:99], v[42:43], v[82:83]
	v_pk_mul_f32 v[114:115], v[40:41], v[84:85]
	v_pk_add_f32 v[148:149], v[4:5], v[6:7]
	v_mul_f32_e32 v4, v22, v22
	v_mul_f32_e32 v6, v23, v23
	v_mul_f32_e32 v90, v84, v84
	v_mul_f32_e32 v92, v85, v85
	v_mul_f32_e32 v94, v82, v82
	v_mul_f32_e32 v96, v83, v83
	v_pk_fma_f32 v[152:153], v[20:21], v[20:21], v[2:3] op_sel_hi:[1,1,0]
	v_add_f32_e32 v5, v30, v31
	v_add_f32_e32 v7, v28, v29
	v_pk_mul_f32 v[28:29], v[38:39], v[86:87]
	v_pk_mul_f32 v[30:31], v[36:37], v[88:89]
	v_mov_b32_e32 v91, v114
	v_mov_b32_e32 v93, v115
	v_mov_b32_e32 v95, v98
	v_mov_b32_e32 v97, v99
	v_mul_f32_e32 v116, v88, v88
	v_mul_f32_e32 v118, v89, v89
	v_mul_f32_e32 v120, v86, v86
	v_mul_f32_e32 v150, v87, v87
	v_pk_add_f32 v[4:5], v[4:5], v[6:7]
	v_mov_b32_e32 v153, v3
	v_pk_add_f32 v[6:7], v[90:91], v[92:93]
	v_pk_add_f32 v[90:91], v[94:95], v[96:97]
	v_mov_b32_e32 v117, v30
	v_mov_b32_e32 v119, v31
	v_mov_b32_e32 v121, v28
	v_mov_b32_e32 v151, v29
	v_pk_add_f32 v[4:5], v[4:5], v[152:153]
	v_pk_add_f32 v[6:7], v[6:7], v[90:91]
	v_pk_add_f32 v[30:31], v[116:117], v[118:119]
	v_pk_add_f32 v[28:29], v[120:121], v[150:151]
	v_pk_add_f32 v[90:91], v[4:5], v[6:7]
	v_pk_add_f32 v[28:29], v[30:31], v[28:29]
	v_mul_f32_e32 v2, v12, v12
	v_pk_add_f32 v[98:99], v[90:91], v[28:29]
	v_pk_fma_f32 v[28:29], v[12:13], v[12:13], v[2:3] op_sel_hi:[1,1,0]
	v_mul_f32_e32 v2, v14, v14
	v_pk_fma_f32 v[30:31], v[14:15], v[14:15], v[2:3] op_sel_hi:[1,1,0]
	s_waitcnt vmcnt(5)
	v_pk_mul_f32 v[14:15], v[14:15], v[124:125]
	v_pk_mul_f32 v[12:13], v[12:13], v[122:123]
	global_load_dwordx4 v[94:97], v[60:61], off
	global_load_dwordx4 v[4:7], v108, s[18:19]
	global_load_dwordx4 v[114:117], v108, s[20:21]
	s_waitcnt vmcnt(5)
; __device__ __forceinline__ float dot4(f32x4 a) { return (a.x * a.x + a.y * a.y) + (a.z * a.z + a.w * a.w); }
; __device__ __forceinline__ void rowwise_phase(const Params& P, int mrows, bool first, int l_post, int j_post, int gate_idx, float coef, bool final_, int l_pre, int j_pre, int shift_idx, int scale_idx) {
;     ...
;             for (int j = 0; j < 8; ++j) { const int c = 4 * lane + 256 * j; xv[j] = *(const f32x4*)(xr + c); const f32x4 g4 = *(const f32x4*)(gp + c), m4 = *(const f32x4*)(mg + c);
;                 ss += dot4(yv[j]); yv[j] = yv[j] * g4 * m4; sxx += dot4(xv[j]); stt += dot4(yv[j]);
;                 const f32x4 xt = xv[j] * yv[j]; sxt += (xt.x + xt.y) + (xt.z + xt.w); }
; #pragma unroll
;             for (int o = 1; o < 64; o <<= 1) { ss += __shfl_xor(ss, o); sxx += __shfl_xor(sxx, o); sxt += __shfl_xor(sxt, o); stt += __shfl_xor(stt, o); }
;             const float rs = rsqrtf(ss * (1.f / DM) + EPS) * coef;
	v_pk_mul_f32 v[90:91], v[138:139], v[14:15]
	v_pk_mul_f32 v[92:93], v[136:137], v[12:13]
	global_load_dwordx4 v[118:121], v[62:63], off
	global_load_dwordx4 v[12:15], v109, s[18:19]
	global_load_dwordx4 v[122:125], v109, s[20:21]
	v_pk_mul_f32 v[154:155], v[50:51], v[90:91]
	v_pk_mul_f32 v[156:157], v[48:49], v[92:93]
	v_mul_f32_e32 v136, v92, v92
	v_mul_f32_e32 v138, v93, v93
	v_mul_f32_e32 v150, v90, v90
	v_mul_f32_e32 v152, v91, v91
	v_mov_b32_e32 v137, v156
	v_mov_b32_e32 v139, v157
	v_mov_b32_e32 v151, v154
	v_mov_b32_e32 v153, v155
	v_mul_f32_e32 v28, v8, v8
	v_mul_f32_e32 v30, v9, v9
	v_mul_f32_e32 v130, v11, v11
	v_pk_add_f32 v[136:137], v[136:137], v[138:139]
	v_pk_add_f32 v[138:139], v[150:151], v[152:153]
	v_pk_add_f32 v[28:29], v[28:29], v[30:31]
	v_pk_add_f32 v[30:31], v[144:145], v[130:131]
	v_pk_add_f32 v[150:151], v[136:137], v[138:139]
	v_pk_add_f32 v[28:29], v[28:29], v[30:31]
	global_load_dwordx4 v[136:139], v[64:65], off
	v_pk_add_f32 v[130:131], v[28:29], v[28:29] op_sel_hi:[0,1]
	v_pk_mul_f32 v[10:11], v[10:11], v[128:129]
	v_pk_mul_f32 v[144:145], v[8:9], v[126:127]
	global_load_dwordx4 v[28:31], v110, s[18:19]
	global_load_dwordx4 v[126:129], v110, s[20:21]
	s_waitcnt vmcnt(9)
	v_pk_mul_f32 v[8:9], v[142:143], v[10:11]
	v_pk_mul_f32 v[10:11], v[140:141], v[144:145]
	v_mul_f32_e32 v2, v52, v52
	v_mul_f32_e32 v130, v53, v53
	v_pk_add_f32 v[140:141], v[148:149], v[148:149] op_sel:[0,1] op_sel_hi:[1,0]
	v_pk_add_f32 v[142:143], v[146:147], v[146:147] op_sel:[0,1] op_sel_hi:[1,0]
	v_mov_b32_e32 v141, v2
	v_mov_b32_e32 v143, v130
	v_mul_f32_e32 v2, v49, v49
	v_pk_add_f32 v[140:141], v[140:141], v[142:143]
	v_pk_fma_f32 v[142:143], v[48:49], v[48:49], v[2:3] op_sel_hi:[1,1,0]
	v_mul_f32_e32 v2, v51, v51
	v_mul_f32_e32 v132, v54, v54
	v_mul_f32_e32 v135, v55, v55
	v_pk_fma_f32 v[144:145], v[50:51], v[50:51], v[2:3] op_sel_hi:[1,1,0]
	v_mov_b32_e32 v143, v135
	v_mov_b32_e32 v145, v132
	v_pk_add_f32 v[142:143], v[142:143], v[144:145]
	v_pk_mul_f32 v[152:153], v[54:55], v[8:9]
	v_pk_mul_f32 v[154:155], v[52:53], v[10:11]
	v_pk_add_f32 v[140:141], v[140:141], v[142:143]
	v_mul_f32_e32 v142, v10, v10
	v_mul_f32_e32 v144, v11, v11
	v_mul_f32_e32 v146, v8, v8
	v_mul_f32_e32 v148, v9, v9
	v_mov_b32_e32 v143, v154
	v_mov_b32_e32 v145, v155
	v_mov_b32_e32 v147, v152
	v_mov_b32_e32 v149, v153
	v_pk_add_f32 v[142:143], v[142:143], v[144:145]
	v_pk_add_f32 v[144:145], v[146:147], v[148:149]
	v_pk_mul_f32 v[146:147], v[18:19], v[18:19]
	v_pk_mul_f32 v[148:149], v[16:17], v[16:17]
	v_mul_f32_e32 v2, v24, v24
	v_pk_mov_b32 v[152:153], v[148:149], v[146:147] op_sel:[1,0]
	v_mov_b32_e32 v149, v147
	v_pk_add_f32 v[146:147], v[152:153], v[148:149]
	v_pk_fma_f32 v[160:161], v[24:25], v[24:25], v[2:3] op_sel_hi:[1,1,0]
	v_mul_f32_e32 v2, v26, v26
	v_pk_add_f32 v[146:147], v[146:147], v[146:147] op_sel_hi:[0,1]
	v_pk_fma_f32 v[162:163], v[26:27], v[26:27], v[2:3] op_sel_hi:[1,1,0]
	v_mul_f32_e32 v160, v32, v32
	v_mul_f32_e32 v162, v33, v33
	v_mul_f32_e32 v146, v34, v34
	v_mul_f32_e32 v130, v35, v35
	s_lshl_b64 s[18:19], s[22:23], 13
	s_add_u32 s20, s26, s25
	s_addc_u32 s21, s27, s24
	s_waitcnt vmcnt(8)
	v_pk_mul_f32 v[18:19], v[18:19], v[96:97]
	v_pk_mul_f32 v[16:17], v[16:17], v[94:95]
	s_waitcnt vmcnt(7)
	v_pk_mul_f32 v[94:95], v[6:7], v[6:7]
	s_waitcnt vmcnt(5)
	v_pk_mul_f32 v[26:27], v[26:27], v[120:121]
	v_pk_mul_f32 v[24:25], v[24:25], v[118:119]
	s_waitcnt vmcnt(3)
	v_pk_mul_f32 v[118:119], v[124:125], v[26:27]
	v_pk_mul_f32 v[120:121], v[122:123], v[24:25]
	v_pk_add_f32 v[122:123], v[160:161], v[162:163]
	v_pk_add_f32 v[124:125], v[146:147], v[130:131]
	v_pk_mul_f32 v[96:97], v[4:5], v[4:5]
	v_pk_add_f32 v[122:123], v[122:123], v[124:125]
	v_pk_mul_f32 v[16:17], v[114:115], v[16:17]
	v_add_f32_e32 v2, v122, v123
	v_pk_mov_b32 v[114:115], v[96:97], v[94:95] op_sel:[1,0]
	v_mov_b32_e32 v97, v95
	v_pk_add_f32 v[114:115], v[96:97], v[114:115]
	v_pk_mul_f32 v[124:125], v[12:13], v[120:121]
	s_waitcnt lgkmcnt(0)
	v_add_f32_dpp v2, v2, v2 quad_perm:[1,0,3,2] row_mask:0xf bank_mask:0xf
	v_pk_mul_f32 v[18:19], v[116:117], v[18:19]
	v_mul_f32_e32 v116, v16, v16
	v_mul_f32_e32 v148, v17, v17
	v_mul_f32_e32 v152, v18, v18
	s_waitcnt lgkmcnt(0)
	v_add_f32_dpp v2, v2, v2 quad_perm:[2,3,0,1] row_mask:0xf bank_mask:0xf
	s_waitcnt vmcnt(2)
	v_pk_mul_f32 v[32:33], v[32:33], v[136:137]
	v_pk_mul_f32 v[34:35], v[34:35], v[138:139]
	s_waitcnt vmcnt(1)
	v_mul_f32_e32 v27, v28, v28
	s_waitcnt vmcnt(0)
	v_pk_mul_f32 v[126:127], v[126:127], v[32:33]
	v_pk_add_f32 v[32:33], v[140:141], v[140:141] op_sel:[0,1] op_sel_hi:[1,0]
	s_waitcnt lgkmcnt(0)
	v_add_f32_dpp v25, v2, v2 row_half_mirror row_mask:0xf bank_mask:0xf
	v_mov_b32_e32 v33, v27
	v_mul_f32_e32 v2, v13, v13
	v_pk_fma_f32 v[130:131], v[12:13], v[12:13], v[2:3] op_sel_hi:[1,1,0]
	v_mul_f32_e32 v2, v15, v15
	v_pk_fma_f32 v[136:137], v[14:15], v[14:15], v[2:3] op_sel_hi:[1,1,0]
	s_waitcnt lgkmcnt(0)
	v_add_f32_dpp v25, v25, v25 row_mirror row_mask:0xf bank_mask:0xf
	ds_bpermute_b32 v27, v104, v25
	v_pk_mul_f32 v[128:129], v[128:129], v[34:35]
	v_mul_f32_e32 v95, v29, v29
	v_pk_add_f32 v[34:35], v[114:115], v[114:115] op_sel:[0,1] op_sel_hi:[1,0]
	v_mul_f32_e32 v154, v19, v19
	s_waitcnt lgkmcnt(0)
	v_add_f32_e32 v2, v25, v27
	ds_bpermute_b32 v25, v105, v2
	v_mov_b32_e32 v35, v95
	v_pk_add_f32 v[114:115], v[32:33], v[34:35]
	v_pk_add_f32 v[32:33], v[98:99], v[150:151]
	v_pk_add_f32 v[34:35], v[142:143], v[144:145]
	s_waitcnt lgkmcnt(0)
; __device__ __forceinline__ float dot4(f32x4 a) { return (a.x * a.x + a.y * a.y) + (a.z * a.z + a.w * a.w); }
; __device__ __forceinline__ void rowwise_phase(const Params& P, int mrows, bool first, int l_post, int j_post, int gate_idx, float coef, bool final_, int l_pre, int j_pre, int shift_idx, int scale_idx) {
;     ...
; #pragma unroll
;             for (int o = 1; o < 64; o <<= 1) { ss += __shfl_xor(ss, o); sxx += __shfl_xor(sxx, o); sxt += __shfl_xor(sxt, o); stt += __shfl_xor(stt, o); }
;             const float rs = rsqrtf(ss * (1.f / DM) + EPS) * coef;
;             ss_new = sxx + 2.f * rs * sxt + rs * rs * stt;
; #pragma unroll
;             for (int j = 0; j < 8; ++j) xv[j] += yv[j] * rs;
;     ...
;             for (int j = 0; j < 8; ++j) { if (!first) *(f32x4*)(xr + 4 * lane + 256 * j) = xv[j]; else ss += dot4(xv[j]); }
;             if (first) ss = wave_sum(ss); else ss = ss_new;
;             const float rs = rsqrtf(ss * (1.f / DM) + EPS);
	v_add_f32_e32 v2, v2, v25
	v_fmamk_f32 v2, v2, 0x3a000000, v169
	v_mul_f32_e32 v25, 0x4b800000, v2
	v_cmp_gt_f32_e32 vcc, s3, v2
	v_pk_add_f32 v[98:99], v[32:33], v[34:35]
	v_pk_mul_f32 v[156:157], v[6:7], v[18:19]
	v_cndmask_b32_e32 v2, v2, v25, vcc
	v_rsq_f32_e32 v2, v2
	v_pk_mul_f32 v[158:159], v[4:5], v[16:17]
	v_pk_mul_f32 v[122:123], v[14:15], v[118:119]
	v_mul_f32_e32 v97, v30, v30
	v_mul_f32_e32 v25, 0x45800000, v2
	v_cndmask_b32_e32 v2, v2, v25, vcc
	v_mul_f32_e32 v132, 0.5, v2
	v_pk_fma_f32 v[34:35], v[20:21], v[132:133], v[46:47] op_sel_hi:[1,0,1]
	v_pk_fma_f32 v[32:33], v[22:23], v[132:133], v[44:45] op_sel_hi:[1,0,1]
	v_pk_fma_f32 v[22:23], v[8:9], v[132:133], v[54:55] op_sel_hi:[1,0,1]
	v_pk_fma_f32 v[8:9], v[120:121], v[132:133], v[12:13] op_sel_hi:[1,0,1]
	v_lshl_add_u64 v[12:13], v[0:1], 0, s[18:19]
	s_movk_i32 s18, 0x1000
	v_pk_fma_f32 v[42:43], v[82:83], v[132:133], v[42:43] op_sel_hi:[1,0,1]
	v_pk_fma_f32 v[40:41], v[84:85], v[132:133], v[40:41] op_sel_hi:[1,0,1]
	v_pk_fma_f32 v[38:39], v[86:87], v[132:133], v[38:39] op_sel_hi:[1,0,1]
	v_pk_fma_f32 v[36:37], v[88:89], v[132:133], v[36:37] op_sel_hi:[1,0,1]
	v_pk_fma_f32 v[46:47], v[90:91], v[132:133], v[50:51] op_sel_hi:[1,0,1]
	v_pk_fma_f32 v[44:45], v[92:93], v[132:133], v[48:49] op_sel_hi:[1,0,1]
	global_store_dwordx4 v[12:13], v[32:35], off
	global_store_dwordx4 v[12:13], v[40:43], off offset:1024
	global_store_dwordx4 v[12:13], v[36:39], off offset:2048
	global_store_dwordx4 v[12:13], v[44:47], off offset:3072
	v_add_co_u32_e32 v12, vcc, s18, v12
	s_add_u32 s18, s20, 0x6000
	v_pk_fma_f32 v[20:21], v[10:11], v[132:133], v[52:53] op_sel_hi:[1,0,1]
	v_addc_co_u32_e32 v13, vcc, 0, v13, vcc
	s_addc_u32 s19, s21, 0
	v_pk_fma_f32 v[18:19], v[18:19], v[132:133], v[6:7] op_sel_hi:[1,0,1]
	v_pk_fma_f32 v[16:17], v[16:17], v[132:133], v[4:5] op_sel_hi:[1,0,1]
	v_pk_fma_f32 v[10:11], v[118:119], v[132:133], v[14:15] op_sel_hi:[1,0,1]
	v_pk_fma_f32 v[6:7], v[128:129], v[132:133], v[30:31] op_sel_hi:[1,0,1]
	v_pk_fma_f32 v[4:5], v[126:127], v[132:133], v[28:29] op_sel_hi:[1,0,1]
	global_store_dwordx4 v[12:13], v[20:23], off
	global_store_dwordx4 v[12:13], v[16:19], off offset:1024
	global_store_dwordx4 v[12:13], v[8:11], off offset:2048
	global_store_dwordx4 v[12:13], v[4:7], off offset:3072
	s_add_u32 s20, s20, 0x8000
	v_mul_f32_e32 v117, v31, v31
	v_pk_mul_f32 v[162:163], v[30:31], v[128:129]
	v_pk_mul_f32 v[164:165], v[28:29], v[126:127]
	s_addc_u32 s21, s21, 0
	global_load_dwordx4 v[12:15], v[66:67], off
	global_load_dwordx4 v[28:31], v106, s[18:19]
	global_load_dwordx4 v[48:51], v106, s[20:21]
	v_mov_b32_e32 v131, v117
	v_mov_b32_e32 v117, v158
	v_mov_b32_e32 v149, v159
	v_mov_b32_e32 v153, v156
	v_mov_b32_e32 v155, v157
	v_mul_f32_e32 v94, v120, v120
	v_mul_f32_e32 v96, v121, v121
	v_mul_f32_e32 v24, v118, v118
	v_mul_f32_e32 v26, v119, v119
	v_mov_b32_e32 v137, v97
	v_pk_add_f32 v[116:117], v[116:117], v[148:149]
	v_pk_add_f32 v[142:143], v[152:153], v[154:155]
	v_mov_b32_e32 v95, v124
	v_mov_b32_e32 v97, v125
	v_mov_b32_e32 v25, v122
	v_mov_b32_e32 v27, v123
	v_pk_add_f32 v[52:53], v[116:117], v[142:143]
	v_pk_add_f32 v[54:55], v[94:95], v[96:97]
	v_pk_add_f32 v[24:25], v[24:25], v[26:27]
	v_mul_f32_e32 v138, v126, v126
	v_mul_f32_e32 v140, v127, v127
	v_mul_f32_e32 v146, v128, v128
	v_mul_f32_e32 v160, v129, v129
	v_pk_add_f32 v[52:53], v[98:99], v[52:53]
	v_pk_add_f32 v[24:25], v[54:55], v[24:25]
	v_mov_b32_e32 v139, v164
	v_mov_b32_e32 v141, v165
	v_mov_b32_e32 v147, v162
	v_mov_b32_e32 v161, v163
	v_pk_add_f32 v[24:25], v[52:53], v[24:25]
	v_pk_add_f32 v[26:27], v[138:139], v[140:141]
	v_pk_add_f32 v[52:53], v[146:147], v[160:161]
	s_lshl_b64 s[22:23], s[22:23], 12
	v_pk_add_f32 v[26:27], v[26:27], v[52:53]
	v_pk_add_f32 v[52:53], v[130:131], v[136:137]
	v_pk_add_f32 v[24:25], v[24:25], v[26:27]
	v_pk_add_f32 v[52:53], v[114:115], v[52:53]
	v_add_f32_e32 v2, v52, v53
	s_add_u32 s6, s6, s8
	s_addc_u32 s7, s7, s9
	s_waitcnt lgkmcnt(0)
	v_add_f32_dpp v24, v24, v24 quad_perm:[1,0,3,2] row_mask:0xf bank_mask:0xf
	v_add_f32_dpp v25, v25, v25 quad_perm:[1,0,3,2] row_mask:0xf bank_mask:0xf
	s_waitcnt lgkmcnt(0)
	v_add_f32_dpp v2, v2, v2 quad_perm:[1,0,3,2] row_mask:0xf bank_mask:0xf
	s_cmpk_gt_i32 s6, 0x23ff
	s_waitcnt lgkmcnt(0)
	v_add_f32_dpp v24, v24, v24 quad_perm:[2,3,0,1] row_mask:0xf bank_mask:0xf
	v_add_f32_dpp v25, v25, v25 quad_perm:[2,3,0,1] row_mask:0xf bank_mask:0xf
	s_waitcnt lgkmcnt(0)
	v_add_f32_dpp v2, v2, v2 quad_perm:[2,3,0,1] row_mask:0xf bank_mask:0xf
	s_waitcnt lgkmcnt(0)
	v_add_f32_dpp v24, v24, v24 row_half_mirror row_mask:0xf bank_mask:0xf
	v_add_f32_dpp v25, v25, v25 row_half_mirror row_mask:0xf bank_mask:0xf
	s_waitcnt lgkmcnt(0)
	v_add_f32_dpp v2, v2, v2 row_half_mirror row_mask:0xf bank_mask:0xf
	s_waitcnt lgkmcnt(0)
	v_add_f32_dpp v24, v24, v24 row_mirror row_mask:0xf bank_mask:0xf
	v_add_f32_dpp v25, v25, v25 row_mirror row_mask:0xf bank_mask:0xf
	ds_bpermute_b32 v27, v104, v25
	ds_bpermute_b32 v26, v104, v24
	s_waitcnt lgkmcnt(0)
	v_add_f32_dpp v2, v2, v2 row_mirror row_mask:0xf bank_mask:0xf
	ds_bpermute_b32 v52, v104, v2
	s_waitcnt lgkmcnt(0)
	v_pk_add_f32 v[24:25], v[24:25], v[26:27]
	ds_bpermute_b32 v27, v105, v25
	ds_bpermute_b32 v26, v105, v24
	s_waitcnt lgkmcnt(0)
	v_add_f32_e32 v2, v2, v52
	ds_bpermute_b32 v52, v105, v2
	s_waitcnt lgkmcnt(0)
	v_pk_add_f32 v[24:25], v[24:25], v[26:27]
	v_pk_mul_f32 v[26:27], v[132:133], v[132:133] op_sel_hi:[0,1]
	v_pk_mul_f32 v[24:25], v[24:25], v[26:27]
	s_waitcnt lgkmcnt(0)
; __device__ __forceinline__ unsigned pk2(float lo, float hi) { return f2bf(lo) | (f2bf(hi) << 16); }
; __device__ __forceinline__ void rowwise_phase(const Params& P, int mrows, bool first, int l_post, int j_post, int gate_idx, float coef, bool final_, int l_pre, int j_pre, int shift_idx, int scale_idx) {
;     ...
;             if (first) ss = wave_sum(ss); else ss = ss_new;
;             const float rs = rsqrtf(ss * (1.f / DM) + EPS);
;             const float* gp = P.norm_pre + (size_t)(l_pre * 3 + j_pre) * DM; const float* mb = MOD + (size_t)(l_pre * 5 + b) * NMODV;
;             bf16* hr = H + (size_t)row * DM;
; #pragma unroll
;             for (int j = 0; j < 8; ++j) { const int c = 4 * lane + 256 * j; const f32x4 g4 = *(const f32x4*)(gp + c), sh = *(const f32x4*)(mb + shift_idx * DM + c), scl = *(const f32x4*)(mb + scale_idx * DM + c);
;                 const f32x4 h = (xv[j] * rs) * g4 * (scl + 1.f) + sh; u32x2 w; w.x = pk2(h.x, h.y); w.y = pk2(h.z, h.w); *(u32x2*)(hr + c) = w; }
	v_add_f32_e32 v2, v2, v52
	v_add_f32_e32 v2, v2, v25
	v_add_f32_e32 v2, v24, v2
	v_fmamk_f32 v2, v2, 0x3a000000, v169
	v_mul_f32_e32 v24, 0x4b800000, v2
	v_cmp_gt_f32_e32 vcc, s3, v2
	s_nop 1
	v_cndmask_b32_e32 v2, v2, v24, vcc
	v_rsq_f32_e32 v2, v2
	s_nop 0
	v_mul_f32_e32 v24, 0x45800000, v2
	v_cndmask_b32_e32 v2, v2, v24, vcc
	v_pk_mul_f32 v[26:27], v[32:33], v[2:3] op_sel_hi:[1,0]
	v_pk_mul_f32 v[24:25], v[34:35], v[2:3] op_sel_hi:[1,0]
	s_waitcnt vmcnt(2)
	v_pk_mul_f32 v[12:13], v[12:13], v[26:27]
	s_waitcnt vmcnt(0)
	v_pk_add_f32 v[26:27], v[48:49], 1.0 op_sel_hi:[1,0]
	v_pk_mul_f32 v[14:15], v[14:15], v[24:25]
	v_pk_add_f32 v[24:25], v[50:51], 1.0 op_sel_hi:[1,0]
	v_pk_fma_f32 v[12:13], v[26:27], v[12:13], v[28:29]
	v_pk_fma_f32 v[14:15], v[24:25], v[14:15], v[30:31]
	v_bfe_u32 v24, v12, 16, 1
	v_add3_u32 v12, v12, v24, s71
	v_bfe_u32 v24, v13, 16, 1
	v_lshrrev_b32_e32 v12, 16, v12
	v_add3_u32 v13, v13, v24, s71
	v_and_or_b32 v24, v13, s70, v12
	v_bfe_u32 v12, v14, 16, 1
	v_add3_u32 v12, v14, v12, s71
	v_bfe_u32 v13, v15, 16, 1
	v_lshrrev_b32_e32 v12, 16, v12
	v_add3_u32 v13, v15, v13, s71
	v_and_or_b32 v25, v13, s70, v12
	v_lshl_add_u64 v[12:13], v[78:79], 0, s[22:23]
	global_store_dwordx2 v[12:13], v[24:25], off
	global_load_dwordx4 v[196:199], v[66:67], off offset:1024
	global_load_dwordx4 v[200:203], v111, s[20:21]
	global_load_dwordx4 v[204:207], v111, s[18:19]
	global_load_dwordx4 v[208:211], v[66:67], off offset:2048
	global_load_dwordx4 v[212:215], v112, s[20:21]
	global_load_dwordx4 v[216:219], v112, s[18:19]
	global_load_dwordx4 v[220:223], v[66:67], off offset:3072
	global_load_dwordx4 v[224:227], v113, s[20:21]
	global_load_dwordx4 v[228:231], v113, s[18:19]
	global_load_dwordx4 v[232:235], v[68:69], off
	global_load_dwordx4 v[236:239], v107, s[20:21]
	global_load_dwordx4 v[240:243], v107, s[18:19]
	s_nop 0
	v_pk_mul_f32 v[40:41], v[40:41], v[2:3] op_sel_hi:[1,0]
	v_pk_mul_f32 v[14:15], v[42:43], v[2:3] op_sel_hi:[1,0]
	v_pk_mul_f32 v[36:37], v[36:37], v[2:3] op_sel_hi:[1,0]
	v_pk_mul_f32 v[20:21], v[20:21], v[2:3] op_sel_hi:[1,0]
	v_pk_mul_f32 v[16:17], v[16:17], v[2:3] op_sel_hi:[1,0]
	v_pk_mul_f32 v[10:11], v[10:11], v[2:3] op_sel_hi:[1,0]
	v_pk_mul_f32 v[8:9], v[8:9], v[2:3] op_sel_hi:[1,0]
	v_pk_mul_f32 v[6:7], v[6:7], v[2:3] op_sel_hi:[1,0]
	v_pk_mul_f32 v[4:5], v[4:5], v[2:3] op_sel_hi:[1,0]
	s_waitcnt vmcnt(11)
	v_pk_mul_f32 v[24:25], v[196:197], v[40:41]
	s_waitcnt vmcnt(10)
	v_pk_add_f32 v[28:29], v[200:201], 1.0 op_sel_hi:[1,0]
	v_pk_mul_f32 v[14:15], v[198:199], v[14:15]
	v_pk_add_f32 v[26:27], v[202:203], 1.0 op_sel_hi:[1,0]
	s_waitcnt vmcnt(9)
	v_pk_fma_f32 v[24:25], v[28:29], v[24:25], v[204:205]
	v_pk_fma_f32 v[14:15], v[26:27], v[14:15], v[206:207]
	v_bfe_u32 v26, v24, 16, 1
	v_add3_u32 v24, v24, v26, s71
	v_bfe_u32 v26, v25, 16, 1
	v_lshrrev_b32_e32 v24, 16, v24
	v_add3_u32 v25, v25, v26, s71
	v_and_or_b32 v24, v25, s70, v24
	v_bfe_u32 v25, v14, 16, 1
	v_add3_u32 v14, v14, v25, s71
	v_bfe_u32 v25, v15, 16, 1
	v_lshrrev_b32_e32 v14, 16, v14
	v_add3_u32 v15, v15, v25, s71
	v_and_or_b32 v25, v15, s70, v14
	global_store_dwordx2 v[12:13], v[24:25], off offset:512
	global_load_dwordx4 v[196:199], v[70:71], off
	global_load_dwordx4 v[200:203], v108, s[20:21]
	global_load_dwordx4 v[204:207], v108, s[18:19]
	s_nop 0
	v_pk_mul_f32 v[14:15], v[38:39], v[2:3] op_sel_hi:[1,0]
	s_waitcnt vmcnt(12)
	v_pk_mul_f32 v[24:25], v[208:209], v[36:37]
	s_waitcnt vmcnt(11)
	v_pk_add_f32 v[28:29], v[212:213], 1.0 op_sel_hi:[1,0]
	v_pk_mul_f32 v[14:15], v[210:211], v[14:15]
	v_pk_add_f32 v[26:27], v[214:215], 1.0 op_sel_hi:[1,0]
	s_waitcnt vmcnt(10)
	v_pk_fma_f32 v[24:25], v[28:29], v[24:25], v[216:217]
	v_pk_fma_f32 v[14:15], v[26:27], v[14:15], v[218:219]
	v_bfe_u32 v26, v24, 16, 1
	v_add3_u32 v24, v24, v26, s71
	v_bfe_u32 v26, v25, 16, 1
	v_lshrrev_b32_e32 v24, 16, v24
	v_add3_u32 v25, v25, v26, s71
	v_and_or_b32 v24, v25, s70, v24
	v_bfe_u32 v25, v14, 16, 1
	v_add3_u32 v14, v14, v25, s71
	v_bfe_u32 v25, v15, 16, 1
	v_lshrrev_b32_e32 v14, 16, v14
	v_add3_u32 v15, v15, v25, s71
	v_and_or_b32 v25, v15, s70, v14
	global_store_dwordx2 v[12:13], v[24:25], off offset:1024
	global_load_dwordx4 v[208:211], v[72:73], off
	global_load_dwordx4 v[212:215], v109, s[20:21]
	global_load_dwordx4 v[216:219], v109, s[18:19]
	s_nop 0
	v_pk_mul_f32 v[14:15], v[46:47], v[2:3] op_sel_hi:[1,0]
	v_pk_mul_f32 v[36:37], v[44:45], v[2:3] op_sel_hi:[1,0]
	s_waitcnt vmcnt(13)
; __device__ __forceinline__ unsigned pk2(float lo, float hi) { return f2bf(lo) | (f2bf(hi) << 16); }
; __device__ __forceinline__ void rowwise_phase(const Params& P, int mrows, bool first, int l_post, int j_post, int gate_idx, float coef, bool final_, int l_pre, int j_pre, int shift_idx, int scale_idx) {
;     ...
;     for (int row = gw; row < mrows; row += NGW) {
;     ...
; #pragma unroll
;             for (int j = 0; j < 8; ++j) { const int c = 4 * lane + 256 * j; const f32x4 g4 = *(const f32x4*)(gp + c), sh = *(const f32x4*)(mb + shift_idx * DM + c), scl = *(const f32x4*)(mb + scale_idx * DM + c);
;                 const f32x4 h = (xv[j] * rs) * g4 * (scl + 1.f) + sh; u32x2 w; w.x = pk2(h.x, h.y); w.y = pk2(h.z, h.w); *(u32x2*)(hr + c) = w; }
	v_pk_mul_f32 v[14:15], v[14:15], v[222:223]
	v_pk_mul_f32 v[24:25], v[36:37], v[220:221]
	s_waitcnt vmcnt(12)
	v_pk_add_f32 v[26:27], v[226:227], 1.0 op_sel_hi:[1,0]
	v_pk_add_f32 v[28:29], v[224:225], 1.0 op_sel_hi:[1,0]
	s_waitcnt vmcnt(11)
	v_pk_fma_f32 v[14:15], v[14:15], v[26:27], v[230:231]
	v_pk_fma_f32 v[24:25], v[24:25], v[28:29], v[228:229]
	v_bfe_u32 v28, v14, 16, 1
	v_bfe_u32 v26, v24, 16, 1
	v_bfe_u32 v27, v25, 16, 1
	v_bfe_u32 v29, v15, 16, 1
	v_add3_u32 v24, v24, v26, s71
	v_add3_u32 v14, v14, v28, s71
	v_add3_u32 v25, v25, v27, s71
	v_add3_u32 v15, v15, v29, s71
	v_lshrrev_b32_e32 v24, 16, v24
	v_lshrrev_b32_e32 v26, 16, v14
	v_and_or_b32 v14, v25, s70, v24
	v_and_or_b32 v15, v15, s70, v26
	global_store_dwordx2 v[12:13], v[14:15], off offset:1536
	global_load_dwordx4 v[220:223], v[74:75], off
	global_load_dwordx4 v[224:227], v110, s[20:21]
	global_load_dwordx4 v[228:231], v110, s[18:19]
	v_pk_mul_f32 v[14:15], v[22:23], v[2:3] op_sel_hi:[1,0]
	s_waitcnt vmcnt(14)
	v_pk_mul_f32 v[20:21], v[20:21], v[232:233]
	v_pk_mul_f32 v[14:15], v[14:15], v[234:235]
	s_waitcnt vmcnt(13)
	v_pk_add_f32 v[22:23], v[238:239], 1.0 op_sel_hi:[1,0]
	v_pk_add_f32 v[24:25], v[236:237], 1.0 op_sel_hi:[1,0]
	s_waitcnt vmcnt(12)
	v_pk_fma_f32 v[14:15], v[14:15], v[22:23], v[242:243]
	v_pk_fma_f32 v[20:21], v[20:21], v[24:25], v[240:241]
	v_bfe_u32 v24, v14, 16, 1
	v_bfe_u32 v22, v20, 16, 1
	v_bfe_u32 v23, v21, 16, 1
	v_bfe_u32 v25, v15, 16, 1
	v_add3_u32 v20, v20, v22, s71
	v_add3_u32 v14, v14, v24, s71
	v_add3_u32 v21, v21, v23, s71
	v_add3_u32 v15, v15, v25, s71
	v_lshrrev_b32_e32 v20, 16, v20
	v_lshrrev_b32_e32 v22, 16, v14
	v_and_or_b32 v14, v21, s70, v20
	v_and_or_b32 v15, v15, s70, v22
	global_store_dwordx2 v[12:13], v[14:15], off offset:2048
	v_pk_mul_f32 v[14:15], v[18:19], v[2:3] op_sel_hi:[1,0]
	s_waitcnt vmcnt(11)
	v_pk_mul_f32 v[16:17], v[16:17], v[196:197]
	v_pk_mul_f32 v[14:15], v[14:15], v[198:199]
	s_waitcnt vmcnt(10)
	v_pk_add_f32 v[18:19], v[202:203], 1.0 op_sel_hi:[1,0]
	v_pk_add_f32 v[20:21], v[200:201], 1.0 op_sel_hi:[1,0]
	s_waitcnt vmcnt(9)
	v_pk_fma_f32 v[14:15], v[14:15], v[18:19], v[206:207]
	v_pk_fma_f32 v[16:17], v[16:17], v[20:21], v[204:205]
	v_bfe_u32 v20, v14, 16, 1
	v_bfe_u32 v18, v16, 16, 1
	v_bfe_u32 v19, v17, 16, 1
	v_bfe_u32 v21, v15, 16, 1
	v_add3_u32 v16, v16, v18, s71
	v_add3_u32 v14, v14, v20, s71
	v_add3_u32 v17, v17, v19, s71
	v_add3_u32 v15, v15, v21, s71
	v_lshrrev_b32_e32 v16, 16, v16
	v_lshrrev_b32_e32 v18, 16, v14
	v_and_or_b32 v14, v17, s70, v16
	v_and_or_b32 v15, v15, s70, v18
	global_store_dwordx2 v[12:13], v[14:15], off offset:2560
	s_nop 0
	s_waitcnt vmcnt(8)
	v_pk_mul_f32 v[8:9], v[8:9], v[208:209]
	v_pk_mul_f32 v[10:11], v[10:11], v[210:211]
	s_waitcnt vmcnt(7)
	v_pk_add_f32 v[14:15], v[214:215], 1.0 op_sel_hi:[1,0]
	v_pk_add_f32 v[16:17], v[212:213], 1.0 op_sel_hi:[1,0]
	s_waitcnt vmcnt(6)
	v_pk_fma_f32 v[10:11], v[10:11], v[14:15], v[218:219]
	v_pk_fma_f32 v[8:9], v[8:9], v[16:17], v[216:217]
	v_bfe_u32 v16, v10, 16, 1
	v_bfe_u32 v14, v8, 16, 1
	v_bfe_u32 v15, v9, 16, 1
	v_bfe_u32 v17, v11, 16, 1
	v_add3_u32 v8, v8, v14, s71
	v_add3_u32 v10, v10, v16, s71
	v_add3_u32 v9, v9, v15, s71
	v_add3_u32 v11, v11, v17, s71
	v_lshrrev_b32_e32 v8, 16, v8
	v_lshrrev_b32_e32 v10, 16, v10
	v_and_or_b32 v8, v9, s70, v8
	v_and_or_b32 v9, v11, s70, v10
	global_store_dwordx2 v[12:13], v[8:9], off offset:3072
	s_nop 0
	s_waitcnt vmcnt(5)
	v_pk_mul_f32 v[4:5], v[4:5], v[220:221]
	v_pk_mul_f32 v[6:7], v[6:7], v[222:223]
	s_waitcnt vmcnt(4)
	v_pk_add_f32 v[8:9], v[226:227], 1.0 op_sel_hi:[1,0]
	v_pk_add_f32 v[10:11], v[224:225], 1.0 op_sel_hi:[1,0]
	s_waitcnt vmcnt(3)
	v_pk_fma_f32 v[6:7], v[6:7], v[8:9], v[230:231]
	v_pk_fma_f32 v[4:5], v[4:5], v[10:11], v[228:229]
	v_bfe_u32 v9, v6, 16, 1
	v_bfe_u32 v2, v4, 16, 1
	v_bfe_u32 v8, v5, 16, 1
	v_bfe_u32 v10, v7, 16, 1
	v_add3_u32 v2, v4, v2, s71
	v_add3_u32 v4, v5, v8, s71
	v_add3_u32 v5, v6, v9, s71
	v_add3_u32 v6, v7, v10, s71
	v_lshrrev_b32_e32 v2, 16, v2
	v_lshrrev_b32_e32 v5, 16, v5
	v_and_or_b32 v4, v4, s70, v2
	v_and_or_b32 v5, v6, s70, v5
	global_store_dwordx2 v[12:13], v[4:5], off offset:3584
	s_cbranch_scc1 .LBB0_294

; __device__ __forceinline__ float silu_(float x) { return x * sigmoid_(x); }
; __device__ __forceinline__ float dot4(f32x4 a) { return (a.x * a.x + a.y * a.y) + (a.z * a.z + a.w * a.w); }
; __device__ __forceinline__ f32x4 ld_bf4(const bf16* p) { const u32x2 w = *(const u32x2*)p; return (f32x4){__builtin_bit_cast(float, w.x << 16), __builtin_bit_cast(float, w.x & 0xffff0000u), __builtin_bit_cast(float, w.y << 16), __builtin_bit_cast(float, w.y & 0xffff0000u)}; }
; #define LDY(p) ld_bf4(p)
; __device__ __forceinline__ void post_phase(const Params& P, int l, int mrows) {
;     ...
;     for (int row = gw; row < mrows; row += NGW) {
;         const bf16* ug = (const bf16*)(P.ws + WS_UG) + (size_t)row * NUG; bf16* yc = YC + (size_t)row * DM;
;     ...
;         {
;             f32x4 gg[2]; float ss = 0.f;
; #pragma unroll
;             for (int j = 0; j < 2; ++j) { const int c = 4 * lane + 256 * j; const float dsk = P.ssd_d[l * 8 + (c >> 6)]; const f32x4 y = LDY(YDP(0, 0) + c) + LDY(YDP(0, 1) + c) + ld_bf4((const bf16*)(P.ws + WS_XBC) + (size_t)row * 768 + c) * dsk; const f32x4 z = ld_bf4(ug + G_SSD_Z + c);
;                 f32x4 t; t.x = y.x * silu_(z.x); t.y = y.y * silu_(z.y); t.z = y.z * silu_(z.z); t.w = y.w * silu_(z.w); gg[j] = t; ss += dot4(t); }
.LBB0_341:
	v_lshl_add_u64 v[48:49], s[10:11], 0, v[2:3]
	v_add_co_u32_e32 v50, vcc, 0x34f00000, v48
	s_mov_b32 s5, 0x2ec00000
	s_nop 0
	v_addc_co_u32_e32 v51, vcc, 0, v49, vcc
	v_add_co_u32_e32 v52, vcc, 0x35800000, v48
	global_load_dwordx2 v[54:55], v[50:51], off
	s_nop 0
	v_addc_co_u32_e32 v53, vcc, 0, v49, vcc
	global_load_dwordx2 v[56:57], v[52:53], off
	global_load_dword v58, v[0:1], off
	v_lshl_add_u64 v[60:61], s[8:9], 0, v[2:3]
	v_add_co_u32_e32 v62, vcc, s5, v60
	s_nop 1
	v_addc_co_u32_e32 v63, vcc, 0, v61, vcc
	global_load_dwordx2 v[64:65], v[62:63], off
	s_mov_b32 s5, 0x26200000
	v_lshl_add_u64 v[66:67], s[18:19], 0, v[2:3]
	v_add_co_u32_e32 v68, vcc, s5, v66
	s_mov_b32 s5, 0x36100000
	s_nop 0
	v_addc_co_u32_e32 v69, vcc, 0, v67, vcc
	global_load_dwordx2 v[70:71], v[68:69], off
	global_load_dword v72, v[4:5], off
	global_load_dwordx2 v[74:75], v[50:51], off offset:512
	global_load_dwordx2 v[76:77], v[52:53], off offset:512
	global_load_dwordx2 v[78:79], v[62:63], off offset:512
	global_load_dwordx2 v[80:81], v[68:69], off offset:512
	global_load_dwordx4 v[82:85], v[6:7], off
	global_load_dwordx4 v[86:89], v[6:7], off offset:1024
	v_add_co_u32_e32 v90, vcc, s5, v48
	s_mov_b32 s5, 0x36a00000
	s_nop 0
	v_addc_co_u32_e32 v91, vcc, 0, v49, vcc
	v_add_co_u32_e32 v92, vcc, s5, v48
	global_load_dwordx2 v[94:95], v[90:91], off
	s_nop 0
	v_addc_co_u32_e32 v93, vcc, 0, v49, vcc
	global_load_dwordx2 v[96:97], v[92:93], off
	s_mov_b32 s5, 0x37300000
	global_load_dwordx2 v[98:99], v[68:69], off offset:1024
	global_load_dwordx2 v[100:101], v[90:91], off offset:512
	global_load_dwordx2 v[102:103], v[92:93], off offset:512
	global_load_dwordx2 v[104:105], v[68:69], off offset:1536
	v_add_co_u32_e32 v106, vcc, s5, v48
	s_mov_b32 s5, 0x37c00000
	s_nop 0
	v_addc_co_u32_e32 v107, vcc, 0, v49, vcc
	v_add_co_u32_e32 v108, vcc, s5, v48
	global_load_dwordx2 v[110:111], v[106:107], off
	s_nop 0
	v_addc_co_u32_e32 v109, vcc, 0, v49, vcc
	global_load_dwordx2 v[112:113], v[108:109], off
	s_mov_b32 s5, 0x38500000
	global_load_dwordx4 v[114:117], v[8:9], off
	global_load_dwordx2 v[118:119], v[68:69], off offset:2048
	global_load_dwordx2 v[120:121], v[106:107], off offset:512
	global_load_dwordx2 v[122:123], v[108:109], off offset:512
	global_load_dwordx4 v[124:127], v[8:9], off
	global_load_dwordx2 v[128:129], v[68:69], off offset:2560
	v_add_co_u32_e32 v130, vcc, s5, v48
	s_mov_b32 s5, 0x38e00000
	s_nop 0
	v_addc_co_u32_e32 v131, vcc, 0, v49, vcc
	v_add_co_u32_e32 v136, vcc, s5, v48
	global_load_dwordx2 v[138:139], v[130:131], off
	s_nop 0
	v_addc_co_u32_e32 v137, vcc, 0, v49, vcc
	global_load_dwordx2 v[140:141], v[136:137], off
	global_load_dwordx2 v[142:143], v[130:131], off offset:512
	global_load_dwordx2 v[144:145], v[136:137], off offset:512
	global_load_dwordx2 v[146:147], v[68:69], off offset:3072
	global_load_dwordx2 v[148:149], v[68:69], off offset:3584
	s_nop 0
	s_nop 0
	s_mov_b32 s6, 0x358637bd
	s_add_i32 s0, s0, s4
	s_waitcnt vmcnt(31)
	v_lshlrev_b32_e32 v14, 16, v54
	v_and_b32_e32 v15, 0xffff0000, v54
	v_lshlrev_b32_e32 v12, 16, v55
	v_and_b32_e32 v13, 0xffff0000, v55
	s_waitcnt vmcnt(30)
	v_lshlrev_b32_e32 v24, 16, v56
	v_and_b32_e32 v25, 0xffff0000, v56
	v_lshlrev_b32_e32 v22, 16, v57
	v_and_b32_e32 v23, 0xffff0000, v57
	v_pk_add_f32 v[12:13], v[12:13], v[22:23]
	v_pk_add_f32 v[14:15], v[14:15], v[24:25]
	s_nop 0
	s_add_u32 s8, s8, s20
	s_waitcnt vmcnt(28)
	v_lshlrev_b32_e32 v26, 16, v64
	v_and_b32_e32 v27, 0xffff0000, v64
	v_lshlrev_b32_e32 v24, 16, v65
	v_and_b32_e32 v25, 0xffff0000, v65
	v_mov_b32_e32 v59, v11
	v_pk_fma_f32 v[24:25], v[58:59], v[24:25], v[12:13] op_sel_hi:[0,1,1]
	v_mov_b32_e32 v59, v11
	v_pk_fma_f32 v[12:13], v[58:59], v[26:27], v[14:15] op_sel_hi:[0,1,1]
	s_nop 0
	s_waitcnt vmcnt(27)
	v_lshlrev_b32_e32 v26, 16, v70
	v_and_b32_e32 v27, 0xffff0000, v70
	v_mul_f32_e32 v14, 0xbfb8aa3b, v26
	v_exp_f32_e32 v14, v14
	s_nop 0
	v_add_f32_e32 v14, 1.0, v14
	v_rcp_f32_e32 v28, v14
	v_mul_f32_e32 v14, 0xbfb8aa3b, v27
	v_exp_f32_e32 v14, v14
	s_nop 0
	v_add_f32_e32 v14, 1.0, v14
	v_rcp_f32_e32 v29, v14
	v_lshlrev_b32_e32 v14, 16, v71
	v_and_b32_e32 v15, 0xffff0000, v71
	v_pk_mul_f32 v[26:27], v[28:29], v[26:27]
	s_nop 0
	v_pk_mul_f32 v[12:13], v[26:27], v[12:13]
	v_mul_f32_e32 v26, 0xbfb8aa3b, v14
	v_mul_f32_e32 v27, 0xbfb8aa3b, v15
	v_exp_f32_e32 v26, v26
	v_exp_f32_e32 v27, v27
	v_add_f32_e32 v26, 1.0, v26
	v_add_f32_e32 v27, 1.0, v27
	v_rcp_f32_e32 v26, v26
	v_rcp_f32_e32 v27, v27
	s_nop 0
	v_pk_mul_f32 v[14:15], v[26:27], v[14:15]
	s_nop 0
	v_pk_mul_f32 v[14:15], v[14:15], v[24:25]
	s_nop 0
	s_waitcnt vmcnt(25)
	v_lshlrev_b32_e32 v26, 16, v74
	v_and_b32_e32 v27, 0xffff0000, v74
	v_lshlrev_b32_e32 v18, 16, v75
	v_and_b32_e32 v19, 0xffff0000, v75
	s_waitcnt vmcnt(24)
	v_lshlrev_b32_e32 v28, 16, v76
	v_and_b32_e32 v29, 0xffff0000, v76
	v_lshlrev_b32_e32 v20, 16, v77
	v_and_b32_e32 v21, 0xffff0000, v77
	v_pk_add_f32 v[18:19], v[18:19], v[20:21]
	v_pk_add_f32 v[26:27], v[26:27], v[28:29]
	s_waitcnt vmcnt(23)
	v_lshlrev_b32_e32 v22, 16, v78
	v_and_b32_e32 v23, 0xffff0000, v78
	v_lshlrev_b32_e32 v20, 16, v79
	v_and_b32_e32 v21, 0xffff0000, v79
	v_mov_b32_e32 v73, v25
	v_pk_fma_f32 v[20:21], v[72:73], v[20:21], v[18:19] op_sel_hi:[0,1,1]
	v_mov_b32_e32 v73, v25
	v_pk_fma_f32 v[18:19], v[72:73], v[22:23], v[26:27] op_sel_hi:[0,1,1]
	s_waitcnt vmcnt(22)
; __device__ __forceinline__ float gelu_tanh_(float x) { const float z = 0.7978845608f * (x + 0.044715f * x * x * x); const float t = 1.f - 2.f * __builtin_amdgcn_rcpf(1.f + __expf(2.f * z)); return 0.5f * x * (1.f + t); }
; __device__ __forceinline__ unsigned pk2(float lo, float hi) { return f2bf(lo) | (f2bf(hi) << 16); }
; __device__ __forceinline__ f32x4 ld_bf4(const bf16* p) { const u32x2 w = *(const u32x2*)p; return (f32x4){__builtin_bit_cast(float, w.x << 16), __builtin_bit_cast(float, w.x & 0xffff0000u), __builtin_bit_cast(float, w.y << 16), __builtin_bit_cast(float, w.y & 0xffff0000u)}; }
; #define LDY(p) ld_bf4(p)
; __device__ __forceinline__ void post_phase(const Params& P, int l, int mrows) {
;     ...
;             const float rs = rsqrtf(wave_sum(ss) * (1.f / 512.f) + EPS);
; #pragma unroll
;             for (int j = 0; j < 2; ++j) { const int c = 4 * lane + 256 * j; const f32x4 w = *(const f32x4*)(P.ssd_norm_w + (size_t)l * 512 + c); const f32x4 o = gg[j] * rs * w;
;                 u32x2 pk; pk.x = pk2(o.x, o.y); pk.y = pk2(o.z, o.w); *(u32x2*)(yc + c) = pk; }
;         }
;         {
; #pragma unroll
;             for (int j = 0; j < 2; ++j) { const int c = 4 * lane + 256 * j; const f32x4 hh = LDY(YDP(1, 0) + c) + LDY(YDP(1, 1) + c); const f32x4 gb = ld_bf4(ug + G_LRU_G + c);
;                 f32x4 o; o.x = hh.x * gelu_tanh_(gb.x); o.y = hh.y * gelu_tanh_(gb.y); o.z = hh.z * gelu_tanh_(gb.z); o.w = hh.w * gelu_tanh_(gb.w);
;                 u32x2 pk; pk.x = pk2(o.x, o.y); pk.y = pk2(o.z, o.w); *(u32x2*)(yc + 512 + c) = pk; }
	v_lshlrev_b32_e32 v24, 16, v80
	v_and_b32_e32 v25, 0xffff0000, v80
	v_mul_f32_e32 v22, 0xbfb8aa3b, v24
	v_exp_f32_e32 v22, v22
	s_nop 0
	v_add_f32_e32 v22, 1.0, v22
	v_rcp_f32_e32 v26, v22
	v_mul_f32_e32 v22, 0xbfb8aa3b, v25
	v_exp_f32_e32 v22, v22
	s_nop 0
	v_add_f32_e32 v22, 1.0, v22
	v_rcp_f32_e32 v27, v22
	v_lshlrev_b32_e32 v22, 16, v81
	v_and_b32_e32 v23, 0xffff0000, v81
	v_pk_mul_f32 v[24:25], v[26:27], v[24:25]
	s_nop 0
	v_pk_mul_f32 v[18:19], v[24:25], v[18:19]
	v_mul_f32_e32 v24, 0xbfb8aa3b, v22
	v_mul_f32_e32 v25, 0xbfb8aa3b, v23
	v_exp_f32_e32 v24, v24
	v_exp_f32_e32 v25, v25
	v_mov_b32_e32 v26, v15
	v_add_f32_e32 v24, 1.0, v24
	v_add_f32_e32 v25, 1.0, v25
	v_rcp_f32_e32 v24, v24
	v_rcp_f32_e32 v25, v25
	s_nop 0
	v_pk_mul_f32 v[22:23], v[24:25], v[22:23]
	s_nop 0
	v_pk_mul_f32 v[20:21], v[22:23], v[20:21]
	v_mov_b32_e32 v24, v13
	v_mov_b32_e32 v25, v19
	v_mov_b32_e32 v22, v12
	v_mov_b32_e32 v23, v18
	v_pk_mul_f32 v[24:25], v[24:25], v[24:25]
	v_mov_b32_e32 v27, v21
	v_pk_fma_f32 v[22:23], v[22:23], v[22:23], v[24:25]
	v_mov_b32_e32 v24, v14
	v_mov_b32_e32 v25, v20
	v_pk_mul_f32 v[26:27], v[26:27], v[26:27]
	s_nop 0
	v_pk_fma_f32 v[24:25], v[24:25], v[24:25], v[26:27]
	s_nop 0
	v_pk_add_f32 v[22:23], v[22:23], v[24:25]
	v_add_f32_e32 v22, v22, v23
	s_waitcnt lgkmcnt(0)
	s_nop 1
	v_add_f32_dpp v22, v22, v22 quad_perm:[1,0,3,2] row_mask:0xf bank_mask:0xf
	s_waitcnt lgkmcnt(0)
	s_nop 1
	v_add_f32_dpp v22, v22, v22 quad_perm:[2,3,0,1] row_mask:0xf bank_mask:0xf
	s_waitcnt lgkmcnt(0)
	s_nop 1
	v_add_f32_dpp v22, v22, v22 row_half_mirror row_mask:0xf bank_mask:0xf
	s_waitcnt lgkmcnt(0)
	s_nop 1
	v_add_f32_dpp v22, v22, v22 row_mirror row_mask:0xf bank_mask:0xf
	ds_bpermute_b32 v23, v34, v22
	s_waitcnt lgkmcnt(0)
	v_add_f32_e32 v22, v22, v23
	ds_bpermute_b32 v23, v35, v22
	s_waitcnt lgkmcnt(0)
	v_add_f32_e32 v22, v22, v23
	v_fmamk_f32 v22, v22, 0x3b000000, v169
	v_cmp_gt_f32_e32 vcc, s3, v22
	v_mul_f32_e32 v23, 0x4b800000, v22
	s_nop 0
	v_cndmask_b32_e32 v22, v22, v23, vcc
	v_rsq_f32_e32 v22, v22
	s_nop 0
	v_mul_f32_e32 v23, 0x45800000, v22
	v_cndmask_b32_e32 v22, v22, v23, vcc
	v_pk_mul_f32 v[12:13], v[12:13], v[22:23] op_sel_hi:[1,0]
	v_pk_mul_f32 v[14:15], v[14:15], v[22:23] op_sel_hi:[1,0]
	s_waitcnt vmcnt(21)
	v_pk_mul_f32 v[12:13], v[82:83], v[12:13]
	s_nop 0
	v_bfe_u32 v23, v12, 16, 1
	v_add3_u32 v12, v12, v23, s71
	v_bfe_u32 v23, v13, 16, 1
	v_pk_mul_f32 v[14:15], v[84:85], v[14:15]
	v_lshrrev_b32_e32 v12, 16, v12
	v_add3_u32 v13, v13, v23, s71
	v_and_or_b32 v24, v13, s70, v12
	v_bfe_u32 v12, v14, 16, 1
	v_add3_u32 v12, v14, v12, s71
	v_bfe_u32 v13, v15, 16, 1
	v_lshrrev_b32_e32 v12, 16, v12
	v_add3_u32 v13, v15, v13, s71
	v_and_or_b32 v25, v13, s70, v12
	v_lshl_add_u64 v[12:13], s[14:15], 0, v[2:3]
	v_add_co_u32_e32 v12, vcc, s22, v12
	v_pk_mul_f32 v[14:15], v[18:19], v[22:23] op_sel_hi:[1,0]
	s_nop 0
	v_addc_co_u32_e32 v13, vcc, 0, v13, vcc
	global_store_dwordx2 v[12:13], v[24:25], off
	v_pk_mul_f32 v[18:19], v[20:21], v[22:23] op_sel_hi:[1,0]
	s_waitcnt vmcnt(21)
	v_pk_mul_f32 v[14:15], v[86:87], v[14:15]
	s_nop 0
	v_bfe_u32 v20, v14, 16, 1
	v_add3_u32 v14, v14, v20, s71
	v_bfe_u32 v20, v15, 16, 1
	v_pk_mul_f32 v[18:19], v[88:89], v[18:19]
	v_lshrrev_b32_e32 v14, 16, v14
	v_add3_u32 v15, v15, v20, s71
	v_and_or_b32 v14, v15, s70, v14
	v_bfe_u32 v15, v18, 16, 1
	v_add3_u32 v15, v18, v15, s71
	v_bfe_u32 v18, v19, 16, 1
	v_lshrrev_b32_e32 v15, 16, v15
	v_add3_u32 v18, v19, v18, s71
	v_and_or_b32 v15, v18, s70, v15
	global_store_dwordx2 v[12:13], v[14:15], off offset:512
	s_nop 0
	s_nop 0
	s_waitcnt vmcnt(21)
	v_lshlrev_b32_e32 v20, 16, v94
	v_and_b32_e32 v21, 0xffff0000, v94
	v_lshlrev_b32_e32 v18, 16, v95
	v_and_b32_e32 v19, 0xffff0000, v95
	s_waitcnt vmcnt(20)
	v_lshlrev_b32_e32 v26, 16, v96
	v_and_b32_e32 v27, 0xffff0000, v96
	v_lshlrev_b32_e32 v24, 16, v97
	v_and_b32_e32 v25, 0xffff0000, v97
	v_pk_add_f32 v[18:19], v[18:19], v[24:25]
	v_pk_add_f32 v[20:21], v[20:21], v[26:27]
	s_waitcnt vmcnt(19)
	v_lshlrev_b32_e32 v26, 16, v98
	v_mul_f32_e32 v28, 0x3d372713, v26
	v_mul_f32_e32 v28, v28, v26
	v_mov_b32_e32 v29, v26
	v_and_b32_e32 v24, 0xffff0000, v98
	v_fmac_f32_e32 v29, v28, v29
	v_mul_f32_e32 v28, 0x3f4c422a, v29
	v_mul_f32_e32 v29, 0x3d372713, v24
	v_mul_f32_e32 v29, v29, v24
	v_mov_b32_e32 v36, v24
	v_fmac_f32_e32 v36, v29, v36
	v_mul_f32_e32 v29, 0x3f4c422a, v36
	v_add_f32_e32 v29, v29, v29
	v_mul_f32_e32 v29, 0x3fb8aa3b, v29
	v_exp_f32_e32 v29, v29
	v_lshlrev_b32_e32 v27, 16, v99
	v_mov_b32_e32 v37, v27
	v_add_f32_e32 v28, v28, v28
	v_add_f32_e32 v29, 1.0, v29
	v_rcp_f32_e32 v36, v29
	v_mul_f32_e32 v29, 0x3d372713, v27
	v_mul_f32_e32 v29, v29, v27
	v_fmac_f32_e32 v37, v29, v37
	v_mul_f32_e32 v29, 0x3f4c422a, v37
	v_add_f32_e32 v29, v29, v29
	v_mul_f32_e32 v28, 0x3fb8aa3b, v28
	v_mul_f32_e32 v29, 0x3fb8aa3b, v29
	v_exp_f32_e32 v28, v28
	v_exp_f32_e32 v29, v29
	v_and_b32_e32 v25, 0xffff0000, v99
	v_pk_mul_f32 v[26:27], v[26:27], 0.5 op_sel_hi:[1,0]
	v_add_f32_e32 v28, 1.0, v28
	v_add_f32_e32 v29, 1.0, v29
	v_rcp_f32_e32 v28, v28
	v_rcp_f32_e32 v29, v29
	s_nop 0
	v_pk_fma_f32 v[28:29], v[28:29], 2.0, 1.0 op_sel_hi:[1,0,0] neg_lo:[1,0,0] neg_hi:[1,0,0]
	s_nop 0
	v_pk_add_f32 v[28:29], v[28:29], 1.0 op_sel_hi:[1,0]
	s_nop 0
	v_pk_mul_f32 v[26:27], v[26:27], v[28:29]
	v_mov_b32_e32 v29, v18
	v_mul_f32_e32 v18, 0x3d372713, v25
	v_mov_b32_e32 v28, v20
	v_mul_f32_e32 v18, v18, v25
	v_mov_b32_e32 v20, v25
	v_fmac_f32_e32 v20, v18, v20
	v_mul_f32_e32 v18, 0x3f4c422a, v20
	v_add_f32_e32 v18, v18, v18
	v_mul_f32_e32 v18, 0x3fb8aa3b, v18
	v_exp_f32_e32 v18, v18
	v_pk_mul_f32 v[26:27], v[28:29], v[26:27]
	v_pk_mul_f32 v[24:25], v[24:25], 0.5 op_sel_hi:[1,0]
	v_and_b32_sdwa v20, v27, v173 dst_sel:DWORD dst_unused:UNUSED_PAD src0_sel:WORD_1 src1_sel:DWORD
	v_add_f32_e32 v18, 1.0, v18
	v_rcp_f32_e32 v37, v18
	v_mov_b32_e32 v18, v21
	v_and_b32_sdwa v21, v26, v173 dst_sel:DWORD dst_unused:UNUSED_PAD src0_sel:WORD_1 src1_sel:DWORD
	v_add3_u32 v21, v26, v21, s71
	v_pk_fma_f32 v[28:29], v[36:37], 2.0, 1.0 op_sel_hi:[1,0,0] neg_lo:[1,0,0] neg_hi:[1,0,0]
	v_add3_u32 v20, v27, v20, s71
	v_pk_add_f32 v[28:29], v[28:29], 1.0 op_sel_hi:[1,0]
	s_nop 0
	v_pk_mul_f32 v[24:25], v[24:25], v[28:29]
	s_nop 0
	v_pk_mul_f32 v[18:19], v[18:19], v[24:25]
	s_nop 0
	v_and_b32_sdwa v24, v19, v173 dst_sel:DWORD dst_unused:UNUSED_PAD src0_sel:WORD_1 src1_sel:DWORD
	v_and_b32_sdwa v25, v18, v173 dst_sel:DWORD dst_unused:UNUSED_PAD src0_sel:WORD_1 src1_sel:DWORD
	v_add3_u32 v19, v19, v24, s71
	v_add3_u32 v18, v18, v25, s71
	v_and_b32_e32 v19, 0xffff0000, v19
	v_and_b32_e32 v18, 0xffff0000, v18
	v_or_b32_sdwa v19, v19, v20 dst_sel:DWORD dst_unused:UNUSED_PAD src0_sel:DWORD src1_sel:WORD_1
	v_or_b32_sdwa v18, v18, v21 dst_sel:DWORD dst_unused:UNUSED_PAD src0_sel:DWORD src1_sel:WORD_1
	global_store_dwordx2 v[12:13], v[18:19], off offset:1024
	s_nop 0
	s_waitcnt vmcnt(19)
; __device__ __forceinline__ float silu_(float x) { return x * sigmoid_(x); }
; __device__ __forceinline__ float gelu_tanh_(float x) { const float z = 0.7978845608f * (x + 0.044715f * x * x * x); const float t = 1.f - 2.f * __builtin_amdgcn_rcpf(1.f + __expf(2.f * z)); return 0.5f * x * (1.f + t); }
; __device__ __forceinline__ unsigned pk2(float lo, float hi) { return f2bf(lo) | (f2bf(hi) << 16); }
; __device__ __forceinline__ float dot4(f32x4 a) { return (a.x * a.x + a.y * a.y) + (a.z * a.z + a.w * a.w); }
; __device__ __forceinline__ f32x4 ld_bf4(const bf16* p) { const u32x2 w = *(const u32x2*)p; return (f32x4){__builtin_bit_cast(float, w.x << 16), __builtin_bit_cast(float, w.x & 0xffff0000u), __builtin_bit_cast(float, w.y << 16), __builtin_bit_cast(float, w.y & 0xffff0000u)}; }
; #define LDY(p) ld_bf4(p)
; __device__ __forceinline__ void post_phase(const Params& P, int l, int mrows) {
;     ...
;             for (int j = 0; j < 2; ++j) { const int c = 4 * lane + 256 * j; const f32x4 hh = LDY(YDP(1, 0) + c) + LDY(YDP(1, 1) + c); const f32x4 gb = ld_bf4(ug + G_LRU_G + c);
;                 f32x4 o; o.x = hh.x * gelu_tanh_(gb.x); o.y = hh.y * gelu_tanh_(gb.y); o.z = hh.z * gelu_tanh_(gb.z); o.w = hh.w * gelu_tanh_(gb.w);
;                 u32x2 pk; pk.x = pk2(o.x, o.y); pk.y = pk2(o.z, o.w); *(u32x2*)(yc + 512 + c) = pk; }
;         }
;         {
; #pragma unroll
;             for (int j = 0; j < 2; ++j) { const int c = 4 * lane + 256 * j; const f32x4 o = LDY(YDP(2, 0) + c) + LDY(YDP(2, 1) + c);
;                 const float rs = rsqrtf(half_sum(dot4(o)) * (1.f / 128.f) + EPS); const f32x4 w = *(const f32x4*)(P.hgrn_norm_w + (size_t)l * 128 + (c & 127)); const f32x4 gt = ld_bf4(ug + G_HG_G + c);
;                 f32x4 r; r.x = o.x * rs * w.x * silu_(gt.x); r.y = o.y * rs * w.y * silu_(gt.y); r.z = o.z * rs * w.z * silu_(gt.z); r.w = o.w * rs * w.w * silu_(gt.w);
	v_lshlrev_b32_e32 v18, 16, v100
	v_and_b32_e32 v19, 0xffff0000, v100
	v_lshlrev_b32_e32 v14, 16, v101
	v_and_b32_e32 v15, 0xffff0000, v101
	s_waitcnt vmcnt(18)
	v_lshlrev_b32_e32 v22, 16, v102
	v_and_b32_e32 v23, 0xffff0000, v102
	v_lshlrev_b32_e32 v20, 16, v103
	v_and_b32_e32 v21, 0xffff0000, v103
	v_pk_add_f32 v[14:15], v[14:15], v[20:21]
	v_pk_add_f32 v[18:19], v[18:19], v[22:23]
	s_waitcnt vmcnt(17)
	v_lshlrev_b32_e32 v22, 16, v104
	v_mul_f32_e32 v24, 0x3d372713, v22
	v_mul_f32_e32 v24, v24, v22
	v_mov_b32_e32 v25, v22
	v_and_b32_e32 v20, 0xffff0000, v104
	v_fmac_f32_e32 v25, v24, v25
	v_mul_f32_e32 v24, 0x3f4c422a, v25
	v_mul_f32_e32 v25, 0x3d372713, v20
	v_mul_f32_e32 v25, v25, v20
	v_mov_b32_e32 v26, v20
	v_fmac_f32_e32 v26, v25, v26
	v_mul_f32_e32 v25, 0x3f4c422a, v26
	v_add_f32_e32 v25, v25, v25
	v_mul_f32_e32 v25, 0x3fb8aa3b, v25
	v_exp_f32_e32 v25, v25
	v_lshlrev_b32_e32 v23, 16, v105
	v_mov_b32_e32 v27, v23
	v_add_f32_e32 v24, v24, v24
	v_add_f32_e32 v25, 1.0, v25
	v_rcp_f32_e32 v26, v25
	v_mul_f32_e32 v25, 0x3d372713, v23
	v_mul_f32_e32 v25, v25, v23
	v_fmac_f32_e32 v27, v25, v27
	v_mul_f32_e32 v25, 0x3f4c422a, v27
	v_add_f32_e32 v25, v25, v25
	v_mul_f32_e32 v24, 0x3fb8aa3b, v24
	v_mul_f32_e32 v25, 0x3fb8aa3b, v25
	v_exp_f32_e32 v24, v24
	v_exp_f32_e32 v25, v25
	v_and_b32_e32 v21, 0xffff0000, v105
	v_pk_mul_f32 v[22:23], v[22:23], 0.5 op_sel_hi:[1,0]
	v_add_f32_e32 v24, 1.0, v24
	v_add_f32_e32 v25, 1.0, v25
	v_rcp_f32_e32 v24, v24
	v_rcp_f32_e32 v25, v25
	s_nop 0
	v_pk_fma_f32 v[24:25], v[24:25], 2.0, 1.0 op_sel_hi:[1,0,0] neg_lo:[1,0,0] neg_hi:[1,0,0]
	s_nop 0
	v_pk_add_f32 v[24:25], v[24:25], 1.0 op_sel_hi:[1,0]
	s_nop 0
	v_pk_mul_f32 v[22:23], v[22:23], v[24:25]
	v_mov_b32_e32 v25, v14
	v_mul_f32_e32 v14, 0x3d372713, v21
	v_mov_b32_e32 v24, v18
	v_mul_f32_e32 v14, v14, v21
	v_mov_b32_e32 v18, v21
	v_fmac_f32_e32 v18, v14, v18
	v_mul_f32_e32 v14, 0x3f4c422a, v18
	v_add_f32_e32 v14, v14, v14
	v_mul_f32_e32 v14, 0x3fb8aa3b, v14
	v_exp_f32_e32 v14, v14
	v_pk_mul_f32 v[22:23], v[24:25], v[22:23]
	v_pk_mul_f32 v[20:21], v[20:21], 0.5 op_sel_hi:[1,0]
	v_and_b32_sdwa v18, v23, v173 dst_sel:DWORD dst_unused:UNUSED_PAD src0_sel:WORD_1 src1_sel:DWORD
	v_add_f32_e32 v14, 1.0, v14
	v_rcp_f32_e32 v27, v14
	v_mov_b32_e32 v14, v19
	v_and_b32_sdwa v19, v22, v173 dst_sel:DWORD dst_unused:UNUSED_PAD src0_sel:WORD_1 src1_sel:DWORD
	v_add3_u32 v19, v22, v19, s71
	v_pk_fma_f32 v[24:25], v[26:27], 2.0, 1.0 op_sel_hi:[1,0,0] neg_lo:[1,0,0] neg_hi:[1,0,0]
	v_add3_u32 v18, v23, v18, s71
	v_pk_add_f32 v[24:25], v[24:25], 1.0 op_sel_hi:[1,0]
	s_nop 0
	v_pk_mul_f32 v[20:21], v[20:21], v[24:25]
	s_nop 0
	v_pk_mul_f32 v[14:15], v[14:15], v[20:21]
	s_nop 0
	v_and_b32_sdwa v20, v15, v173 dst_sel:DWORD dst_unused:UNUSED_PAD src0_sel:WORD_1 src1_sel:DWORD
	v_and_b32_sdwa v21, v14, v173 dst_sel:DWORD dst_unused:UNUSED_PAD src0_sel:WORD_1 src1_sel:DWORD
	v_add3_u32 v15, v15, v20, s71
	v_add3_u32 v14, v14, v21, s71
	v_and_b32_e32 v15, 0xffff0000, v15
	v_and_b32_e32 v14, 0xffff0000, v14
	v_or_b32_sdwa v15, v15, v18 dst_sel:DWORD dst_unused:UNUSED_PAD src0_sel:DWORD src1_sel:WORD_1
	v_or_b32_sdwa v14, v14, v19 dst_sel:DWORD dst_unused:UNUSED_PAD src0_sel:DWORD src1_sel:WORD_1
	global_store_dwordx2 v[12:13], v[14:15], off offset:1536
	s_nop 0
	s_nop 0
	s_waitcnt vmcnt(17)
	v_lshlrev_b32_e32 v20, 16, v110
	v_and_b32_e32 v21, 0xffff0000, v110
	v_lshlrev_b32_e32 v18, 16, v111
	v_and_b32_e32 v19, 0xffff0000, v111
	s_waitcnt vmcnt(16)
	v_lshlrev_b32_e32 v26, 16, v112
	v_and_b32_e32 v27, 0xffff0000, v112
	v_lshlrev_b32_e32 v24, 16, v113
	v_and_b32_e32 v25, 0xffff0000, v113
	v_pk_add_f32 v[26:27], v[20:21], v[26:27]
	v_pk_add_f32 v[24:25], v[18:19], v[24:25]
	v_pk_mul_f32 v[20:21], v[26:27], v[26:27]
	v_pk_mul_f32 v[18:19], v[24:25], v[24:25]
	v_mov_b32_e32 v44, v26
	v_pk_mov_b32 v[28:29], v[20:21], v[18:19] op_sel:[1,0]
	v_mov_b32_e32 v21, v19
	v_pk_add_f32 v[28:29], v[28:29], v[20:21]
	v_mov_b32_e32 v45, v24
	v_mov_b32_e32 v24, v27
	s_waitcnt vmcnt(15)
	v_mov_b32_e32 v46, v114
	s_waitcnt vmcnt(14)
	v_lshlrev_b32_e32 v39, 16, v119
	v_lshlrev_b32_e32 v38, 16, v118
	v_and_b32_e32 v36, 0xffff0000, v118
	v_mul_f32_e32 v41, 0xbfb8aa3b, v36
	v_mul_f32_e32 v18, 0xbfb8aa3b, v39
	v_exp_f32_e32 v41, v41
	v_exp_f32_e32 v18, v18
	v_and_b32_e32 v37, 0xffff0000, v119
	v_mul_f32_e32 v40, 0xbfb8aa3b, v38
	v_add_f32_e32 v41, 1.0, v41
	v_add_f32_e32 v18, 1.0, v18
	v_rcp_f32_e32 v42, v41
	v_rcp_f32_e32 v41, v18
	v_mul_f32_e32 v18, 0xbfb8aa3b, v37
	v_exp_f32_e32 v18, v18
	v_exp_f32_e32 v40, v40
	v_mov_b32_e32 v47, v116
	v_mov_b32_e32 v20, v115
	v_add_f32_e32 v18, 1.0, v18
	v_rcp_f32_e32 v43, v18
	v_add_f32_e32 v40, 1.0, v40
	v_rcp_f32_e32 v40, v40
	s_waitcnt vmcnt(13)
	v_lshlrev_b32_e32 v26, 16, v120
	v_pk_mul_f32 v[18:19], v[42:43], v[36:37]
	v_and_b32_e32 v27, 0xffff0000, v120
	v_lshlrev_b32_e32 v14, 16, v121
	v_and_b32_e32 v15, 0xffff0000, v121
	s_waitcnt vmcnt(12)
	v_lshlrev_b32_e32 v36, 16, v122
	v_and_b32_e32 v37, 0xffff0000, v122
	v_lshlrev_b32_e32 v22, 16, v123
	v_and_b32_e32 v23, 0xffff0000, v123
	v_pk_add_f32 v[26:27], v[26:27], v[36:37]
	v_pk_add_f32 v[22:23], v[14:15], v[22:23]
	v_pk_mul_f32 v[36:37], v[26:27], v[26:27]
	v_pk_mul_f32 v[14:15], v[22:23], v[22:23]
	v_pk_mul_f32 v[38:39], v[40:41], v[38:39]
	v_pk_mov_b32 v[40:41], v[36:37], v[14:15] op_sel:[1,0]
	v_mov_b32_e32 v37, v15
	v_pk_add_f32 v[14:15], v[40:41], v[36:37]
	v_mov_b32_e32 v37, v28
	v_mov_b32_e32 v36, v14
	v_mov_b32_e32 v28, v15
	v_pk_add_f32 v[14:15], v[36:37], v[28:29]
	v_mov_b32_e32 v43, v22
	v_mov_b32_e32 v22, v27
	v_mov_b32_e32 v42, v26
	s_waitcnt lgkmcnt(0)
; __device__ __forceinline__ float silu_(float x) { return x * sigmoid_(x); }
; __device__ __forceinline__ unsigned pk2(float lo, float hi) { return f2bf(lo) | (f2bf(hi) << 16); }
; __device__ __forceinline__ float dot4(f32x4 a) { return (a.x * a.x + a.y * a.y) + (a.z * a.z + a.w * a.w); }
; __device__ __forceinline__ f32x4 ld_bf4(const bf16* p) { const u32x2 w = *(const u32x2*)p; return (f32x4){__builtin_bit_cast(float, w.x << 16), __builtin_bit_cast(float, w.x & 0xffff0000u), __builtin_bit_cast(float, w.y << 16), __builtin_bit_cast(float, w.y & 0xffff0000u)}; }
; #define LDY(p) ld_bf4(p)
; __device__ __forceinline__ float half_sum(float v) {
; #pragma unroll
;     for (int o = 1; o < 32; o <<= 1) v += __shfl_xor(v, o);
;     return v;
; }
; __device__ __forceinline__ void post_phase(const Params& P, int l, int mrows) {
;     ...
;         {
; #pragma unroll
;             for (int j = 0; j < 2; ++j) { const int c = 4 * lane + 256 * j; const f32x4 o = LDY(YDP(2, 0) + c) + LDY(YDP(2, 1) + c);
;                 const float rs = rsqrtf(half_sum(dot4(o)) * (1.f / 128.f) + EPS); const f32x4 w = *(const f32x4*)(P.hgrn_norm_w + (size_t)l * 128 + (c & 127)); const f32x4 gt = ld_bf4(ug + G_HG_G + c);
;                 f32x4 r; r.x = o.x * rs * w.x * silu_(gt.x); r.y = o.y * rs * w.y * silu_(gt.y); r.z = o.z * rs * w.z * silu_(gt.z); r.w = o.w * rs * w.w * silu_(gt.w);
;                 u32x2 pk; pk.x = pk2(r.x, r.y); pk.y = pk2(r.z, r.w); *(u32x2*)(yc + 1024 + c) = pk; }
;         }
;         {
; #pragma unroll
;             for (int j = 0; j < 2; ++j) { const int c = 4 * lane + 256 * j; const f32x4 o = LDY(YDP(3, 0) + c) + LDY(YDP(3, 1) + c);
;                 const float rs = rsqrtf(half_sum(dot4(o)) * (1.f / 128.f) + EPS); const f32x4 gt = ld_bf4(ug + G_RT_G + c);
;                 f32x4 r; r.x = o.x * rs * silu_(gt.x); r.y = o.y * rs * silu_(gt.y); r.z = o.z * rs * silu_(gt.z); r.w = o.w * rs * silu_(gt.w);
;                 u32x2 pk; pk.x = pk2(r.x, r.y); pk.y = pk2(r.z, r.w); *(u32x2*)(yc + 1536 + c) = pk; }
	v_add_f32_dpp v14, v14, v14 quad_perm:[1,0,3,2] row_mask:0xf bank_mask:0xf
	v_add_f32_dpp v15, v15, v15 quad_perm:[1,0,3,2] row_mask:0xf bank_mask:0xf
	s_waitcnt lgkmcnt(0)
	s_nop 0
	v_add_f32_dpp v14, v14, v14 quad_perm:[2,3,0,1] row_mask:0xf bank_mask:0xf
	v_add_f32_dpp v15, v15, v15 quad_perm:[2,3,0,1] row_mask:0xf bank_mask:0xf
	s_waitcnt lgkmcnt(0)
	s_nop 0
	v_add_f32_dpp v14, v14, v14 row_half_mirror row_mask:0xf bank_mask:0xf
	v_add_f32_dpp v15, v15, v15 row_half_mirror row_mask:0xf bank_mask:0xf
	s_waitcnt lgkmcnt(0)
	s_nop 0
	v_add_f32_dpp v14, v14, v14 row_mirror row_mask:0xf bank_mask:0xf
	v_add_f32_dpp v15, v15, v15 row_mirror row_mask:0xf bank_mask:0xf
	ds_bpermute_b32 v29, v34, v15
	ds_bpermute_b32 v28, v34, v14
	s_waitcnt lgkmcnt(0)
	v_pk_add_f32 v[28:29], v[14:15], v[28:29]
	v_mov_b64_e32 v[14:15], s[6:7]
	v_pk_fma_f32 v[28:29], v[28:29], s[24:25], v[14:15] op_sel_hi:[1,0,0]
	s_nop 0
	v_mul_f32_e32 v36, 0x4b800000, v29
	v_cmp_gt_f32_e64 s[6:7], s3, v29
	v_cmp_gt_f32_e32 vcc, s3, v28
	s_nop 0
	v_cndmask_b32_e64 v29, v29, v36, s[6:7]
	v_rsq_f32_e32 v29, v29
	s_nop 0
	v_mul_f32_e32 v36, 0x45800000, v29
	v_cndmask_b32_e64 v36, v29, v36, s[6:7]
	v_pk_mul_f32 v[24:25], v[24:25], v[36:37] op_sel_hi:[1,0]
	v_pk_mul_f32 v[40:41], v[44:45], v[36:37] op_sel_hi:[1,0]
	v_mov_b32_e32 v21, v117
	v_pk_mul_f32 v[20:21], v[20:21], v[24:25]
	v_pk_mul_f32 v[40:41], v[46:47], v[40:41]
	v_pk_mul_f32 v[18:19], v[18:19], v[20:21]
	v_pk_mul_f32 v[38:39], v[38:39], v[40:41]
	v_and_b32_sdwa v24, v19, v173 dst_sel:DWORD dst_unused:UNUSED_PAD src0_sel:WORD_1 src1_sel:DWORD
	v_and_b32_sdwa v25, v18, v173 dst_sel:DWORD dst_unused:UNUSED_PAD src0_sel:WORD_1 src1_sel:DWORD
	v_and_b32_sdwa v20, v39, v173 dst_sel:DWORD dst_unused:UNUSED_PAD src0_sel:WORD_1 src1_sel:DWORD
	v_and_b32_sdwa v21, v38, v173 dst_sel:DWORD dst_unused:UNUSED_PAD src0_sel:WORD_1 src1_sel:DWORD
	v_add3_u32 v19, v19, v24, s71
	v_add3_u32 v18, v18, v25, s71
	v_add3_u32 v21, v38, v21, s71
	v_add3_u32 v20, v39, v20, s71
	v_and_b32_e32 v19, 0xffff0000, v19
	v_and_b32_e32 v18, 0xffff0000, v18
	v_or_b32_sdwa v19, v19, v20 dst_sel:DWORD dst_unused:UNUSED_PAD src0_sel:DWORD src1_sel:WORD_1
	v_or_b32_sdwa v18, v18, v21 dst_sel:DWORD dst_unused:UNUSED_PAD src0_sel:DWORD src1_sel:WORD_1
	global_store_dwordx2 v[12:13], v[18:19], off offset:2048
	v_mul_f32_e32 v18, 0x4b800000, v28
	v_cndmask_b32_e32 v18, v28, v18, vcc
	v_rsq_f32_e32 v18, v18
	s_nop 0
	v_mul_f32_e32 v19, 0x45800000, v18
	v_cndmask_b32_e32 v24, v18, v19, vcc
	s_waitcnt vmcnt(12)
	v_mov_b32_e32 v44, v124
	s_waitcnt vmcnt(11)
	v_lshlrev_b32_e32 v36, 16, v128
	v_mul_f32_e32 v25, 0xbfb8aa3b, v36
	v_exp_f32_e32 v25, v25
	v_and_b32_e32 v28, 0xffff0000, v128
	v_lshlrev_b32_e32 v37, 16, v129
	v_mul_f32_e32 v18, 0xbfb8aa3b, v37
	v_add_f32_e32 v25, 1.0, v25
	v_rcp_f32_e32 v38, v25
	v_mul_f32_e32 v25, 0xbfb8aa3b, v28
	v_exp_f32_e32 v25, v25
	v_exp_f32_e32 v18, v18
	v_and_b32_e32 v29, 0xffff0000, v129
	v_mov_b32_e32 v45, v126
	v_add_f32_e32 v25, 1.0, v25
	v_add_f32_e32 v18, 1.0, v18
	v_pk_mul_f32 v[22:23], v[22:23], v[24:25] op_sel_hi:[1,0]
	v_mov_b32_e32 v20, v125
	v_rcp_f32_e32 v39, v18
	v_mov_b32_e32 v21, v127
	v_pk_mul_f32 v[18:19], v[20:21], v[22:23]
	v_mul_f32_e32 v20, 0xbfb8aa3b, v29
	v_exp_f32_e32 v20, v20
	v_rcp_f32_e32 v40, v25
	v_pk_mul_f32 v[42:43], v[42:43], v[24:25] op_sel_hi:[1,0]
	v_pk_mul_f32 v[36:37], v[38:39], v[36:37]
	v_add_f32_e32 v20, 1.0, v20
	v_rcp_f32_e32 v41, v20
	v_pk_mul_f32 v[42:43], v[44:45], v[42:43]
	v_pk_mul_f32 v[20:21], v[40:41], v[28:29]
	s_nop 0
	v_pk_mul_f32 v[18:19], v[20:21], v[18:19]
	v_pk_mul_f32 v[36:37], v[36:37], v[42:43]
	v_and_b32_sdwa v22, v19, v173 dst_sel:DWORD dst_unused:UNUSED_PAD src0_sel:WORD_1 src1_sel:DWORD
	v_and_b32_sdwa v23, v18, v173 dst_sel:DWORD dst_unused:UNUSED_PAD src0_sel:WORD_1 src1_sel:DWORD
	v_and_b32_sdwa v20, v37, v173 dst_sel:DWORD dst_unused:UNUSED_PAD src0_sel:WORD_1 src1_sel:DWORD
	v_and_b32_sdwa v21, v36, v173 dst_sel:DWORD dst_unused:UNUSED_PAD src0_sel:WORD_1 src1_sel:DWORD
	v_add3_u32 v19, v19, v22, s71
	v_add3_u32 v18, v18, v23, s71
	v_add3_u32 v21, v36, v21, s71
	v_add3_u32 v20, v37, v20, s71
	v_and_b32_e32 v19, 0xffff0000, v19
	v_and_b32_e32 v18, 0xffff0000, v18
	v_or_b32_sdwa v19, v19, v20 dst_sel:DWORD dst_unused:UNUSED_PAD src0_sel:DWORD src1_sel:WORD_1
	v_or_b32_sdwa v18, v18, v21 dst_sel:DWORD dst_unused:UNUSED_PAD src0_sel:DWORD src1_sel:WORD_1
	global_store_dwordx2 v[12:13], v[18:19], off offset:2560
	s_nop 0
	s_nop 0
	s_mul_hi_i32 s5, s4, 0x600
	s_addc_u32 s9, s9, s5
	s_add_u32 s10, s10, s12
	s_addc_u32 s11, s11, s13
	s_add_u32 s14, s14, s16
	s_addc_u32 s15, s15, s17
	s_add_u32 s18, s18, s1
	s_mul_hi_i32 s5, s4, 0x2a00
	s_addc_u32 s19, s19, s5
	s_cmp_ge_i32 s0, s23
	s_waitcnt vmcnt(11)
	v_lshlrev_b32_e32 v20, 16, v138
	v_and_b32_e32 v21, 0xffff0000, v138
	v_lshlrev_b32_e32 v22, 16, v139
	v_and_b32_e32 v23, 0xffff0000, v139
	s_waitcnt vmcnt(10)
	v_lshlrev_b32_e32 v26, 16, v140
	v_and_b32_e32 v27, 0xffff0000, v140
	v_lshlrev_b32_e32 v24, 16, v141
	v_and_b32_e32 v25, 0xffff0000, v141
	v_pk_add_f32 v[26:27], v[20:21], v[26:27]
	v_pk_add_f32 v[20:21], v[22:23], v[24:25]
	v_pk_mul_f32 v[24:25], v[26:27], v[26:27]
	v_pk_mul_f32 v[22:23], v[20:21], v[20:21]
	s_nop 0
	v_pk_mov_b32 v[28:29], v[24:25], v[22:23] op_sel:[1,0]
	v_mov_b32_e32 v25, v23
	v_pk_add_f32 v[22:23], v[28:29], v[24:25]
	s_waitcnt vmcnt(7)
; __device__ __forceinline__ float silu_(float x) { return x * sigmoid_(x); }
; __device__ __forceinline__ unsigned pk2(float lo, float hi) { return f2bf(lo) | (f2bf(hi) << 16); }
; __device__ __forceinline__ float dot4(f32x4 a) { return (a.x * a.x + a.y * a.y) + (a.z * a.z + a.w * a.w); }
; __device__ __forceinline__ f32x4 ld_bf4(const bf16* p) { const u32x2 w = *(const u32x2*)p; return (f32x4){__builtin_bit_cast(float, w.x << 16), __builtin_bit_cast(float, w.x & 0xffff0000u), __builtin_bit_cast(float, w.y << 16), __builtin_bit_cast(float, w.y & 0xffff0000u)}; }
; #define LDY(p) ld_bf4(p)
; __device__ __forceinline__ float half_sum(float v) {
; #pragma unroll
;     for (int o = 1; o < 32; o <<= 1) v += __shfl_xor(v, o);
;     return v;
; }
; __device__ __forceinline__ void post_phase(const Params& P, int l, int mrows) {
;     ...
;     for (int row = gw; row < mrows; row += NGW) {
;     ...
;         {
; #pragma unroll
;             for (int j = 0; j < 2; ++j) { const int c = 4 * lane + 256 * j; const f32x4 o = LDY(YDP(3, 0) + c) + LDY(YDP(3, 1) + c);
;                 const float rs = rsqrtf(half_sum(dot4(o)) * (1.f / 128.f) + EPS); const f32x4 gt = ld_bf4(ug + G_RT_G + c);
;                 f32x4 r; r.x = o.x * rs * silu_(gt.x); r.y = o.y * rs * silu_(gt.y); r.z = o.z * rs * silu_(gt.z); r.w = o.w * rs * silu_(gt.w);
;                 u32x2 pk; pk.x = pk2(r.x, r.y); pk.y = pk2(r.z, r.w); *(u32x2*)(yc + 1536 + c) = pk; }
	v_lshlrev_b32_e32 v28, 16, v146
	v_and_b32_e32 v36, 0xffff0000, v146
	v_mul_f32_e32 v24, 0xbfb8aa3b, v28
	v_exp_f32_e32 v24, v24
	v_lshlrev_b32_e32 v29, 16, v147
	v_and_b32_e32 v37, 0xffff0000, v147
	v_mov_b32_e32 v25, v20
	v_add_f32_e32 v24, 1.0, v24
	v_rcp_f32_e32 v38, v24
	v_mul_f32_e32 v24, 0xbfb8aa3b, v36
	v_exp_f32_e32 v24, v24
	v_mul_f32_e32 v20, 0xbfb8aa3b, v29
	v_exp_f32_e32 v20, v20
	v_add_f32_e32 v24, 1.0, v24
	v_rcp_f32_e32 v40, v24
	v_mov_b32_e32 v24, v26
	v_mul_f32_e32 v26, 0xbfb8aa3b, v37
	v_exp_f32_e32 v26, v26
	v_add_f32_e32 v20, 1.0, v20
	v_rcp_f32_e32 v39, v20
	v_mov_b32_e32 v20, v27
	v_add_f32_e32 v26, 1.0, v26
	v_rcp_f32_e32 v41, v26
	v_pk_mul_f32 v[28:29], v[38:39], v[28:29]
	v_lshlrev_b32_e32 v38, 16, v144
	v_and_b32_e32 v39, 0xffff0000, v144
	v_pk_mul_f32 v[26:27], v[40:41], v[36:37]
	v_lshlrev_b32_e32 v36, 16, v142
	v_and_b32_e32 v37, 0xffff0000, v142
	v_lshlrev_b32_e32 v18, 16, v143
	v_and_b32_e32 v19, 0xffff0000, v143
	v_lshlrev_b32_e32 v16, 16, v145
	v_and_b32_e32 v17, 0xffff0000, v145
	v_pk_add_f32 v[36:37], v[36:37], v[38:39]
	v_pk_add_f32 v[16:17], v[18:19], v[16:17]
	v_pk_mul_f32 v[38:39], v[36:37], v[36:37]
	v_pk_mul_f32 v[18:19], v[16:17], v[16:17]
	s_nop 0
	v_pk_mov_b32 v[40:41], v[38:39], v[18:19] op_sel:[1,0]
	v_mov_b32_e32 v39, v19
	v_pk_add_f32 v[18:19], v[40:41], v[38:39]
	v_mov_b32_e32 v39, v22
	v_mov_b32_e32 v38, v18
	v_mov_b32_e32 v22, v19
	v_pk_add_f32 v[18:19], v[38:39], v[22:23]
	s_waitcnt lgkmcnt(0)
	s_nop 1
	v_add_f32_dpp v18, v18, v18 quad_perm:[1,0,3,2] row_mask:0xf bank_mask:0xf
	v_add_f32_dpp v19, v19, v19 quad_perm:[1,0,3,2] row_mask:0xf bank_mask:0xf
	s_waitcnt lgkmcnt(0)
	s_nop 0
	v_add_f32_dpp v18, v18, v18 quad_perm:[2,3,0,1] row_mask:0xf bank_mask:0xf
	v_add_f32_dpp v19, v19, v19 quad_perm:[2,3,0,1] row_mask:0xf bank_mask:0xf
	s_waitcnt lgkmcnt(0)
	s_nop 0
	v_add_f32_dpp v18, v18, v18 row_half_mirror row_mask:0xf bank_mask:0xf
	v_add_f32_dpp v19, v19, v19 row_half_mirror row_mask:0xf bank_mask:0xf
	s_waitcnt lgkmcnt(0)
	s_nop 0
	v_add_f32_dpp v18, v18, v18 row_mirror row_mask:0xf bank_mask:0xf
	v_add_f32_dpp v19, v19, v19 row_mirror row_mask:0xf bank_mask:0xf
	ds_bpermute_b32 v23, v34, v19
	ds_bpermute_b32 v22, v34, v18
	s_waitcnt lgkmcnt(0)
	v_pk_add_f32 v[18:19], v[18:19], v[22:23]
	s_nop 0
	v_pk_fma_f32 v[14:15], v[18:19], s[24:25], v[14:15] op_sel_hi:[1,0,0]
	s_nop 0
	v_mul_f32_e32 v18, 0x4b800000, v15
	v_cmp_gt_f32_e64 s[6:7], s3, v15
	v_cmp_gt_f32_e32 vcc, s3, v14
	s_nop 0
	v_cndmask_b32_e64 v15, v15, v18, s[6:7]
	v_rsq_f32_e32 v15, v15
	s_nop 0
	v_mul_f32_e32 v18, 0x45800000, v15
	v_cndmask_b32_e64 v18, v15, v18, s[6:7]
	v_pk_mul_f32 v[22:23], v[24:25], v[18:19] op_sel_hi:[1,0]
	v_pk_mul_f32 v[18:19], v[20:21], v[18:19] op_sel_hi:[1,0]
	v_pk_mul_f32 v[22:23], v[28:29], v[22:23]
	v_pk_mul_f32 v[18:19], v[26:27], v[18:19]
	v_and_b32_sdwa v20, v22, v173 dst_sel:DWORD dst_unused:UNUSED_PAD src0_sel:WORD_1 src1_sel:DWORD
	v_add3_u32 v20, v22, v20, s71
	v_and_b32_sdwa v21, v19, v173 dst_sel:DWORD dst_unused:UNUSED_PAD src0_sel:WORD_1 src1_sel:DWORD
	v_and_b32_sdwa v22, v18, v173 dst_sel:DWORD dst_unused:UNUSED_PAD src0_sel:WORD_1 src1_sel:DWORD
	v_and_b32_sdwa v15, v23, v173 dst_sel:DWORD dst_unused:UNUSED_PAD src0_sel:WORD_1 src1_sel:DWORD
	v_add3_u32 v19, v19, v21, s71
	v_add3_u32 v18, v18, v22, s71
	v_add3_u32 v15, v23, v15, s71
	v_and_b32_e32 v19, 0xffff0000, v19
	v_and_b32_e32 v18, 0xffff0000, v18
	v_or_b32_sdwa v19, v19, v15 dst_sel:DWORD dst_unused:UNUSED_PAD src0_sel:DWORD src1_sel:WORD_1
	v_or_b32_sdwa v18, v18, v20 dst_sel:DWORD dst_unused:UNUSED_PAD src0_sel:DWORD src1_sel:WORD_1
	global_store_dwordx2 v[12:13], v[18:19], off offset:3072
	v_mul_f32_e32 v15, 0x4b800000, v14
	v_cndmask_b32_e32 v14, v14, v15, vcc
	v_rsq_f32_e32 v14, v14
	v_mov_b32_e32 v24, v36
	v_mov_b32_e32 v25, v16
	v_mov_b32_e32 v16, v37
	v_mul_f32_e32 v15, 0x45800000, v14
	v_cndmask_b32_e32 v14, v14, v15, vcc
	s_waitcnt vmcnt(7)
	v_lshlrev_b32_e32 v18, 16, v148
	v_mul_f32_e32 v15, 0xbfb8aa3b, v18
	v_exp_f32_e32 v15, v15
	v_and_b32_e32 v10, 0xffff0000, v148
	v_lshlrev_b32_e32 v19, 16, v149
	v_and_b32_e32 v11, 0xffff0000, v149
	v_add_f32_e32 v15, 1.0, v15
	v_rcp_f32_e32 v20, v15
	v_mul_f32_e32 v15, 0xbfb8aa3b, v10
	v_exp_f32_e32 v15, v15
	s_nop 0
	v_add_f32_e32 v15, 1.0, v15
	v_rcp_f32_e32 v22, v15
	v_pk_mul_f32 v[24:25], v[24:25], v[14:15] op_sel_hi:[1,0]
	v_mul_f32_e32 v15, 0xbfb8aa3b, v19
	v_exp_f32_e32 v15, v15
	s_nop 0
	v_add_f32_e32 v15, 1.0, v15
	v_rcp_f32_e32 v21, v15
	v_pk_mul_f32 v[14:15], v[16:17], v[14:15] op_sel_hi:[1,0]
	v_mul_f32_e32 v16, 0xbfb8aa3b, v11
	v_exp_f32_e32 v16, v16
	v_pk_mul_f32 v[18:19], v[20:21], v[18:19]
	v_add_f32_e32 v16, 1.0, v16
	v_rcp_f32_e32 v23, v16
	v_pk_mul_f32 v[18:19], v[18:19], v[24:25]
	v_pk_mul_f32 v[10:11], v[22:23], v[10:11]
	s_nop 0
	v_pk_mul_f32 v[10:11], v[10:11], v[14:15]
	v_and_b32_sdwa v14, v19, v173 dst_sel:DWORD dst_unused:UNUSED_PAD src0_sel:WORD_1 src1_sel:DWORD
	v_and_b32_sdwa v16, v11, v173 dst_sel:DWORD dst_unused:UNUSED_PAD src0_sel:WORD_1 src1_sel:DWORD
	v_and_b32_sdwa v17, v10, v173 dst_sel:DWORD dst_unused:UNUSED_PAD src0_sel:WORD_1 src1_sel:DWORD
	v_and_b32_sdwa v15, v18, v173 dst_sel:DWORD dst_unused:UNUSED_PAD src0_sel:WORD_1 src1_sel:DWORD
	v_add3_u32 v11, v11, v16, s71
	v_add3_u32 v10, v10, v17, s71
	v_add3_u32 v15, v18, v15, s71
	v_add3_u32 v14, v19, v14, s71
	v_and_b32_e32 v11, 0xffff0000, v11
	v_and_b32_e32 v10, 0xffff0000, v10
	v_or_b32_sdwa v11, v11, v14 dst_sel:DWORD dst_unused:UNUSED_PAD src0_sel:DWORD src1_sel:WORD_1
	v_or_b32_sdwa v10, v10, v15 dst_sel:DWORD dst_unused:UNUSED_PAD src0_sel:DWORD src1_sel:WORD_1
	global_store_dwordx2 v[12:13], v[10:11], off offset:3584
	s_cbranch_scc0 .LBB0_341
